# K-loops: all s_setprio flips removed (equal priority for both wave halves)
# speedup vs baseline: 1.0051x; 1.0051x over previous
; #define G8_STA(bufoff, ptr, sg, h) G8_STAGE1(bufoff, (ptr) + (h) * ((sg) ? hA1 : hA0), ((sg) ? voffA1 : voffA0), ((sg) ? r64A1 : r64A0))
; #define G8_STB(bufoff, ptr, sg, h) G8_STAGE1(bufoff, (ptr) + (h) * ((sg) ? hB1 : hB0), ((sg) ? voffB1 : voffB0), ((sg) ? r64B1 : r64B0))
; #define G8_LDA(dst, b, h) do { _Pragma("unroll") for (int m = 0; m < 4; ++m) _Pragma("unroll") for (int k = 0; k < 2; ++k) dst[m][k] = *(const LAS bf16x8*)(lds + G8_SA(b, h) + aoff + m * 2048 + k * 1024); } while (0)
; #define G8_LDB(dst, b, h) do { _Pragma("unroll") for (int n = 0; n < 2; ++n) _Pragma("unroll") for (int k = 0; k < 2; ++k) dst[n][k] = *(const LAS bf16x8*)(lds + G8_SB(b, h) + boff + n * 2048 + k * 1024); } while (0)
; #define G8_MMA(ai, bj, At, Bt) do { __builtin_amdgcn_s_setprio(1); _Pragma("unroll") for (int m = 0; m < 4; ++m) _Pragma("unroll") for (int n = 0; n < 2; ++n) _Pragma("unroll") for (int k = 0; k < 2; ++k) \
;         acc[ai][bj][m][n] = __builtin_amdgcn_mfma_f32_16x16x32_bf16(Bt[n][k], At[m][k], acc[ai][bj][m][n], 0, 0, 0); __builtin_amdgcn_s_setprio(0); } while (0)
; #define G8_BAR __builtin_amdgcn_s_barrier()
; template <class P>
; __device__ __forceinline__ void gemm_phase(LAS unsigned char* lds, const P& p, const int G, const int c) {
;     ...
;         for (int t = 0; t < nt; t += 2) {
;             const bool last = (t == nt - 2);
;             const bool sg1 = (NS > 1) && (t + 1 >= nt0);
;             const bool sg2 = (NS > 1) && !last && (t + 2 >= nt0);
;             const char* a1 = sg1 ? cA1 + (long)(t + 1 - nt0) * ksA1 : cA0 + (long)(t + 1) * ksA0;
;             const char* a2 = last ? nA0 : (sg2 ? cA1 + (long)(t + 2 - nt0) * ksA1 : cA0 + (long)(t + 2) * ksA0);
;             const char* b2 = last ? nB0 : (sg2 ? cB1 + (long)(t + 2 - nt0) * ksB1 : cB0 + (long)(t + 2) * ksB0);
;             const char* a3 = a2 + (sg2 ? ksA1 : ksA0); const char* b3 = b2 + (sg2 ? ksB1 : ksB0);
;             G8_LDB(B0, 0, 0); G8_LDB(B1, 0, 1); G8_SCHED; G8_LDA(At, 0, 0); G8_STA(G8_SA(1, 1), a1, sg1, 1);
;             G8_WAIT_V(8); G8_WAIT_L(0); G8_BAR; G8_MMA(0, 0, At, B0); G8_MMA(0, 1, At, B1); G8_BAR; G8_SCHED;
;             G8_LDA(At, 0, 1); G8_STB(G8_SB(0, 0), b2, sg2, 0); G8_STB(G8_SB(0, 1), b2, sg2, 1); G8_STA(G8_SA(0, 0), a2, sg2, 0);
;             G8_WAIT_V(8); G8_WAIT_L(0); G8_BAR; G8_MMA(1, 0, At, B0); G8_MMA(1, 1, At, B1); G8_BAR; G8_SCHED;
.LBB0_155:
	ds_read_b128 v[56:59], v173
	ds_read_b128 v[60:63], v173 offset:1024
	ds_read_b128 v[176:179], v173 offset:2048
	ds_read_b128 v[180:183], v173 offset:3072
	ds_read_b128 v[184:187], v174
	ds_read_b128 v[188:191], v174 offset:1024
	ds_read_b128 v[192:195], v174 offset:2048
	ds_read_b128 v[196:199], v174 offset:3072
	s_add_u32 s53, s82, s84
	s_addc_u32 s56, s83, s85
	s_add_u32 s53, s53, 0x820000
	s_addc_u32 s56, s56, 0
	s_cmp_eq_u32 s84, 0x38e0000
	s_cselect_b32 s57, s18, s56
	s_cselect_b32 s56, s19, s53
	s_cselect_b32 s65, s30, s29
	s_cselect_b32 s64, s31, s28
	v_lshl_add_u64 v[64:65], v[54:55], 0, s[84:85]
	s_mov_b64 s[66:67], 0x414000
	v_lshl_add_u64 v[234:235], v[64:65], 0, s[66:67]
	s_add_i32 m0, s27, 0xc000
	s_mov_b64 s[66:67], 0x416000
	ds_read_b128 v[200:203], v175
	ds_read_b128 v[204:207], v175 offset:1024
	ds_read_b128 v[210:213], v175 offset:2048
	ds_read_b128 v[214:217], v175 offset:3072
	ds_read_b128 v[218:221], v175 offset:4096
	ds_read_b128 v[222:225], v175 offset:5120
	ds_read_b128 v[226:229], v175 offset:6144
	ds_read_b128 v[230:233], v175 offset:7168
	global_load_lds_dwordx4 v[234:235], off
	v_lshl_add_u64 v[64:65], v[64:65], 0, s[66:67]
	s_add_i32 m0, s27, 0xe000
	s_nop 0
	global_load_lds_dwordx4 v[64:65], off
	s_waitcnt vmcnt(8)
	s_waitcnt lgkmcnt(0)
	s_barrier
	s_waitcnt lgkmcnt(0)
	v_mfma_f32_16x16x32_bf16 v[98:101], v[56:59], v[200:203], v[98:101]
	v_mfma_f32_16x16x32_bf16 v[138:141], v[176:179], v[200:203], v[138:141]
	v_mfma_f32_16x16x32_bf16 v[70:73], v[56:59], v[210:213], v[70:73]
	v_mfma_f32_16x16x32_bf16 v[114:117], v[176:179], v[210:213], v[114:117]
	v_mfma_f32_16x16x32_bf16 v[46:49], v[56:59], v[218:221], v[46:49]
	v_mfma_f32_16x16x32_bf16 v[110:113], v[176:179], v[218:221], v[110:113]
	v_mfma_f32_16x16x32_bf16 v[38:41], v[56:59], v[226:229], v[38:41]
	v_mfma_f32_16x16x32_bf16 v[130:133], v[176:179], v[226:229], v[130:133]
	v_mfma_f32_16x16x32_bf16 v[98:101], v[60:63], v[204:207], v[98:101]
	v_mfma_f32_16x16x32_bf16 v[138:141], v[180:183], v[204:207], v[138:141]
	v_mfma_f32_16x16x32_bf16 v[70:73], v[60:63], v[214:217], v[70:73]
	v_mfma_f32_16x16x32_bf16 v[114:117], v[180:183], v[214:217], v[114:117]
	v_mfma_f32_16x16x32_bf16 v[46:49], v[60:63], v[222:225], v[46:49]
	v_mfma_f32_16x16x32_bf16 v[110:113], v[180:183], v[222:225], v[110:113]
	v_mfma_f32_16x16x32_bf16 v[38:41], v[60:63], v[230:233], v[38:41]
	v_mfma_f32_16x16x32_bf16 v[130:133], v[180:183], v[230:233], v[130:133]
	v_mfma_f32_16x16x32_bf16 v[134:137], v[184:187], v[200:203], v[134:137]
	v_mfma_f32_16x16x32_bf16 v[74:77], v[192:195], v[200:203], v[74:77]
	v_mfma_f32_16x16x32_bf16 v[106:109], v[184:187], v[210:213], v[106:109]
	v_mfma_f32_16x16x32_bf16 v[50:53], v[192:195], v[210:213], v[50:53]
	v_mfma_f32_16x16x32_bf16 v[102:105], v[184:187], v[218:221], v[102:105]
	v_mfma_f32_16x16x32_bf16 v[42:45], v[192:195], v[218:221], v[42:45]
	v_mfma_f32_16x16x32_bf16 v[126:129], v[184:187], v[226:229], v[126:129]
	v_mfma_f32_16x16x32_bf16 v[34:37], v[192:195], v[226:229], v[34:37]
	v_mfma_f32_16x16x32_bf16 v[134:137], v[188:191], v[204:207], v[134:137]
	v_mfma_f32_16x16x32_bf16 v[74:77], v[196:199], v[204:207], v[74:77]
	v_mfma_f32_16x16x32_bf16 v[106:109], v[188:191], v[214:217], v[106:109]
	v_mfma_f32_16x16x32_bf16 v[50:53], v[196:199], v[214:217], v[50:53]
	v_mfma_f32_16x16x32_bf16 v[102:105], v[188:191], v[222:225], v[102:105]
	v_mfma_f32_16x16x32_bf16 v[42:45], v[196:199], v[222:225], v[42:45]
	v_mfma_f32_16x16x32_bf16 v[126:129], v[188:191], v[230:233], v[126:129]
	v_mfma_f32_16x16x32_bf16 v[34:37], v[196:199], v[230:233], v[34:37]
	s_barrier
	s_add_i32 s53, s50, s2
	v_lshl_add_u64 v[234:235], s[64:65], 0, v[142:143]
	s_mov_b32 m0, s53
	ds_read_b128 v[200:203], v175 offset:16384
	ds_read_b128 v[204:207], v175 offset:17408
	ds_read_b128 v[210:213], v175 offset:18432
	ds_read_b128 v[214:217], v175 offset:19456
	ds_read_b128 v[218:221], v175 offset:20480
	ds_read_b128 v[222:225], v175 offset:21504
	ds_read_b128 v[226:229], v175 offset:22528
	ds_read_b128 v[230:233], v175 offset:23552
	global_load_lds_dwordx4 v[234:235], off
	v_lshl_add_u64 v[64:65], v[234:235], 0, s[4:5]
	s_add_i32 m0, s53, 0x2000
	s_add_i32 s53, s51, s2
	global_load_lds_dwordx4 v[64:65], off
	v_lshl_add_u64 v[64:65], v[234:235], 0, s[6:7]
	s_mov_b32 m0, s53
	v_lshl_add_u64 v[236:237], s[56:57], 0, v[144:145]
	global_load_lds_dwordx4 v[64:65], off
	v_lshl_add_u64 v[64:65], v[234:235], 0, s[8:9]
	s_add_i32 m0, s53, 0x2000
	s_nop 0
	global_load_lds_dwordx4 v[64:65], off
	s_mov_b32 m0, s27
	v_lshl_add_u64 v[64:65], v[236:237], 0, s[4:5]
	global_load_lds_dwordx4 v[236:237], off
	s_mov_b32 m0, s33
	s_nop 0
	global_load_lds_dwordx4 v[64:65], off
	s_waitcnt vmcnt(8)
	s_waitcnt lgkmcnt(0)
	s_barrier
; #define G8_STA(bufoff, ptr, sg, h) G8_STAGE1(bufoff, (ptr) + (h) * ((sg) ? hA1 : hA0), ((sg) ? voffA1 : voffA0), ((sg) ? r64A1 : r64A0))
; #define G8_LDA(dst, b, h) do { _Pragma("unroll") for (int m = 0; m < 4; ++m) _Pragma("unroll") for (int k = 0; k < 2; ++k) dst[m][k] = *(const LAS bf16x8*)(lds + G8_SA(b, h) + aoff + m * 2048 + k * 1024); } while (0)
; #define G8_LDB(dst, b, h) do { _Pragma("unroll") for (int n = 0; n < 2; ++n) _Pragma("unroll") for (int k = 0; k < 2; ++k) dst[n][k] = *(const LAS bf16x8*)(lds + G8_SB(b, h) + boff + n * 2048 + k * 1024); } while (0)
; #define G8_MMA(ai, bj, At, Bt) do { __builtin_amdgcn_s_setprio(1); _Pragma("unroll") for (int m = 0; m < 4; ++m) _Pragma("unroll") for (int n = 0; n < 2; ++n) _Pragma("unroll") for (int k = 0; k < 2; ++k) \
;         acc[ai][bj][m][n] = __builtin_amdgcn_mfma_f32_16x16x32_bf16(Bt[n][k], At[m][k], acc[ai][bj][m][n], 0, 0, 0); __builtin_amdgcn_s_setprio(0); } while (0)
; #define G8_WAIT_V(n) asm volatile("s_waitcnt vmcnt(" #n ")" ::: "memory")
; #define G8_WAIT_L(n) asm volatile("s_waitcnt lgkmcnt(" #n ")" ::: "memory")
; #define G8_BAR __builtin_amdgcn_s_barrier()
; #define G8_SCHED __builtin_amdgcn_sched_barrier(0)
; template <class P>
; __device__ __forceinline__ void gemm_phase(LAS unsigned char* lds, const P& p, const int G, const int c) {
;     ...
;             G8_WAIT_V(8); G8_WAIT_L(0); G8_BAR; G8_MMA(1, 0, At, B0); G8_MMA(1, 1, At, B1); G8_BAR; G8_SCHED;
;             G8_LDB(B0, 1, 0); G8_LDB(B1, 1, 1); G8_SCHED; G8_LDA(At, 1, 0); G8_STA(G8_SA(0, 1), a2, sg2, 1);
;             G8_WAIT_V(8); G8_WAIT_L(0); G8_BAR; G8_MMA(0, 0, At, B0); G8_MMA(0, 1, At, B1); G8_BAR; G8_SCHED;
	s_waitcnt lgkmcnt(0)
	v_mfma_f32_16x16x32_bf16 v[30:33], v[56:59], v[200:203], v[30:33]
	v_mfma_f32_16x16x32_bf16 v[122:125], v[176:179], v[200:203], v[122:125]
	v_mfma_f32_16x16x32_bf16 v[22:25], v[56:59], v[210:213], v[22:25]
	v_mfma_f32_16x16x32_bf16 v[94:97], v[176:179], v[210:213], v[94:97]
	v_mfma_f32_16x16x32_bf16 v[14:17], v[56:59], v[218:221], v[14:17]
	v_mfma_f32_16x16x32_bf16 v[90:93], v[176:179], v[218:221], v[90:93]
	v_mfma_f32_16x16x32_bf16 v[6:9], v[56:59], v[226:229], v[6:9]
	v_mfma_f32_16x16x32_bf16 v[30:33], v[60:63], v[204:207], v[30:33]
	v_mfma_f32_16x16x32_bf16 v[122:125], v[180:183], v[204:207], v[122:125]
	v_mfma_f32_16x16x32_bf16 v[22:25], v[60:63], v[214:217], v[22:25]
	v_mfma_f32_16x16x32_bf16 v[94:97], v[180:183], v[214:217], v[94:97]
	v_mfma_f32_16x16x32_bf16 v[14:17], v[60:63], v[222:225], v[14:17]
	v_mfma_f32_16x16x32_bf16 v[90:93], v[180:183], v[222:225], v[90:93]
	v_mfma_f32_16x16x32_bf16 v[6:9], v[60:63], v[230:233], v[6:9]
	v_mfma_f32_16x16x32_bf16 v[56:59], v[176:179], v[226:229], v[78:81]
	v_mfma_f32_16x16x32_bf16 v[56:59], v[180:183], v[230:233], v[56:59]
	v_mfma_f32_16x16x32_bf16 v[78:81], v[184:187], v[210:213], v[86:89]
	v_mfma_f32_16x16x32_bf16 v[26:29], v[192:195], v[200:203], v[26:29]
	v_mfma_f32_16x16x32_bf16 v[86:89], v[188:191], v[214:217], v[78:81]
	v_mfma_f32_16x16x32_bf16 v[18:21], v[192:195], v[210:213], v[18:21]
	v_mfma_f32_16x16x32_bf16 v[78:81], v[184:187], v[218:221], v[82:85]
	v_mfma_f32_16x16x32_bf16 v[10:13], v[192:195], v[218:221], v[10:13]
	v_mfma_f32_16x16x32_bf16 v[64:67], v[184:187], v[226:229], v[66:69]
	v_mfma_f32_16x16x32_bf16 v[2:5], v[192:195], v[226:229], v[2:5]
	v_mfma_f32_16x16x32_bf16 v[60:63], v[184:187], v[200:203], v[118:121]
	v_mfma_f32_16x16x32_bf16 v[26:29], v[196:199], v[204:207], v[26:29]
	v_mfma_f32_16x16x32_bf16 v[18:21], v[196:199], v[214:217], v[18:21]
	v_mfma_f32_16x16x32_bf16 v[82:85], v[188:191], v[222:225], v[78:81]
	v_mfma_f32_16x16x32_bf16 v[10:13], v[196:199], v[222:225], v[10:13]
	v_mfma_f32_16x16x32_bf16 v[64:67], v[188:191], v[230:233], v[64:67]
	v_mfma_f32_16x16x32_bf16 v[2:5], v[196:199], v[230:233], v[2:5]
	v_mfma_f32_16x16x32_bf16 v[60:63], v[188:191], v[204:207], v[60:63]
	s_barrier
	s_add_i32 s53, 0, 0x18000
	v_add_u32_e32 v68, s53, v152
	s_add_i32 s56, 0, 0x1c000
	ds_read_b128 v[78:81], v68
	ds_read_b128 v[118:121], v68 offset:1024
	ds_read_b128 v[176:179], v68 offset:2048
	ds_read_b128 v[180:183], v68 offset:3072
	v_add_u32_e32 v68, s56, v152
	ds_read_b128 v[184:187], v68
	ds_read_b128 v[188:191], v68 offset:1024
	ds_read_b128 v[192:195], v68 offset:2048
	ds_read_b128 v[196:199], v68 offset:3072
	s_mov_b32 m0, s34
	v_lshl_add_u64 v[68:69], v[236:237], 0, s[6:7]
	ds_read_b128 v[200:203], v175 offset:32768
	ds_read_b128 v[204:207], v175 offset:33792
	ds_read_b128 v[210:213], v175 offset:34816
	ds_read_b128 v[214:217], v175 offset:35840
	ds_read_b128 v[218:221], v175 offset:36864
	ds_read_b128 v[222:225], v175 offset:37888
	ds_read_b128 v[226:229], v175 offset:38912
	ds_read_b128 v[230:233], v175 offset:39936
	global_load_lds_dwordx4 v[68:69], off
	v_lshl_add_u64 v[68:69], v[236:237], 0, s[8:9]
	s_mov_b32 m0, s35
	s_nop 0
	global_load_lds_dwordx4 v[68:69], off
	s_waitcnt vmcnt(8)
	s_waitcnt lgkmcnt(0)
	s_barrier
	s_waitcnt lgkmcnt(0)
	v_mfma_f32_16x16x32_bf16 v[98:101], v[78:81], v[200:203], v[98:101]
	v_mfma_f32_16x16x32_bf16 v[138:141], v[176:179], v[200:203], v[138:141]
	v_mfma_f32_16x16x32_bf16 v[68:71], v[78:81], v[210:213], v[70:73]
	v_mfma_f32_16x16x32_bf16 v[114:117], v[176:179], v[210:213], v[114:117]
	v_mfma_f32_16x16x32_bf16 v[46:49], v[78:81], v[218:221], v[46:49]
	v_mfma_f32_16x16x32_bf16 v[110:113], v[176:179], v[218:221], v[110:113]
	v_mfma_f32_16x16x32_bf16 v[38:41], v[78:81], v[226:229], v[38:41]
	v_mfma_f32_16x16x32_bf16 v[130:133], v[176:179], v[226:229], v[130:133]
	v_mfma_f32_16x16x32_bf16 v[98:101], v[118:121], v[204:207], v[98:101]
	v_mfma_f32_16x16x32_bf16 v[138:141], v[180:183], v[204:207], v[138:141]
	v_mfma_f32_16x16x32_bf16 v[70:73], v[118:121], v[214:217], v[68:71]
	v_mfma_f32_16x16x32_bf16 v[114:117], v[180:183], v[214:217], v[114:117]
	v_mfma_f32_16x16x32_bf16 v[46:49], v[118:121], v[222:225], v[46:49]
	v_mfma_f32_16x16x32_bf16 v[110:113], v[180:183], v[222:225], v[110:113]
	v_mfma_f32_16x16x32_bf16 v[38:41], v[118:121], v[230:233], v[38:41]
	v_mfma_f32_16x16x32_bf16 v[130:133], v[180:183], v[230:233], v[130:133]
	v_mfma_f32_16x16x32_bf16 v[134:137], v[184:187], v[200:203], v[134:137]
	v_mfma_f32_16x16x32_bf16 v[74:77], v[192:195], v[200:203], v[74:77]
	v_mfma_f32_16x16x32_bf16 v[106:109], v[184:187], v[210:213], v[106:109]
	v_mfma_f32_16x16x32_bf16 v[50:53], v[192:195], v[210:213], v[50:53]
	v_mfma_f32_16x16x32_bf16 v[102:105], v[184:187], v[218:221], v[102:105]
	v_mfma_f32_16x16x32_bf16 v[42:45], v[192:195], v[218:221], v[42:45]
	v_mfma_f32_16x16x32_bf16 v[126:129], v[184:187], v[226:229], v[126:129]
	v_mfma_f32_16x16x32_bf16 v[34:37], v[192:195], v[226:229], v[34:37]
	v_mfma_f32_16x16x32_bf16 v[134:137], v[188:191], v[204:207], v[134:137]
	v_mfma_f32_16x16x32_bf16 v[74:77], v[196:199], v[204:207], v[74:77]
	v_mfma_f32_16x16x32_bf16 v[106:109], v[188:191], v[214:217], v[106:109]
	v_mfma_f32_16x16x32_bf16 v[50:53], v[196:199], v[214:217], v[50:53]
	v_mfma_f32_16x16x32_bf16 v[102:105], v[188:191], v[222:225], v[102:105]
	v_mfma_f32_16x16x32_bf16 v[42:45], v[196:199], v[222:225], v[42:45]
	v_mfma_f32_16x16x32_bf16 v[126:129], v[188:191], v[230:233], v[126:129]
	v_mfma_f32_16x16x32_bf16 v[34:37], v[196:199], v[230:233], v[34:37]
	s_barrier
; #define G8_STA(bufoff, ptr, sg, h) G8_STAGE1(bufoff, (ptr) + (h) * ((sg) ? hA1 : hA0), ((sg) ? voffA1 : voffA0), ((sg) ? r64A1 : r64A0))
; #define G8_STB(bufoff, ptr, sg, h) G8_STAGE1(bufoff, (ptr) + (h) * ((sg) ? hB1 : hB0), ((sg) ? voffB1 : voffB0), ((sg) ? r64B1 : r64B0))
; #define G8_LDA(dst, b, h) do { _Pragma("unroll") for (int m = 0; m < 4; ++m) _Pragma("unroll") for (int k = 0; k < 2; ++k) dst[m][k] = *(const LAS bf16x8*)(lds + G8_SA(b, h) + aoff + m * 2048 + k * 1024); } while (0)
; #define G8_MMA(ai, bj, At, Bt) do { __builtin_amdgcn_s_setprio(1); _Pragma("unroll") for (int m = 0; m < 4; ++m) _Pragma("unroll") for (int n = 0; n < 2; ++n) _Pragma("unroll") for (int k = 0; k < 2; ++k) \
;         acc[ai][bj][m][n] = __builtin_amdgcn_mfma_f32_16x16x32_bf16(Bt[n][k], At[m][k], acc[ai][bj][m][n], 0, 0, 0); __builtin_amdgcn_s_setprio(0); } while (0)
; #define G8_WAIT_V(n) asm volatile("s_waitcnt vmcnt(" #n ")" ::: "memory")
; #define G8_WAIT_L(n) asm volatile("s_waitcnt lgkmcnt(" #n ")" ::: "memory")
; #define G8_BAR __builtin_amdgcn_s_barrier()
; #define G8_SCHED __builtin_amdgcn_sched_barrier(0)
; template <class P>
; __device__ __forceinline__ void gemm_phase(LAS unsigned char* lds, const P& p, const int G, const int c) {
;     ...
;             G8_LDA(At, 1, 1); G8_STB(G8_SB(1, 0), b3, sg2, 0); G8_STB(G8_SB(1, 1), b3, sg2, 1); G8_STA(G8_SA(1, 0), a3, sg2, 0);
;             G8_WAIT_V(8); G8_WAIT_L(0); G8_BAR; G8_MMA(1, 0, At, B0); G8_MMA(1, 1, At, B1); G8_BAR; G8_SCHED;
;         }
;         if (wr == 0) G8_BAR;
	s_add_i32 s53, s53, s2
	v_lshl_add_u64 v[68:69], v[234:235], 0, s[12:13]
	s_mov_b32 m0, s53
	ds_read_b128 v[200:203], v175 offset:49152
	ds_read_b128 v[204:207], v175 offset:50176
	ds_read_b128 v[210:213], v175 offset:51200
	ds_read_b128 v[214:217], v175 offset:52224
	ds_read_b128 v[218:221], v175 offset:53248
	ds_read_b128 v[222:225], v175 offset:54272
	ds_read_b128 v[226:229], v175 offset:55296
	ds_read_b128 v[230:233], v175 offset:56320
	global_load_lds_dwordx4 v[68:69], off
	v_lshl_add_u64 v[68:69], v[234:235], 0, s[14:15]
	s_add_i32 m0, s53, 0x2000
	s_add_i32 s53, s56, s2
	global_load_lds_dwordx4 v[68:69], off
	v_lshl_add_u64 v[68:69], v[234:235], 0, s[22:23]
	s_mov_b32 m0, s53
	s_nop 0
	global_load_lds_dwordx4 v[68:69], off
	v_lshl_add_u64 v[68:69], v[234:235], 0, s[36:37]
	s_add_i32 m0, s53, 0x2000
	s_nop 0
	global_load_lds_dwordx4 v[68:69], off
	v_lshl_add_u64 v[68:69], v[236:237], 0, s[16:17]
	s_mov_b32 m0, s47
	s_nop 0
	global_load_lds_dwordx4 v[68:69], off
	v_lshl_add_u64 v[68:69], v[236:237], 0, s[20:21]
	s_mov_b32 m0, s48
	s_nop 0
	global_load_lds_dwordx4 v[68:69], off
	s_waitcnt vmcnt(8)
	s_waitcnt lgkmcnt(0)
	s_barrier
	s_waitcnt lgkmcnt(0)
	v_mfma_f32_16x16x32_bf16 v[30:33], v[78:81], v[200:203], v[30:33]
	v_mfma_f32_16x16x32_bf16 v[122:125], v[176:179], v[200:203], v[122:125]
	v_mfma_f32_16x16x32_bf16 v[22:25], v[78:81], v[210:213], v[22:25]
	v_mfma_f32_16x16x32_bf16 v[94:97], v[176:179], v[210:213], v[94:97]
	v_mfma_f32_16x16x32_bf16 v[14:17], v[78:81], v[218:221], v[14:17]
	v_mfma_f32_16x16x32_bf16 v[90:93], v[176:179], v[218:221], v[90:93]
	v_mfma_f32_16x16x32_bf16 v[6:9], v[78:81], v[226:229], v[6:9]
	v_mfma_f32_16x16x32_bf16 v[56:59], v[176:179], v[226:229], v[56:59]
	v_mfma_f32_16x16x32_bf16 v[30:33], v[118:121], v[204:207], v[30:33]
	v_mfma_f32_16x16x32_bf16 v[122:125], v[180:183], v[204:207], v[122:125]
	v_mfma_f32_16x16x32_bf16 v[22:25], v[118:121], v[214:217], v[22:25]
	v_mfma_f32_16x16x32_bf16 v[94:97], v[180:183], v[214:217], v[94:97]
	v_mfma_f32_16x16x32_bf16 v[14:17], v[118:121], v[222:225], v[14:17]
	v_mfma_f32_16x16x32_bf16 v[90:93], v[180:183], v[222:225], v[90:93]
	v_mfma_f32_16x16x32_bf16 v[6:9], v[118:121], v[230:233], v[6:9]
	v_mfma_f32_16x16x32_bf16 v[78:81], v[180:183], v[230:233], v[56:59]
	v_mfma_f32_16x16x32_bf16 v[56:59], v[184:187], v[200:203], v[60:63]
	v_mfma_f32_16x16x32_bf16 v[118:121], v[188:191], v[204:207], v[56:59]
	v_mfma_f32_16x16x32_bf16 v[56:59], v[184:187], v[210:213], v[86:89]
	v_mfma_f32_16x16x32_bf16 v[86:89], v[188:191], v[214:217], v[56:59]
	v_mfma_f32_16x16x32_bf16 v[56:59], v[184:187], v[218:221], v[82:85]
	v_mfma_f32_16x16x32_bf16 v[26:29], v[192:195], v[200:203], v[26:29]
	v_mfma_f32_16x16x32_bf16 v[18:21], v[192:195], v[210:213], v[18:21]
	v_mfma_f32_16x16x32_bf16 v[82:85], v[188:191], v[222:225], v[56:59]
	v_mfma_f32_16x16x32_bf16 v[10:13], v[192:195], v[218:221], v[10:13]
	v_mfma_f32_16x16x32_bf16 v[56:59], v[184:187], v[226:229], v[64:67]
	v_mfma_f32_16x16x32_bf16 v[2:5], v[192:195], v[226:229], v[2:5]
	v_mfma_f32_16x16x32_bf16 v[26:29], v[196:199], v[204:207], v[26:29]
	v_mfma_f32_16x16x32_bf16 v[18:21], v[196:199], v[214:217], v[18:21]
	v_mfma_f32_16x16x32_bf16 v[10:13], v[196:199], v[222:225], v[10:13]
	v_mfma_f32_16x16x32_bf16 v[66:69], v[188:191], v[230:233], v[56:59]
	v_mfma_f32_16x16x32_bf16 v[2:5], v[196:199], v[230:233], v[2:5]
	s_barrier
	s_add_i32 s52, s52, 2
	s_add_u32 s28, s28, 0x200000
	s_addc_u32 s29, s29, 0
	s_add_u32 s84, s84, 0x820000
	s_addc_u32 s85, s85, 0
	s_cmp_gt_u32 s52, 13
	s_cbranch_scc0 .LBB0_155
	s_and_b64 vcc, exec, s[38:39]
	s_cbranch_vccz .LBB0_158
	s_barrier

; #define G8_STA(bufoff, ptr, sg, h) G8_STAGE1(bufoff, (ptr) + (h) * ((sg) ? hA1 : hA0), ((sg) ? voffA1 : voffA0), ((sg) ? r64A1 : r64A0))
; #define G8_STB(bufoff, ptr, sg, h) G8_STAGE1(bufoff, (ptr) + (h) * ((sg) ? hB1 : hB0), ((sg) ? voffB1 : voffB0), ((sg) ? r64B1 : r64B0))
; #define G8_LDA(dst, b, h) do { _Pragma("unroll") for (int m = 0; m < 4; ++m) _Pragma("unroll") for (int k = 0; k < 2; ++k) dst[m][k] = *(const LAS bf16x8*)(lds + G8_SA(b, h) + aoff + m * 2048 + k * 1024); } while (0)
; #define G8_LDB(dst, b, h) do { _Pragma("unroll") for (int n = 0; n < 2; ++n) _Pragma("unroll") for (int k = 0; k < 2; ++k) dst[n][k] = *(const LAS bf16x8*)(lds + G8_SB(b, h) + boff + n * 2048 + k * 1024); } while (0)
; #define G8_MMA(ai, bj, At, Bt) do { __builtin_amdgcn_s_setprio(1); _Pragma("unroll") for (int m = 0; m < 4; ++m) _Pragma("unroll") for (int n = 0; n < 2; ++n) _Pragma("unroll") for (int k = 0; k < 2; ++k) \
;         acc[ai][bj][m][n] = __builtin_amdgcn_mfma_f32_16x16x32_bf16(Bt[n][k], At[m][k], acc[ai][bj][m][n], 0, 0, 0); __builtin_amdgcn_s_setprio(0); } while (0)
; #define G8_BAR __builtin_amdgcn_s_barrier()
; template <class P>
; __device__ __forceinline__ void gemm_phase(LAS unsigned char* lds, const P& p, const int G, const int c) {
;     ...
;         for (int t = 0; t < nt; t += 2) {
;             const bool last = (t == nt - 2);
;             const bool sg1 = (NS > 1) && (t + 1 >= nt0);
;             const bool sg2 = (NS > 1) && !last && (t + 2 >= nt0);
;             const char* a1 = sg1 ? cA1 + (long)(t + 1 - nt0) * ksA1 : cA0 + (long)(t + 1) * ksA0;
;             const char* a2 = last ? nA0 : (sg2 ? cA1 + (long)(t + 2 - nt0) * ksA1 : cA0 + (long)(t + 2) * ksA0);
;             const char* b2 = last ? nB0 : (sg2 ? cB1 + (long)(t + 2 - nt0) * ksB1 : cB0 + (long)(t + 2) * ksB0);
;             const char* a3 = a2 + (sg2 ? ksA1 : ksA0); const char* b3 = b2 + (sg2 ? ksB1 : ksB0);
;             G8_LDB(B0, 0, 0); G8_LDB(B1, 0, 1); G8_SCHED; G8_LDA(At, 0, 0); G8_STA(G8_SA(1, 1), a1, sg1, 1);
;             G8_WAIT_V(8); G8_WAIT_L(0); G8_BAR; G8_MMA(0, 0, At, B0); G8_MMA(0, 1, At, B1); G8_BAR; G8_SCHED;
;             G8_LDA(At, 0, 1); G8_STB(G8_SB(0, 0), b2, sg2, 0); G8_STB(G8_SB(0, 1), b2, sg2, 1); G8_STA(G8_SA(0, 0), a2, sg2, 0);
;             G8_WAIT_V(8); G8_WAIT_L(0); G8_BAR; G8_MMA(1, 0, At, B0); G8_MMA(1, 1, At, B1); G8_BAR; G8_SCHED;
.LBB0_277:
	v_add_u32_e32 v144, s52, v1
	ds_read_b128 v[132:135], v144
	ds_read_b128 v[136:139], v144 offset:1024
	ds_read_b128 v[140:143], v144 offset:2048
	ds_read_b128 v[176:179], v144 offset:3072
	v_add_u32_e32 v144, s53, v1
	ds_read_b128 v[180:183], v144
	ds_read_b128 v[184:187], v144 offset:1024
	ds_read_b128 v[188:191], v144 offset:2048
	ds_read_b128 v[192:195], v144 offset:3072
	s_add_i32 s57, s57, 2
	s_and_b64 s[30:31], exec, s[30:31]
	s_cselect_b32 s31, s7, s49
	s_cselect_b32 s30, s18, s19
	v_lshl_add_u64 v[144:145], v[130:131], 0, s[76:77]
	s_mov_b64 s[64:65], 0x414000
	v_lshl_add_u64 v[230:231], v[144:145], 0, s[64:65]
	s_add_i32 m0, s27, 0xc000
	s_mov_b64 s[64:65], 0x416000
	ds_read_b128 v[196:199], v175
	ds_read_b128 v[200:203], v175 offset:1024
	ds_read_b128 v[204:207], v175 offset:2048
	ds_read_b128 v[210:213], v175 offset:3072
	ds_read_b128 v[214:217], v175 offset:4096
	ds_read_b128 v[218:221], v175 offset:5120
	ds_read_b128 v[222:225], v175 offset:6144
	ds_read_b128 v[226:229], v175 offset:7168
	global_load_lds_dwordx4 v[230:231], off
	v_lshl_add_u64 v[144:145], v[144:145], 0, s[64:65]
	s_add_i32 m0, s27, 0xe000
	s_nop 0
	global_load_lds_dwordx4 v[144:145], off
	s_waitcnt vmcnt(8)
	s_waitcnt lgkmcnt(0)
	s_barrier
	s_waitcnt lgkmcnt(0)
	v_mfma_f32_16x16x32_bf16 v[126:129], v[132:135], v[196:199], v[126:129]
	v_mfma_f32_16x16x32_bf16 v[122:125], v[140:143], v[196:199], v[122:125]
	v_mfma_f32_16x16x32_bf16 v[118:121], v[132:135], v[204:207], v[118:121]
	v_mfma_f32_16x16x32_bf16 v[114:117], v[140:143], v[204:207], v[114:117]
	v_mfma_f32_16x16x32_bf16 v[106:109], v[132:135], v[214:217], v[106:109]
	v_mfma_f32_16x16x32_bf16 v[98:101], v[140:143], v[214:217], v[98:101]
	v_mfma_f32_16x16x32_bf16 v[94:97], v[132:135], v[222:225], v[94:97]
	v_mfma_f32_16x16x32_bf16 v[86:89], v[140:143], v[222:225], v[86:89]
	v_mfma_f32_16x16x32_bf16 v[126:129], v[136:139], v[200:203], v[126:129]
	v_mfma_f32_16x16x32_bf16 v[122:125], v[176:179], v[200:203], v[122:125]
	v_mfma_f32_16x16x32_bf16 v[118:121], v[136:139], v[210:213], v[118:121]
	v_mfma_f32_16x16x32_bf16 v[114:117], v[176:179], v[210:213], v[114:117]
	v_mfma_f32_16x16x32_bf16 v[106:109], v[136:139], v[218:221], v[106:109]
	v_mfma_f32_16x16x32_bf16 v[98:101], v[176:179], v[218:221], v[98:101]
	v_mfma_f32_16x16x32_bf16 v[94:97], v[136:139], v[226:229], v[94:97]
	v_mfma_f32_16x16x32_bf16 v[86:89], v[176:179], v[226:229], v[86:89]
	v_mfma_f32_16x16x32_bf16 v[110:113], v[180:183], v[196:199], v[110:113]
	v_mfma_f32_16x16x32_bf16 v[102:105], v[188:191], v[196:199], v[102:105]
	v_mfma_f32_16x16x32_bf16 v[90:93], v[180:183], v[204:207], v[90:93]
	v_mfma_f32_16x16x32_bf16 v[82:85], v[188:191], v[204:207], v[82:85]
	v_mfma_f32_16x16x32_bf16 v[78:81], v[180:183], v[214:217], v[78:81]
	v_mfma_f32_16x16x32_bf16 v[74:77], v[188:191], v[214:217], v[74:77]
	v_mfma_f32_16x16x32_bf16 v[70:73], v[180:183], v[222:225], v[70:73]
	v_mfma_f32_16x16x32_bf16 v[66:69], v[188:191], v[222:225], v[66:69]
	v_mfma_f32_16x16x32_bf16 v[110:113], v[184:187], v[200:203], v[110:113]
	v_mfma_f32_16x16x32_bf16 v[102:105], v[192:195], v[200:203], v[102:105]
	v_mfma_f32_16x16x32_bf16 v[90:93], v[184:187], v[210:213], v[90:93]
	v_mfma_f32_16x16x32_bf16 v[82:85], v[192:195], v[210:213], v[82:85]
	v_mfma_f32_16x16x32_bf16 v[78:81], v[184:187], v[218:221], v[78:81]
	v_mfma_f32_16x16x32_bf16 v[74:77], v[192:195], v[218:221], v[74:77]
	v_mfma_f32_16x16x32_bf16 v[70:73], v[184:187], v[226:229], v[70:73]
	v_mfma_f32_16x16x32_bf16 v[66:69], v[192:195], v[226:229], v[66:69]
	s_barrier
	v_lshl_add_u64 v[144:145], s[30:31], 0, v[148:149]
	s_add_i32 s30, s52, s26
	s_mov_b32 m0, s30
	ds_read_b128 v[196:199], v175 offset:16384
	ds_read_b128 v[200:203], v175 offset:17408
	ds_read_b128 v[204:207], v175 offset:18432
	ds_read_b128 v[210:213], v175 offset:19456
	ds_read_b128 v[214:217], v175 offset:20480
	ds_read_b128 v[218:221], v175 offset:21504
	ds_read_b128 v[222:225], v175 offset:22528
	ds_read_b128 v[226:229], v175 offset:23552
	global_load_lds_dwordx4 v[144:145], off
	v_lshl_add_u64 v[230:231], v[144:145], 0, s[10:11]
	s_add_i32 m0, s30, 0x2000
	s_add_i32 s30, s53, s26
	global_load_lds_dwordx4 v[230:231], off
	v_lshl_add_u64 v[230:231], v[144:145], 0, s[12:13]
	s_mov_b32 m0, s30
	s_nop 0
	global_load_lds_dwordx4 v[230:231], off
	v_lshl_add_u64 v[230:231], v[144:145], 0, s[14:15]
	s_add_i32 m0, s30, 0x2000
	s_nop 0
	global_load_lds_dwordx4 v[230:231], off
	v_lshl_add_u64 v[230:231], s[28:29], 0, v[150:151]
	s_mov_b32 m0, s27
	v_lshl_add_u64 v[232:233], v[230:231], 0, s[10:11]
	global_load_lds_dwordx4 v[230:231], off
	s_mov_b32 m0, s33
	s_nop 0
	global_load_lds_dwordx4 v[232:233], off
	s_waitcnt vmcnt(8)
	s_waitcnt lgkmcnt(0)
	s_barrier
; #define G8_STA(bufoff, ptr, sg, h) G8_STAGE1(bufoff, (ptr) + (h) * ((sg) ? hA1 : hA0), ((sg) ? voffA1 : voffA0), ((sg) ? r64A1 : r64A0))
; #define G8_LDA(dst, b, h) do { _Pragma("unroll") for (int m = 0; m < 4; ++m) _Pragma("unroll") for (int k = 0; k < 2; ++k) dst[m][k] = *(const LAS bf16x8*)(lds + G8_SA(b, h) + aoff + m * 2048 + k * 1024); } while (0)
; #define G8_LDB(dst, b, h) do { _Pragma("unroll") for (int n = 0; n < 2; ++n) _Pragma("unroll") for (int k = 0; k < 2; ++k) dst[n][k] = *(const LAS bf16x8*)(lds + G8_SB(b, h) + boff + n * 2048 + k * 1024); } while (0)
; #define G8_MMA(ai, bj, At, Bt) do { __builtin_amdgcn_s_setprio(1); _Pragma("unroll") for (int m = 0; m < 4; ++m) _Pragma("unroll") for (int n = 0; n < 2; ++n) _Pragma("unroll") for (int k = 0; k < 2; ++k) \
;         acc[ai][bj][m][n] = __builtin_amdgcn_mfma_f32_16x16x32_bf16(Bt[n][k], At[m][k], acc[ai][bj][m][n], 0, 0, 0); __builtin_amdgcn_s_setprio(0); } while (0)
; #define G8_WAIT_V(n) asm volatile("s_waitcnt vmcnt(" #n ")" ::: "memory")
; #define G8_WAIT_L(n) asm volatile("s_waitcnt lgkmcnt(" #n ")" ::: "memory")
; #define G8_BAR __builtin_amdgcn_s_barrier()
; #define G8_SCHED __builtin_amdgcn_sched_barrier(0)
; template <class P>
; __device__ __forceinline__ void gemm_phase(LAS unsigned char* lds, const P& p, const int G, const int c) {
;     ...
;             G8_WAIT_V(8); G8_WAIT_L(0); G8_BAR; G8_MMA(1, 0, At, B0); G8_MMA(1, 1, At, B1); G8_BAR; G8_SCHED;
;             G8_LDB(B0, 1, 0); G8_LDB(B1, 1, 1); G8_SCHED; G8_LDA(At, 1, 0); G8_STA(G8_SA(0, 1), a2, sg2, 1);
;             G8_WAIT_V(8); G8_WAIT_L(0); G8_BAR; G8_MMA(0, 0, At, B0); G8_MMA(0, 1, At, B1); G8_BAR; G8_SCHED;
	s_waitcnt lgkmcnt(0)
	v_mfma_f32_16x16x32_bf16 v[62:65], v[132:135], v[196:199], v[62:65]
	v_mfma_f32_16x16x32_bf16 v[58:61], v[140:143], v[196:199], v[58:61]
	v_mfma_f32_16x16x32_bf16 v[54:57], v[132:135], v[204:207], v[54:57]
	v_mfma_f32_16x16x32_bf16 v[50:53], v[140:143], v[204:207], v[50:53]
	v_mfma_f32_16x16x32_bf16 v[46:49], v[132:135], v[214:217], v[46:49]
	v_mfma_f32_16x16x32_bf16 v[38:41], v[140:143], v[214:217], v[38:41]
	v_mfma_f32_16x16x32_bf16 v[30:33], v[132:135], v[222:225], v[30:33]
	v_mfma_f32_16x16x32_bf16 v[22:25], v[140:143], v[222:225], v[22:25]
	v_mfma_f32_16x16x32_bf16 v[62:65], v[136:139], v[200:203], v[62:65]
	v_mfma_f32_16x16x32_bf16 v[58:61], v[176:179], v[200:203], v[58:61]
	v_mfma_f32_16x16x32_bf16 v[54:57], v[136:139], v[210:213], v[54:57]
	v_mfma_f32_16x16x32_bf16 v[50:53], v[176:179], v[210:213], v[50:53]
	v_mfma_f32_16x16x32_bf16 v[46:49], v[136:139], v[218:221], v[46:49]
	v_mfma_f32_16x16x32_bf16 v[38:41], v[176:179], v[218:221], v[38:41]
	v_mfma_f32_16x16x32_bf16 v[30:33], v[136:139], v[226:229], v[30:33]
	v_mfma_f32_16x16x32_bf16 v[22:25], v[176:179], v[226:229], v[22:25]
	v_mfma_f32_16x16x32_bf16 v[42:45], v[180:183], v[196:199], v[42:45]
	v_mfma_f32_16x16x32_bf16 v[34:37], v[188:191], v[196:199], v[34:37]
	v_mfma_f32_16x16x32_bf16 v[26:29], v[180:183], v[204:207], v[26:29]
	v_mfma_f32_16x16x32_bf16 v[18:21], v[188:191], v[204:207], v[18:21]
	v_mfma_f32_16x16x32_bf16 v[14:17], v[180:183], v[214:217], v[14:17]
	v_mfma_f32_16x16x32_bf16 v[10:13], v[188:191], v[214:217], v[10:13]
	v_mfma_f32_16x16x32_bf16 v[6:9], v[180:183], v[222:225], v[6:9]
	v_mfma_f32_16x16x32_bf16 v[2:5], v[188:191], v[222:225], v[2:5]
	v_mfma_f32_16x16x32_bf16 v[42:45], v[184:187], v[200:203], v[42:45]
	v_mfma_f32_16x16x32_bf16 v[34:37], v[192:195], v[200:203], v[34:37]
	v_mfma_f32_16x16x32_bf16 v[26:29], v[184:187], v[210:213], v[26:29]
	v_mfma_f32_16x16x32_bf16 v[18:21], v[192:195], v[210:213], v[18:21]
	v_mfma_f32_16x16x32_bf16 v[14:17], v[184:187], v[218:221], v[14:17]
	v_mfma_f32_16x16x32_bf16 v[10:13], v[192:195], v[218:221], v[10:13]
	v_mfma_f32_16x16x32_bf16 v[6:9], v[184:187], v[226:229], v[6:9]
	v_mfma_f32_16x16x32_bf16 v[2:5], v[192:195], v[226:229], v[2:5]
	s_barrier
	s_add_i32 s28, 0, 0x18000
	s_add_i32 s29, 0, 0x1c000
	v_add_u32_e32 v176, s28, v1
	v_add_u32_e32 v192, s29, v1
	ds_read_b128 v[132:135], v176
	ds_read_b128 v[136:139], v176 offset:1024
	ds_read_b128 v[140:143], v176 offset:2048
	ds_read_b128 v[176:179], v176 offset:3072
	ds_read_b128 v[180:183], v192
	ds_read_b128 v[184:187], v192 offset:1024
	ds_read_b128 v[188:191], v192 offset:2048
	ds_read_b128 v[192:195], v192 offset:3072
	s_mov_b32 m0, s34
	v_lshl_add_u64 v[232:233], v[230:231], 0, s[12:13]
	ds_read_b128 v[196:199], v175 offset:32768
	ds_read_b128 v[200:203], v175 offset:33792
	ds_read_b128 v[204:207], v175 offset:34816
	ds_read_b128 v[210:213], v175 offset:35840
	ds_read_b128 v[214:217], v175 offset:36864
	ds_read_b128 v[218:221], v175 offset:37888
	ds_read_b128 v[222:225], v175 offset:38912
	ds_read_b128 v[226:229], v175 offset:39936
	global_load_lds_dwordx4 v[232:233], off
	v_lshl_add_u64 v[232:233], v[230:231], 0, s[14:15]
	s_mov_b32 m0, s35
	s_nop 0
	global_load_lds_dwordx4 v[232:233], off
	s_waitcnt vmcnt(8)
	s_waitcnt lgkmcnt(0)
	s_barrier
	s_waitcnt lgkmcnt(0)
	v_mfma_f32_16x16x32_bf16 v[126:129], v[132:135], v[196:199], v[126:129]
	v_mfma_f32_16x16x32_bf16 v[122:125], v[140:143], v[196:199], v[122:125]
	v_mfma_f32_16x16x32_bf16 v[118:121], v[132:135], v[204:207], v[118:121]
	v_mfma_f32_16x16x32_bf16 v[114:117], v[140:143], v[204:207], v[114:117]
	v_mfma_f32_16x16x32_bf16 v[106:109], v[132:135], v[214:217], v[106:109]
	v_mfma_f32_16x16x32_bf16 v[98:101], v[140:143], v[214:217], v[98:101]
	v_mfma_f32_16x16x32_bf16 v[94:97], v[132:135], v[222:225], v[94:97]
	v_mfma_f32_16x16x32_bf16 v[86:89], v[140:143], v[222:225], v[86:89]
	v_mfma_f32_16x16x32_bf16 v[126:129], v[136:139], v[200:203], v[126:129]
	v_mfma_f32_16x16x32_bf16 v[122:125], v[176:179], v[200:203], v[122:125]
	v_mfma_f32_16x16x32_bf16 v[118:121], v[136:139], v[210:213], v[118:121]
	v_mfma_f32_16x16x32_bf16 v[114:117], v[176:179], v[210:213], v[114:117]
	v_mfma_f32_16x16x32_bf16 v[106:109], v[136:139], v[218:221], v[106:109]
	v_mfma_f32_16x16x32_bf16 v[98:101], v[176:179], v[218:221], v[98:101]
	v_mfma_f32_16x16x32_bf16 v[94:97], v[136:139], v[226:229], v[94:97]
	v_mfma_f32_16x16x32_bf16 v[86:89], v[176:179], v[226:229], v[86:89]
	v_mfma_f32_16x16x32_bf16 v[110:113], v[180:183], v[196:199], v[110:113]
	v_mfma_f32_16x16x32_bf16 v[102:105], v[188:191], v[196:199], v[102:105]
	v_mfma_f32_16x16x32_bf16 v[90:93], v[180:183], v[204:207], v[90:93]
	v_mfma_f32_16x16x32_bf16 v[82:85], v[188:191], v[204:207], v[82:85]
	v_mfma_f32_16x16x32_bf16 v[78:81], v[180:183], v[214:217], v[78:81]
	v_mfma_f32_16x16x32_bf16 v[74:77], v[188:191], v[214:217], v[74:77]
	v_mfma_f32_16x16x32_bf16 v[70:73], v[180:183], v[222:225], v[70:73]
	v_mfma_f32_16x16x32_bf16 v[66:69], v[188:191], v[222:225], v[66:69]
	v_mfma_f32_16x16x32_bf16 v[110:113], v[184:187], v[200:203], v[110:113]
	v_mfma_f32_16x16x32_bf16 v[102:105], v[192:195], v[200:203], v[102:105]
	v_mfma_f32_16x16x32_bf16 v[90:93], v[184:187], v[210:213], v[90:93]
	v_mfma_f32_16x16x32_bf16 v[82:85], v[192:195], v[210:213], v[82:85]
	v_mfma_f32_16x16x32_bf16 v[78:81], v[184:187], v[218:221], v[78:81]
	v_mfma_f32_16x16x32_bf16 v[74:77], v[192:195], v[218:221], v[74:77]
	v_mfma_f32_16x16x32_bf16 v[70:73], v[184:187], v[226:229], v[70:73]
	v_mfma_f32_16x16x32_bf16 v[66:69], v[192:195], v[226:229], v[66:69]
	s_barrier
; #define G8_STA(bufoff, ptr, sg, h) G8_STAGE1(bufoff, (ptr) + (h) * ((sg) ? hA1 : hA0), ((sg) ? voffA1 : voffA0), ((sg) ? r64A1 : r64A0))
; #define G8_STB(bufoff, ptr, sg, h) G8_STAGE1(bufoff, (ptr) + (h) * ((sg) ? hB1 : hB0), ((sg) ? voffB1 : voffB0), ((sg) ? r64B1 : r64B0))
; #define G8_LDA(dst, b, h) do { _Pragma("unroll") for (int m = 0; m < 4; ++m) _Pragma("unroll") for (int k = 0; k < 2; ++k) dst[m][k] = *(const LAS bf16x8*)(lds + G8_SA(b, h) + aoff + m * 2048 + k * 1024); } while (0)
; #define G8_MMA(ai, bj, At, Bt) do { __builtin_amdgcn_s_setprio(1); _Pragma("unroll") for (int m = 0; m < 4; ++m) _Pragma("unroll") for (int n = 0; n < 2; ++n) _Pragma("unroll") for (int k = 0; k < 2; ++k) \
;         acc[ai][bj][m][n] = __builtin_amdgcn_mfma_f32_16x16x32_bf16(Bt[n][k], At[m][k], acc[ai][bj][m][n], 0, 0, 0); __builtin_amdgcn_s_setprio(0); } while (0)
; #define G8_WAIT_V(n) asm volatile("s_waitcnt vmcnt(" #n ")" ::: "memory")
; #define G8_WAIT_L(n) asm volatile("s_waitcnt lgkmcnt(" #n ")" ::: "memory")
; #define G8_BAR __builtin_amdgcn_s_barrier()
; #define G8_SCHED __builtin_amdgcn_sched_barrier(0)
; template <class P>
; __device__ __forceinline__ void gemm_phase(LAS unsigned char* lds, const P& p, const int G, const int c) {
;     ...
;             G8_LDA(At, 1, 1); G8_STB(G8_SB(1, 0), b3, sg2, 0); G8_STB(G8_SB(1, 1), b3, sg2, 1); G8_STA(G8_SA(1, 0), a3, sg2, 0);
;             G8_WAIT_V(8); G8_WAIT_L(0); G8_BAR; G8_MMA(1, 0, At, B0); G8_MMA(1, 1, At, B1); G8_BAR; G8_SCHED;
;         }
	s_add_i32 s28, s28, s26
	v_lshl_add_u64 v[232:233], v[144:145], 0, s[20:21]
	s_mov_b32 m0, s28
	ds_read_b128 v[196:199], v175 offset:49152
	ds_read_b128 v[200:203], v175 offset:50176
	ds_read_b128 v[204:207], v175 offset:51200
	ds_read_b128 v[210:213], v175 offset:52224
	ds_read_b128 v[214:217], v175 offset:53248
	ds_read_b128 v[218:221], v175 offset:54272
	ds_read_b128 v[222:225], v175 offset:55296
	ds_read_b128 v[226:229], v175 offset:56320
	global_load_lds_dwordx4 v[232:233], off
	v_lshl_add_u64 v[232:233], v[144:145], 0, s[22:23]
	s_add_i32 m0, s28, 0x2000
	s_add_i32 s28, s29, s26
	global_load_lds_dwordx4 v[232:233], off
	v_lshl_add_u64 v[232:233], v[144:145], 0, s[40:41]
	s_mov_b32 m0, s28
	v_lshl_add_u64 v[144:145], v[144:145], 0, s[42:43]
	global_load_lds_dwordx4 v[232:233], off
	s_add_i32 m0, s28, 0x2000
	s_nop 0
	global_load_lds_dwordx4 v[144:145], off
	v_lshl_add_u64 v[144:145], v[230:231], 0, s[36:37]
	s_mov_b32 m0, s50
	s_nop 0
	global_load_lds_dwordx4 v[144:145], off
	v_lshl_add_u64 v[144:145], v[230:231], 0, s[38:39]
	s_mov_b32 m0, s51
	s_nop 0
	global_load_lds_dwordx4 v[144:145], off
	s_waitcnt vmcnt(8)
	s_waitcnt lgkmcnt(0)
	s_barrier
	s_waitcnt lgkmcnt(0)
	v_mfma_f32_16x16x32_bf16 v[62:65], v[132:135], v[196:199], v[62:65]
	v_mfma_f32_16x16x32_bf16 v[58:61], v[140:143], v[196:199], v[58:61]
	v_mfma_f32_16x16x32_bf16 v[54:57], v[132:135], v[204:207], v[54:57]
	v_mfma_f32_16x16x32_bf16 v[50:53], v[140:143], v[204:207], v[50:53]
	v_mfma_f32_16x16x32_bf16 v[46:49], v[132:135], v[214:217], v[46:49]
	v_mfma_f32_16x16x32_bf16 v[38:41], v[140:143], v[214:217], v[38:41]
	v_mfma_f32_16x16x32_bf16 v[30:33], v[132:135], v[222:225], v[30:33]
	v_mfma_f32_16x16x32_bf16 v[22:25], v[140:143], v[222:225], v[22:25]
	v_mfma_f32_16x16x32_bf16 v[62:65], v[136:139], v[200:203], v[62:65]
	v_mfma_f32_16x16x32_bf16 v[58:61], v[176:179], v[200:203], v[58:61]
	v_mfma_f32_16x16x32_bf16 v[54:57], v[136:139], v[210:213], v[54:57]
	v_mfma_f32_16x16x32_bf16 v[50:53], v[176:179], v[210:213], v[50:53]
	v_mfma_f32_16x16x32_bf16 v[46:49], v[136:139], v[218:221], v[46:49]
	v_mfma_f32_16x16x32_bf16 v[38:41], v[176:179], v[218:221], v[38:41]
	v_mfma_f32_16x16x32_bf16 v[30:33], v[136:139], v[226:229], v[30:33]
	v_mfma_f32_16x16x32_bf16 v[22:25], v[176:179], v[226:229], v[22:25]
	v_mfma_f32_16x16x32_bf16 v[42:45], v[180:183], v[196:199], v[42:45]
	v_mfma_f32_16x16x32_bf16 v[34:37], v[188:191], v[196:199], v[34:37]
	v_mfma_f32_16x16x32_bf16 v[26:29], v[180:183], v[204:207], v[26:29]
	v_mfma_f32_16x16x32_bf16 v[18:21], v[188:191], v[204:207], v[18:21]
	v_mfma_f32_16x16x32_bf16 v[14:17], v[180:183], v[214:217], v[14:17]
	v_mfma_f32_16x16x32_bf16 v[10:13], v[188:191], v[214:217], v[10:13]
	v_mfma_f32_16x16x32_bf16 v[6:9], v[180:183], v[222:225], v[6:9]
	v_mfma_f32_16x16x32_bf16 v[2:5], v[188:191], v[222:225], v[2:5]
	v_mfma_f32_16x16x32_bf16 v[42:45], v[184:187], v[200:203], v[42:45]
	v_mfma_f32_16x16x32_bf16 v[34:37], v[192:195], v[200:203], v[34:37]
	v_mfma_f32_16x16x32_bf16 v[26:29], v[184:187], v[210:213], v[26:29]
	v_mfma_f32_16x16x32_bf16 v[18:21], v[192:195], v[210:213], v[18:21]
	v_mfma_f32_16x16x32_bf16 v[14:17], v[184:187], v[218:221], v[14:17]
	v_mfma_f32_16x16x32_bf16 v[10:13], v[192:195], v[218:221], v[10:13]
	v_mfma_f32_16x16x32_bf16 v[6:9], v[184:187], v[226:229], v[6:9]
	v_mfma_f32_16x16x32_bf16 v[2:5], v[192:195], v[226:229], v[2:5]
	s_barrier
	s_add_u32 s19, s19, 0x40000
	s_addc_u32 s49, s49, 0
	s_add_u32 s76, s76, 0x820000
	s_addc_u32 s77, s77, 0
	s_cmp_ge_u32 s57, s5
	s_cbranch_scc1 .LBB0_282

; #define G8_STA(bufoff, ptr, sg, h) G8_STAGE1(bufoff, (ptr) + (h) * ((sg) ? hA1 : hA0), ((sg) ? voffA1 : voffA0), ((sg) ? r64A1 : r64A0))
; #define G8_STB(bufoff, ptr, sg, h) G8_STAGE1(bufoff, (ptr) + (h) * ((sg) ? hB1 : hB0), ((sg) ? voffB1 : voffB0), ((sg) ? r64B1 : r64B0))
; #define G8_LDA(dst, b, h) do { _Pragma("unroll") for (int m = 0; m < 4; ++m) _Pragma("unroll") for (int k = 0; k < 2; ++k) dst[m][k] = *(const LAS bf16x8*)(lds + G8_SA(b, h) + aoff + m * 2048 + k * 1024); } while (0)
; #define G8_LDB(dst, b, h) do { _Pragma("unroll") for (int n = 0; n < 2; ++n) _Pragma("unroll") for (int k = 0; k < 2; ++k) dst[n][k] = *(const LAS bf16x8*)(lds + G8_SB(b, h) + boff + n * 2048 + k * 1024); } while (0)
; #define G8_MMA(ai, bj, At, Bt) do { __builtin_amdgcn_s_setprio(1); _Pragma("unroll") for (int m = 0; m < 4; ++m) _Pragma("unroll") for (int n = 0; n < 2; ++n) _Pragma("unroll") for (int k = 0; k < 2; ++k) \
;         acc[ai][bj][m][n] = __builtin_amdgcn_mfma_f32_16x16x32_bf16(Bt[n][k], At[m][k], acc[ai][bj][m][n], 0, 0, 0); __builtin_amdgcn_s_setprio(0); } while (0)
; #define G8_BAR __builtin_amdgcn_s_barrier()
; template <class P>
; __device__ __forceinline__ void gemm_phase(LAS unsigned char* lds, const P& p, const int G, const int c) {
;     ...
;         for (int t = 0; t < nt; t += 2) {
;             const bool last = (t == nt - 2);
;             const bool sg1 = (NS > 1) && (t + 1 >= nt0);
;             const bool sg2 = (NS > 1) && !last && (t + 2 >= nt0);
;             const char* a1 = sg1 ? cA1 + (long)(t + 1 - nt0) * ksA1 : cA0 + (long)(t + 1) * ksA0;
;             const char* a2 = last ? nA0 : (sg2 ? cA1 + (long)(t + 2 - nt0) * ksA1 : cA0 + (long)(t + 2) * ksA0);
;             const char* b2 = last ? nB0 : (sg2 ? cB1 + (long)(t + 2 - nt0) * ksB1 : cB0 + (long)(t + 2) * ksB0);
;             const char* a3 = a2 + (sg2 ? ksA1 : ksA0); const char* b3 = b2 + (sg2 ? ksB1 : ksB0);
;             G8_LDB(B0, 0, 0); G8_LDB(B1, 0, 1); G8_SCHED; G8_LDA(At, 0, 0); G8_STA(G8_SA(1, 1), a1, sg1, 1);
;             G8_WAIT_V(8); G8_WAIT_L(0); G8_BAR; G8_MMA(0, 0, At, B0); G8_MMA(0, 1, At, B1); G8_BAR; G8_SCHED;
;             G8_LDA(At, 0, 1); G8_STB(G8_SB(0, 0), b2, sg2, 0); G8_STB(G8_SB(0, 1), b2, sg2, 1); G8_STA(G8_SA(0, 0), a2, sg2, 0);
;             G8_WAIT_V(8); G8_WAIT_L(0); G8_BAR; G8_MMA(1, 0, At, B0); G8_MMA(1, 1, At, B1); G8_BAR; G8_SCHED;
.LBB0_410:
	v_add_u32_e32 v130, s65, v137
	ds_read_b128 v[142:145], v130
	ds_read_b128 v[146:149], v130 offset:1024
	ds_read_b128 v[162:165], v130 offset:2048
	ds_read_b128 v[166:169], v130 offset:3072
	v_add_u32_e32 v130, s66, v137
	ds_read_b128 v[170:173], v130
	ds_read_b128 v[174:177], v130 offset:1024
	ds_read_b128 v[178:181], v130 offset:2048
	ds_read_b128 v[182:185], v130 offset:3072
	s_add_i32 s74, s74, 2
	s_and_b64 s[30:31], exec, s[30:31]
	s_cselect_b32 s31, s7, s53
	s_cselect_b32 s30, s18, s19
	v_lshl_add_u64 v[206:207], v[140:141], 0, s[70:71]
	v_lshl_add_u64 v[222:223], v[206:207], 0, s[76:77]
	s_add_i32 m0, s27, 0xc000
	ds_read_b128 v[186:189], v158
	ds_read_b128 v[190:193], v158 offset:1024
	ds_read_b128 v[194:197], v158 offset:2048
	ds_read_b128 v[198:201], v158 offset:3072
	ds_read_b128 v[202:205], v158 offset:4096
	ds_read_b128 v[210:213], v158 offset:5120
	ds_read_b128 v[214:217], v158 offset:6144
	ds_read_b128 v[218:221], v158 offset:7168
	global_load_lds_dwordx4 v[222:223], off
	v_lshl_add_u64 v[206:207], v[206:207], 0, s[48:49]
	s_add_i32 m0, s27, 0xe000
	s_nop 0
	global_load_lds_dwordx4 v[206:207], off
	s_waitcnt vmcnt(8)
	s_waitcnt lgkmcnt(0)
	s_barrier
	s_waitcnt lgkmcnt(0)
	v_mfma_f32_16x16x32_bf16 v[126:129], v[142:145], v[186:189], v[126:129]
	v_mfma_f32_16x16x32_bf16 v[122:125], v[162:165], v[186:189], v[122:125]
	v_mfma_f32_16x16x32_bf16 v[110:113], v[142:145], v[194:197], v[110:113]
	v_mfma_f32_16x16x32_bf16 v[106:109], v[162:165], v[194:197], v[106:109]
	v_mfma_f32_16x16x32_bf16 v[94:97], v[142:145], v[202:205], v[94:97]
	v_mfma_f32_16x16x32_bf16 v[90:93], v[162:165], v[202:205], v[90:93]
	v_mfma_f32_16x16x32_bf16 v[78:81], v[142:145], v[214:217], v[78:81]
	v_mfma_f32_16x16x32_bf16 v[74:77], v[162:165], v[214:217], v[74:77]
	v_mfma_f32_16x16x32_bf16 v[126:129], v[146:149], v[190:193], v[126:129]
	v_mfma_f32_16x16x32_bf16 v[122:125], v[166:169], v[190:193], v[122:125]
	v_mfma_f32_16x16x32_bf16 v[110:113], v[146:149], v[198:201], v[110:113]
	v_mfma_f32_16x16x32_bf16 v[106:109], v[166:169], v[198:201], v[106:109]
	v_mfma_f32_16x16x32_bf16 v[94:97], v[146:149], v[210:213], v[94:97]
	v_mfma_f32_16x16x32_bf16 v[90:93], v[166:169], v[210:213], v[90:93]
	v_mfma_f32_16x16x32_bf16 v[78:81], v[146:149], v[218:221], v[78:81]
	v_mfma_f32_16x16x32_bf16 v[74:77], v[166:169], v[218:221], v[74:77]
	v_mfma_f32_16x16x32_bf16 v[118:121], v[170:173], v[186:189], v[118:121]
	v_mfma_f32_16x16x32_bf16 v[114:117], v[178:181], v[186:189], v[114:117]
	v_mfma_f32_16x16x32_bf16 v[102:105], v[170:173], v[194:197], v[102:105]
	v_mfma_f32_16x16x32_bf16 v[98:101], v[178:181], v[194:197], v[98:101]
	v_mfma_f32_16x16x32_bf16 v[86:89], v[170:173], v[202:205], v[86:89]
	v_mfma_f32_16x16x32_bf16 v[82:85], v[178:181], v[202:205], v[82:85]
	v_mfma_f32_16x16x32_bf16 v[70:73], v[170:173], v[214:217], v[70:73]
	v_mfma_f32_16x16x32_bf16 v[66:69], v[178:181], v[214:217], v[66:69]
	v_mfma_f32_16x16x32_bf16 v[118:121], v[174:177], v[190:193], v[118:121]
	v_mfma_f32_16x16x32_bf16 v[114:117], v[182:185], v[190:193], v[114:117]
	v_mfma_f32_16x16x32_bf16 v[102:105], v[174:177], v[198:201], v[102:105]
	v_mfma_f32_16x16x32_bf16 v[98:101], v[182:185], v[198:201], v[98:101]
	v_mfma_f32_16x16x32_bf16 v[86:89], v[174:177], v[210:213], v[86:89]
	v_mfma_f32_16x16x32_bf16 v[82:85], v[182:185], v[210:213], v[82:85]
	v_mfma_f32_16x16x32_bf16 v[70:73], v[174:177], v[218:221], v[70:73]
	v_mfma_f32_16x16x32_bf16 v[66:69], v[182:185], v[218:221], v[66:69]
	s_barrier
	v_lshl_add_u64 v[206:207], s[30:31], 0, v[132:133]
	s_add_i32 s30, s65, s26
	s_mov_b32 m0, s30
	ds_read_b128 v[186:189], v158 offset:16384
	ds_read_b128 v[190:193], v158 offset:17408
	ds_read_b128 v[194:197], v158 offset:18432
	ds_read_b128 v[198:201], v158 offset:19456
	ds_read_b128 v[202:205], v158 offset:20480
	ds_read_b128 v[210:213], v158 offset:21504
	ds_read_b128 v[214:217], v158 offset:22528
	ds_read_b128 v[218:221], v158 offset:23552
	global_load_lds_dwordx4 v[206:207], off
	v_lshl_add_u64 v[222:223], v[206:207], 0, s[8:9]
	s_add_i32 m0, s30, 0x2000
	s_add_i32 s30, s66, s26
	global_load_lds_dwordx4 v[222:223], off
	v_lshl_add_u64 v[222:223], v[206:207], 0, s[10:11]
	s_mov_b32 m0, s30
	s_nop 0
	global_load_lds_dwordx4 v[222:223], off
	v_lshl_add_u64 v[222:223], v[206:207], 0, s[12:13]
	s_add_i32 m0, s30, 0x2000
	s_nop 0
	global_load_lds_dwordx4 v[222:223], off
	v_lshl_add_u64 v[222:223], s[28:29], 0, v[134:135]
	s_mov_b32 m0, s27
	v_lshl_add_u64 v[224:225], v[222:223], 0, s[8:9]
	global_load_lds_dwordx4 v[222:223], off
	s_mov_b32 m0, s33
	s_nop 0
	global_load_lds_dwordx4 v[224:225], off
	s_waitcnt vmcnt(8)
	s_waitcnt lgkmcnt(0)
	s_barrier
; #define G8_STA(bufoff, ptr, sg, h) G8_STAGE1(bufoff, (ptr) + (h) * ((sg) ? hA1 : hA0), ((sg) ? voffA1 : voffA0), ((sg) ? r64A1 : r64A0))
; #define G8_LDA(dst, b, h) do { _Pragma("unroll") for (int m = 0; m < 4; ++m) _Pragma("unroll") for (int k = 0; k < 2; ++k) dst[m][k] = *(const LAS bf16x8*)(lds + G8_SA(b, h) + aoff + m * 2048 + k * 1024); } while (0)
; #define G8_LDB(dst, b, h) do { _Pragma("unroll") for (int n = 0; n < 2; ++n) _Pragma("unroll") for (int k = 0; k < 2; ++k) dst[n][k] = *(const LAS bf16x8*)(lds + G8_SB(b, h) + boff + n * 2048 + k * 1024); } while (0)
; #define G8_MMA(ai, bj, At, Bt) do { __builtin_amdgcn_s_setprio(1); _Pragma("unroll") for (int m = 0; m < 4; ++m) _Pragma("unroll") for (int n = 0; n < 2; ++n) _Pragma("unroll") for (int k = 0; k < 2; ++k) \
;         acc[ai][bj][m][n] = __builtin_amdgcn_mfma_f32_16x16x32_bf16(Bt[n][k], At[m][k], acc[ai][bj][m][n], 0, 0, 0); __builtin_amdgcn_s_setprio(0); } while (0)
; #define G8_WAIT_V(n) asm volatile("s_waitcnt vmcnt(" #n ")" ::: "memory")
; #define G8_WAIT_L(n) asm volatile("s_waitcnt lgkmcnt(" #n ")" ::: "memory")
; #define G8_BAR __builtin_amdgcn_s_barrier()
; #define G8_SCHED __builtin_amdgcn_sched_barrier(0)
; template <class P>
; __device__ __forceinline__ void gemm_phase(LAS unsigned char* lds, const P& p, const int G, const int c) {
;     ...
;             G8_WAIT_V(8); G8_WAIT_L(0); G8_BAR; G8_MMA(1, 0, At, B0); G8_MMA(1, 1, At, B1); G8_BAR; G8_SCHED;
;             G8_LDB(B0, 1, 0); G8_LDB(B1, 1, 1); G8_SCHED; G8_LDA(At, 1, 0); G8_STA(G8_SA(0, 1), a2, sg2, 1);
;             G8_WAIT_V(8); G8_WAIT_L(0); G8_BAR; G8_MMA(0, 0, At, B0); G8_MMA(0, 1, At, B1); G8_BAR; G8_SCHED;
	s_waitcnt lgkmcnt(0)
	v_mfma_f32_16x16x32_bf16 v[62:65], v[142:145], v[186:189], v[62:65]
	v_mfma_f32_16x16x32_bf16 v[58:61], v[162:165], v[186:189], v[58:61]
	v_mfma_f32_16x16x32_bf16 v[46:49], v[142:145], v[194:197], v[46:49]
	v_mfma_f32_16x16x32_bf16 v[42:45], v[162:165], v[194:197], v[42:45]
	v_mfma_f32_16x16x32_bf16 v[30:33], v[142:145], v[202:205], v[30:33]
	v_mfma_f32_16x16x32_bf16 v[26:29], v[162:165], v[202:205], v[26:29]
	v_mfma_f32_16x16x32_bf16 v[14:17], v[142:145], v[214:217], v[14:17]
	v_mfma_f32_16x16x32_bf16 v[10:13], v[162:165], v[214:217], v[10:13]
	v_mfma_f32_16x16x32_bf16 v[62:65], v[146:149], v[190:193], v[62:65]
	v_mfma_f32_16x16x32_bf16 v[58:61], v[166:169], v[190:193], v[58:61]
	v_mfma_f32_16x16x32_bf16 v[46:49], v[146:149], v[198:201], v[46:49]
	v_mfma_f32_16x16x32_bf16 v[42:45], v[166:169], v[198:201], v[42:45]
	v_mfma_f32_16x16x32_bf16 v[30:33], v[146:149], v[210:213], v[30:33]
	v_mfma_f32_16x16x32_bf16 v[26:29], v[166:169], v[210:213], v[26:29]
	v_mfma_f32_16x16x32_bf16 v[14:17], v[146:149], v[218:221], v[14:17]
	v_mfma_f32_16x16x32_bf16 v[10:13], v[166:169], v[218:221], v[10:13]
	v_mfma_f32_16x16x32_bf16 v[54:57], v[170:173], v[186:189], v[54:57]
	v_mfma_f32_16x16x32_bf16 v[50:53], v[178:181], v[186:189], v[50:53]
	v_mfma_f32_16x16x32_bf16 v[38:41], v[170:173], v[194:197], v[38:41]
	v_mfma_f32_16x16x32_bf16 v[34:37], v[178:181], v[194:197], v[34:37]
	v_mfma_f32_16x16x32_bf16 v[22:25], v[170:173], v[202:205], v[22:25]
	v_mfma_f32_16x16x32_bf16 v[18:21], v[178:181], v[202:205], v[18:21]
	v_mfma_f32_16x16x32_bf16 v[6:9], v[170:173], v[214:217], v[6:9]
	v_mfma_f32_16x16x32_bf16 v[2:5], v[178:181], v[214:217], v[2:5]
	v_mfma_f32_16x16x32_bf16 v[54:57], v[174:177], v[190:193], v[54:57]
	v_mfma_f32_16x16x32_bf16 v[50:53], v[182:185], v[190:193], v[50:53]
	v_mfma_f32_16x16x32_bf16 v[38:41], v[174:177], v[198:201], v[38:41]
	v_mfma_f32_16x16x32_bf16 v[34:37], v[182:185], v[198:201], v[34:37]
	v_mfma_f32_16x16x32_bf16 v[22:25], v[174:177], v[210:213], v[22:25]
	v_mfma_f32_16x16x32_bf16 v[18:21], v[182:185], v[210:213], v[18:21]
	v_mfma_f32_16x16x32_bf16 v[6:9], v[174:177], v[218:221], v[6:9]
	v_mfma_f32_16x16x32_bf16 v[2:5], v[182:185], v[218:221], v[2:5]
	s_barrier
	s_add_i32 s28, 0, 0x18000
	v_add_u32_e32 v130, s28, v137
	s_add_i32 s29, 0, 0x1c000
	ds_read_b128 v[142:145], v130
	ds_read_b128 v[146:149], v130 offset:1024
	ds_read_b128 v[162:165], v130 offset:2048
	ds_read_b128 v[166:169], v130 offset:3072
	v_add_u32_e32 v130, s29, v137
	ds_read_b128 v[170:173], v130
	ds_read_b128 v[174:177], v130 offset:1024
	ds_read_b128 v[178:181], v130 offset:2048
	ds_read_b128 v[182:185], v130 offset:3072
	s_mov_b32 m0, s34
	v_lshl_add_u64 v[224:225], v[222:223], 0, s[10:11]
	ds_read_b128 v[186:189], v158 offset:32768
	ds_read_b128 v[190:193], v158 offset:33792
	ds_read_b128 v[194:197], v158 offset:34816
	ds_read_b128 v[198:201], v158 offset:35840
	ds_read_b128 v[202:205], v158 offset:36864
	ds_read_b128 v[210:213], v158 offset:37888
	ds_read_b128 v[214:217], v158 offset:38912
	ds_read_b128 v[218:221], v158 offset:39936
	global_load_lds_dwordx4 v[224:225], off
	v_lshl_add_u64 v[224:225], v[222:223], 0, s[12:13]
	s_mov_b32 m0, s35
	s_nop 0
	global_load_lds_dwordx4 v[224:225], off
	s_waitcnt vmcnt(8)
	s_waitcnt lgkmcnt(0)
	s_barrier
	s_waitcnt lgkmcnt(0)
	v_mfma_f32_16x16x32_bf16 v[126:129], v[142:145], v[186:189], v[126:129]
	v_mfma_f32_16x16x32_bf16 v[122:125], v[162:165], v[186:189], v[122:125]
	v_mfma_f32_16x16x32_bf16 v[110:113], v[142:145], v[194:197], v[110:113]
	v_mfma_f32_16x16x32_bf16 v[106:109], v[162:165], v[194:197], v[106:109]
	v_mfma_f32_16x16x32_bf16 v[94:97], v[142:145], v[202:205], v[94:97]
	v_mfma_f32_16x16x32_bf16 v[90:93], v[162:165], v[202:205], v[90:93]
	v_mfma_f32_16x16x32_bf16 v[78:81], v[142:145], v[214:217], v[78:81]
	v_mfma_f32_16x16x32_bf16 v[74:77], v[162:165], v[214:217], v[74:77]
	v_mfma_f32_16x16x32_bf16 v[126:129], v[146:149], v[190:193], v[126:129]
	v_mfma_f32_16x16x32_bf16 v[122:125], v[166:169], v[190:193], v[122:125]
	v_mfma_f32_16x16x32_bf16 v[110:113], v[146:149], v[198:201], v[110:113]
	v_mfma_f32_16x16x32_bf16 v[106:109], v[166:169], v[198:201], v[106:109]
	v_mfma_f32_16x16x32_bf16 v[94:97], v[146:149], v[210:213], v[94:97]
	v_mfma_f32_16x16x32_bf16 v[90:93], v[166:169], v[210:213], v[90:93]
	v_mfma_f32_16x16x32_bf16 v[78:81], v[146:149], v[218:221], v[78:81]
	v_mfma_f32_16x16x32_bf16 v[74:77], v[166:169], v[218:221], v[74:77]
	v_mfma_f32_16x16x32_bf16 v[118:121], v[170:173], v[186:189], v[118:121]
	v_mfma_f32_16x16x32_bf16 v[114:117], v[178:181], v[186:189], v[114:117]
	v_mfma_f32_16x16x32_bf16 v[102:105], v[170:173], v[194:197], v[102:105]
	v_mfma_f32_16x16x32_bf16 v[98:101], v[178:181], v[194:197], v[98:101]
	v_mfma_f32_16x16x32_bf16 v[86:89], v[170:173], v[202:205], v[86:89]
	v_mfma_f32_16x16x32_bf16 v[82:85], v[178:181], v[202:205], v[82:85]
	v_mfma_f32_16x16x32_bf16 v[70:73], v[170:173], v[214:217], v[70:73]
	v_mfma_f32_16x16x32_bf16 v[66:69], v[178:181], v[214:217], v[66:69]
	v_mfma_f32_16x16x32_bf16 v[118:121], v[174:177], v[190:193], v[118:121]
	v_mfma_f32_16x16x32_bf16 v[114:117], v[182:185], v[190:193], v[114:117]
	v_mfma_f32_16x16x32_bf16 v[102:105], v[174:177], v[198:201], v[102:105]
	v_mfma_f32_16x16x32_bf16 v[98:101], v[182:185], v[198:201], v[98:101]
	v_mfma_f32_16x16x32_bf16 v[86:89], v[174:177], v[210:213], v[86:89]
	v_mfma_f32_16x16x32_bf16 v[82:85], v[182:185], v[210:213], v[82:85]
	v_mfma_f32_16x16x32_bf16 v[70:73], v[174:177], v[218:221], v[70:73]
	v_mfma_f32_16x16x32_bf16 v[66:69], v[182:185], v[218:221], v[66:69]
	s_barrier
; #define G8_STA(bufoff, ptr, sg, h) G8_STAGE1(bufoff, (ptr) + (h) * ((sg) ? hA1 : hA0), ((sg) ? voffA1 : voffA0), ((sg) ? r64A1 : r64A0))
; #define G8_STB(bufoff, ptr, sg, h) G8_STAGE1(bufoff, (ptr) + (h) * ((sg) ? hB1 : hB0), ((sg) ? voffB1 : voffB0), ((sg) ? r64B1 : r64B0))
; #define G8_LDA(dst, b, h) do { _Pragma("unroll") for (int m = 0; m < 4; ++m) _Pragma("unroll") for (int k = 0; k < 2; ++k) dst[m][k] = *(const LAS bf16x8*)(lds + G8_SA(b, h) + aoff + m * 2048 + k * 1024); } while (0)
; #define G8_MMA(ai, bj, At, Bt) do { __builtin_amdgcn_s_setprio(1); _Pragma("unroll") for (int m = 0; m < 4; ++m) _Pragma("unroll") for (int n = 0; n < 2; ++n) _Pragma("unroll") for (int k = 0; k < 2; ++k) \
;         acc[ai][bj][m][n] = __builtin_amdgcn_mfma_f32_16x16x32_bf16(Bt[n][k], At[m][k], acc[ai][bj][m][n], 0, 0, 0); __builtin_amdgcn_s_setprio(0); } while (0)
; #define G8_WAIT_V(n) asm volatile("s_waitcnt vmcnt(" #n ")" ::: "memory")
; #define G8_WAIT_L(n) asm volatile("s_waitcnt lgkmcnt(" #n ")" ::: "memory")
; #define G8_BAR __builtin_amdgcn_s_barrier()
; #define G8_SCHED __builtin_amdgcn_sched_barrier(0)
; template <class P>
; __device__ __forceinline__ void gemm_phase(LAS unsigned char* lds, const P& p, const int G, const int c) {
;     ...
;             G8_LDA(At, 1, 1); G8_STB(G8_SB(1, 0), b3, sg2, 0); G8_STB(G8_SB(1, 1), b3, sg2, 1); G8_STA(G8_SA(1, 0), a3, sg2, 0);
;             G8_WAIT_V(8); G8_WAIT_L(0); G8_BAR; G8_MMA(1, 0, At, B0); G8_MMA(1, 1, At, B1); G8_BAR; G8_SCHED;
;         }
	s_add_i32 s28, s28, s26
	v_lshl_add_u64 v[224:225], v[206:207], 0, s[20:21]
	s_mov_b32 m0, s28
	ds_read_b128 v[186:189], v158 offset:49152
	ds_read_b128 v[190:193], v158 offset:50176
	ds_read_b128 v[194:197], v158 offset:51200
	ds_read_b128 v[198:201], v158 offset:52224
	ds_read_b128 v[202:205], v158 offset:53248
	ds_read_b128 v[210:213], v158 offset:54272
	ds_read_b128 v[214:217], v158 offset:55296
	ds_read_b128 v[218:221], v158 offset:56320
	global_load_lds_dwordx4 v[224:225], off
	v_lshl_add_u64 v[224:225], v[206:207], 0, s[22:23]
	s_add_i32 m0, s28, 0x2000
	s_add_i32 s28, s29, s26
	global_load_lds_dwordx4 v[224:225], off
	v_lshl_add_u64 v[224:225], v[206:207], 0, s[40:41]
	s_mov_b32 m0, s28
	v_lshl_add_u64 v[206:207], v[206:207], 0, s[42:43]
	global_load_lds_dwordx4 v[224:225], off
	s_add_i32 m0, s28, 0x2000
	s_nop 0
	global_load_lds_dwordx4 v[206:207], off
	v_lshl_add_u64 v[206:207], v[222:223], 0, s[36:37]
	s_mov_b32 m0, s51
	s_nop 0
	global_load_lds_dwordx4 v[206:207], off
	v_lshl_add_u64 v[206:207], v[222:223], 0, s[38:39]
	s_mov_b32 m0, s64
	s_nop 0
	global_load_lds_dwordx4 v[206:207], off
	s_waitcnt vmcnt(8)
	s_waitcnt lgkmcnt(0)
	s_barrier
	s_waitcnt lgkmcnt(0)
	v_mfma_f32_16x16x32_bf16 v[62:65], v[142:145], v[186:189], v[62:65]
	v_mfma_f32_16x16x32_bf16 v[58:61], v[162:165], v[186:189], v[58:61]
	v_mfma_f32_16x16x32_bf16 v[46:49], v[142:145], v[194:197], v[46:49]
	v_mfma_f32_16x16x32_bf16 v[42:45], v[162:165], v[194:197], v[42:45]
	v_mfma_f32_16x16x32_bf16 v[30:33], v[142:145], v[202:205], v[30:33]
	v_mfma_f32_16x16x32_bf16 v[26:29], v[162:165], v[202:205], v[26:29]
	v_mfma_f32_16x16x32_bf16 v[14:17], v[142:145], v[214:217], v[14:17]
	v_mfma_f32_16x16x32_bf16 v[10:13], v[162:165], v[214:217], v[10:13]
	v_mfma_f32_16x16x32_bf16 v[62:65], v[146:149], v[190:193], v[62:65]
	v_mfma_f32_16x16x32_bf16 v[58:61], v[166:169], v[190:193], v[58:61]
	v_mfma_f32_16x16x32_bf16 v[46:49], v[146:149], v[198:201], v[46:49]
	v_mfma_f32_16x16x32_bf16 v[42:45], v[166:169], v[198:201], v[42:45]
	v_mfma_f32_16x16x32_bf16 v[30:33], v[146:149], v[210:213], v[30:33]
	v_mfma_f32_16x16x32_bf16 v[26:29], v[166:169], v[210:213], v[26:29]
	v_mfma_f32_16x16x32_bf16 v[14:17], v[146:149], v[218:221], v[14:17]
	v_mfma_f32_16x16x32_bf16 v[10:13], v[166:169], v[218:221], v[10:13]
	v_mfma_f32_16x16x32_bf16 v[54:57], v[170:173], v[186:189], v[54:57]
	v_mfma_f32_16x16x32_bf16 v[50:53], v[178:181], v[186:189], v[50:53]
	v_mfma_f32_16x16x32_bf16 v[38:41], v[170:173], v[194:197], v[38:41]
	v_mfma_f32_16x16x32_bf16 v[34:37], v[178:181], v[194:197], v[34:37]
	v_mfma_f32_16x16x32_bf16 v[22:25], v[170:173], v[202:205], v[22:25]
	v_mfma_f32_16x16x32_bf16 v[18:21], v[178:181], v[202:205], v[18:21]
	v_mfma_f32_16x16x32_bf16 v[6:9], v[170:173], v[214:217], v[6:9]
	v_mfma_f32_16x16x32_bf16 v[2:5], v[178:181], v[214:217], v[2:5]
	v_mfma_f32_16x16x32_bf16 v[54:57], v[174:177], v[190:193], v[54:57]
	v_mfma_f32_16x16x32_bf16 v[50:53], v[182:185], v[190:193], v[50:53]
	v_mfma_f32_16x16x32_bf16 v[38:41], v[174:177], v[198:201], v[38:41]
	v_mfma_f32_16x16x32_bf16 v[34:37], v[182:185], v[198:201], v[34:37]
	v_mfma_f32_16x16x32_bf16 v[22:25], v[174:177], v[210:213], v[22:25]
	v_mfma_f32_16x16x32_bf16 v[18:21], v[182:185], v[210:213], v[18:21]
	v_mfma_f32_16x16x32_bf16 v[6:9], v[174:177], v[218:221], v[6:9]
	v_mfma_f32_16x16x32_bf16 v[2:5], v[182:185], v[218:221], v[2:5]
	s_barrier
	s_add_u32 s19, s19, 0x100000
	s_addc_u32 s53, s53, 0
	s_add_u32 s70, s70, 0x820000
	s_addc_u32 s71, s71, 0
	s_cmp_ge_u32 s74, s1
	s_cbranch_scc1 .LBB0_415

; #define G8_STA(bufoff, ptr, sg, h) G8_STAGE1(bufoff, (ptr) + (h) * ((sg) ? hA1 : hA0), ((sg) ? voffA1 : voffA0), ((sg) ? r64A1 : r64A0))
; #define G8_STB(bufoff, ptr, sg, h) G8_STAGE1(bufoff, (ptr) + (h) * ((sg) ? hB1 : hB0), ((sg) ? voffB1 : voffB0), ((sg) ? r64B1 : r64B0))
; #define G8_LDA(dst, b, h) do { _Pragma("unroll") for (int m = 0; m < 4; ++m) _Pragma("unroll") for (int k = 0; k < 2; ++k) dst[m][k] = *(const LAS bf16x8*)(lds + G8_SA(b, h) + aoff + m * 2048 + k * 1024); } while (0)
; #define G8_LDB(dst, b, h) do { _Pragma("unroll") for (int n = 0; n < 2; ++n) _Pragma("unroll") for (int k = 0; k < 2; ++k) dst[n][k] = *(const LAS bf16x8*)(lds + G8_SB(b, h) + boff + n * 2048 + k * 1024); } while (0)
; #define G8_MMA(ai, bj, At, Bt) do { __builtin_amdgcn_s_setprio(1); _Pragma("unroll") for (int m = 0; m < 4; ++m) _Pragma("unroll") for (int n = 0; n < 2; ++n) _Pragma("unroll") for (int k = 0; k < 2; ++k) \
;         acc[ai][bj][m][n] = __builtin_amdgcn_mfma_f32_16x16x32_bf16(Bt[n][k], At[m][k], acc[ai][bj][m][n], 0, 0, 0); __builtin_amdgcn_s_setprio(0); } while (0)
; #define G8_BAR __builtin_amdgcn_s_barrier()
; template <class P>
; __device__ __forceinline__ void gemm_phase(LAS unsigned char* lds, const P& p, const int G, const int c) {
;     ...
;         for (int t = 0; t < nt; t += 2) {
;             const bool last = (t == nt - 2);
;             const bool sg1 = (NS > 1) && (t + 1 >= nt0);
;             const bool sg2 = (NS > 1) && !last && (t + 2 >= nt0);
;             const char* a1 = sg1 ? cA1 + (long)(t + 1 - nt0) * ksA1 : cA0 + (long)(t + 1) * ksA0;
;             const char* a2 = last ? nA0 : (sg2 ? cA1 + (long)(t + 2 - nt0) * ksA1 : cA0 + (long)(t + 2) * ksA0);
;             const char* b2 = last ? nB0 : (sg2 ? cB1 + (long)(t + 2 - nt0) * ksB1 : cB0 + (long)(t + 2) * ksB0);
;             const char* a3 = a2 + (sg2 ? ksA1 : ksA0); const char* b3 = b2 + (sg2 ? ksB1 : ksB0);
;             G8_LDB(B0, 0, 0); G8_LDB(B1, 0, 1); G8_SCHED; G8_LDA(At, 0, 0); G8_STA(G8_SA(1, 1), a1, sg1, 1);
;             G8_WAIT_V(8); G8_WAIT_L(0); G8_BAR; G8_MMA(0, 0, At, B0); G8_MMA(0, 1, At, B1); G8_BAR; G8_SCHED;
;             G8_LDA(At, 0, 1); G8_STB(G8_SB(0, 0), b2, sg2, 0); G8_STB(G8_SB(0, 1), b2, sg2, 1); G8_STA(G8_SA(0, 0), a2, sg2, 0);
;             G8_WAIT_V(8); G8_WAIT_L(0); G8_BAR; G8_MMA(1, 0, At, B0); G8_MMA(1, 1, At, B1); G8_BAR; G8_SCHED;
.LBB0_539:
	s_add_u32 s6, s92, s94
	s_addc_u32 s7, s93, s95
	s_add_u32 s6, s6, 0x10000
	s_addc_u32 s7, s7, 0
	s_add_i32 s65, 0, 0x10000
	s_cmp_eq_u32 s94, 0x30000
	s_cselect_b32 s7, s18, s7
	s_cselect_b32 s6, s19, s6
	v_add_u32_e32 v130, s65, v156
	s_cselect_b32 s51, s89, s29
	s_cselect_b32 s50, s88, s28
	s_add_i32 s34, 0, 0x14000
	ds_read_b128 v[160:163], v130
	ds_read_b128 v[164:167], v130 offset:1024
	ds_read_b128 v[168:171], v130 offset:2048
	ds_read_b128 v[172:175], v130 offset:3072
	v_add_u32_e32 v130, s34, v156
	ds_read_b128 v[176:179], v130
	ds_read_b128 v[180:183], v130 offset:1024
	ds_read_b128 v[184:187], v130 offset:2048
	ds_read_b128 v[188:191], v130 offset:3072
	v_lshl_add_u64 v[226:227], v[154:155], 0, s[94:95]
	s_mov_b64 s[54:55], 0xc000
	v_lshl_add_u64 v[228:229], v[226:227], 0, s[54:55]
	s_add_i32 m0, s11, 0xc000
	s_mov_b64 s[54:55], 0xe000
	ds_read_b128 v[192:195], v158
	ds_read_b128 v[196:199], v158 offset:1024
	ds_read_b128 v[200:203], v158 offset:2048
	ds_read_b128 v[204:207], v158 offset:3072
	ds_read_b128 v[210:213], v158 offset:4096
	ds_read_b128 v[214:217], v158 offset:5120
	ds_read_b128 v[218:221], v158 offset:6144
	ds_read_b128 v[222:225], v158 offset:7168
	global_load_lds_dwordx4 v[228:229], off
	v_lshl_add_u64 v[226:227], v[226:227], 0, s[54:55]
	s_add_i32 m0, s11, 0xe000
	s_nop 0
	global_load_lds_dwordx4 v[226:227], off
	s_waitcnt vmcnt(8)
	s_waitcnt lgkmcnt(0)
	s_barrier
	s_waitcnt lgkmcnt(0)
	v_mfma_f32_16x16x32_bf16 v[126:129], v[160:163], v[192:195], v[126:129]
	v_mfma_f32_16x16x32_bf16 v[122:125], v[168:171], v[192:195], v[122:125]
	v_mfma_f32_16x16x32_bf16 v[118:121], v[160:163], v[200:203], v[118:121]
	v_mfma_f32_16x16x32_bf16 v[114:117], v[168:171], v[200:203], v[114:117]
	v_mfma_f32_16x16x32_bf16 v[102:105], v[160:163], v[210:213], v[102:105]
	v_mfma_f32_16x16x32_bf16 v[98:101], v[168:171], v[210:213], v[98:101]
	v_mfma_f32_16x16x32_bf16 v[86:89], v[160:163], v[218:221], v[86:89]
	v_mfma_f32_16x16x32_bf16 v[82:85], v[168:171], v[218:221], v[82:85]
	v_mfma_f32_16x16x32_bf16 v[126:129], v[164:167], v[196:199], v[126:129]
	v_mfma_f32_16x16x32_bf16 v[122:125], v[172:175], v[196:199], v[122:125]
	v_mfma_f32_16x16x32_bf16 v[118:121], v[164:167], v[204:207], v[118:121]
	v_mfma_f32_16x16x32_bf16 v[114:117], v[172:175], v[204:207], v[114:117]
	v_mfma_f32_16x16x32_bf16 v[102:105], v[164:167], v[214:217], v[102:105]
	v_mfma_f32_16x16x32_bf16 v[98:101], v[172:175], v[214:217], v[98:101]
	v_mfma_f32_16x16x32_bf16 v[86:89], v[164:167], v[222:225], v[86:89]
	v_mfma_f32_16x16x32_bf16 v[82:85], v[172:175], v[222:225], v[82:85]
	v_mfma_f32_16x16x32_bf16 v[110:113], v[176:179], v[192:195], v[110:113]
	v_mfma_f32_16x16x32_bf16 v[106:109], v[184:187], v[192:195], v[106:109]
	v_mfma_f32_16x16x32_bf16 v[94:97], v[176:179], v[200:203], v[94:97]
	v_mfma_f32_16x16x32_bf16 v[90:93], v[184:187], v[200:203], v[90:93]
	v_mfma_f32_16x16x32_bf16 v[78:81], v[176:179], v[210:213], v[78:81]
	v_mfma_f32_16x16x32_bf16 v[74:77], v[184:187], v[210:213], v[74:77]
	v_mfma_f32_16x16x32_bf16 v[70:73], v[176:179], v[218:221], v[70:73]
	v_mfma_f32_16x16x32_bf16 v[66:69], v[184:187], v[218:221], v[66:69]
	v_mfma_f32_16x16x32_bf16 v[110:113], v[180:183], v[196:199], v[110:113]
	v_mfma_f32_16x16x32_bf16 v[106:109], v[188:191], v[196:199], v[106:109]
	v_mfma_f32_16x16x32_bf16 v[94:97], v[180:183], v[204:207], v[94:97]
	v_mfma_f32_16x16x32_bf16 v[90:93], v[188:191], v[204:207], v[90:93]
	v_mfma_f32_16x16x32_bf16 v[78:81], v[180:183], v[214:217], v[78:81]
	v_mfma_f32_16x16x32_bf16 v[74:77], v[188:191], v[214:217], v[74:77]
	v_mfma_f32_16x16x32_bf16 v[70:73], v[180:183], v[222:225], v[70:73]
	v_mfma_f32_16x16x32_bf16 v[66:69], v[188:191], v[222:225], v[66:69]
	s_barrier
	s_add_i32 s20, s65, s10
	v_lshl_add_u64 v[226:227], s[50:51], 0, v[132:133]
	s_mov_b32 m0, s20
	ds_read_b128 v[192:195], v158 offset:16384
	ds_read_b128 v[196:199], v158 offset:17408
	ds_read_b128 v[200:203], v158 offset:18432
	ds_read_b128 v[204:207], v158 offset:19456
	ds_read_b128 v[210:213], v158 offset:20480
	ds_read_b128 v[214:217], v158 offset:21504
	ds_read_b128 v[218:221], v158 offset:22528
	ds_read_b128 v[222:225], v158 offset:23552
	global_load_lds_dwordx4 v[226:227], off
	v_lshl_add_u64 v[228:229], v[226:227], 0, s[22:23]
	s_add_i32 m0, s20, 0x2000
	s_add_i32 s20, s34, s10
	global_load_lds_dwordx4 v[228:229], off
	v_lshl_add_u64 v[228:229], v[226:227], 0, s[36:37]
	s_mov_b32 m0, s20
	s_nop 0
	global_load_lds_dwordx4 v[228:229], off
	v_lshl_add_u64 v[228:229], v[226:227], 0, s[38:39]
	s_add_i32 m0, s20, 0x2000
	s_nop 0
	global_load_lds_dwordx4 v[228:229], off
	v_lshl_add_u64 v[228:229], s[6:7], 0, v[134:135]
	s_mov_b32 m0, s11
	v_lshl_add_u64 v[230:231], v[228:229], 0, s[22:23]
	global_load_lds_dwordx4 v[228:229], off
	s_mov_b32 m0, s14
	s_nop 0
	global_load_lds_dwordx4 v[230:231], off
	s_waitcnt vmcnt(8)
	s_waitcnt lgkmcnt(0)
	s_barrier
; #define G8_STA(bufoff, ptr, sg, h) G8_STAGE1(bufoff, (ptr) + (h) * ((sg) ? hA1 : hA0), ((sg) ? voffA1 : voffA0), ((sg) ? r64A1 : r64A0))
; #define G8_LDA(dst, b, h) do { _Pragma("unroll") for (int m = 0; m < 4; ++m) _Pragma("unroll") for (int k = 0; k < 2; ++k) dst[m][k] = *(const LAS bf16x8*)(lds + G8_SA(b, h) + aoff + m * 2048 + k * 1024); } while (0)
; #define G8_LDB(dst, b, h) do { _Pragma("unroll") for (int n = 0; n < 2; ++n) _Pragma("unroll") for (int k = 0; k < 2; ++k) dst[n][k] = *(const LAS bf16x8*)(lds + G8_SB(b, h) + boff + n * 2048 + k * 1024); } while (0)
; #define G8_MMA(ai, bj, At, Bt) do { __builtin_amdgcn_s_setprio(1); _Pragma("unroll") for (int m = 0; m < 4; ++m) _Pragma("unroll") for (int n = 0; n < 2; ++n) _Pragma("unroll") for (int k = 0; k < 2; ++k) \
;         acc[ai][bj][m][n] = __builtin_amdgcn_mfma_f32_16x16x32_bf16(Bt[n][k], At[m][k], acc[ai][bj][m][n], 0, 0, 0); __builtin_amdgcn_s_setprio(0); } while (0)
; #define G8_WAIT_V(n) asm volatile("s_waitcnt vmcnt(" #n ")" ::: "memory")
; #define G8_WAIT_L(n) asm volatile("s_waitcnt lgkmcnt(" #n ")" ::: "memory")
; #define G8_BAR __builtin_amdgcn_s_barrier()
; #define G8_SCHED __builtin_amdgcn_sched_barrier(0)
; template <class P>
; __device__ __forceinline__ void gemm_phase(LAS unsigned char* lds, const P& p, const int G, const int c) {
;     ...
;             G8_WAIT_V(8); G8_WAIT_L(0); G8_BAR; G8_MMA(1, 0, At, B0); G8_MMA(1, 1, At, B1); G8_BAR; G8_SCHED;
;             G8_LDB(B0, 1, 0); G8_LDB(B1, 1, 1); G8_SCHED; G8_LDA(At, 1, 0); G8_STA(G8_SA(0, 1), a2, sg2, 1);
;             G8_WAIT_V(8); G8_WAIT_L(0); G8_BAR; G8_MMA(0, 0, At, B0); G8_MMA(0, 1, At, B1); G8_BAR; G8_SCHED;
	s_waitcnt lgkmcnt(0)
	v_mfma_f32_16x16x32_bf16 v[62:65], v[160:163], v[192:195], v[62:65]
	v_mfma_f32_16x16x32_bf16 v[58:61], v[168:171], v[192:195], v[58:61]
	v_mfma_f32_16x16x32_bf16 v[54:57], v[160:163], v[200:203], v[54:57]
	v_mfma_f32_16x16x32_bf16 v[50:53], v[168:171], v[200:203], v[50:53]
	v_mfma_f32_16x16x32_bf16 v[38:41], v[160:163], v[210:213], v[38:41]
	v_mfma_f32_16x16x32_bf16 v[34:37], v[168:171], v[210:213], v[34:37]
	v_mfma_f32_16x16x32_bf16 v[22:25], v[160:163], v[218:221], v[22:25]
	v_mfma_f32_16x16x32_bf16 v[18:21], v[168:171], v[218:221], v[18:21]
	v_mfma_f32_16x16x32_bf16 v[62:65], v[164:167], v[196:199], v[62:65]
	v_mfma_f32_16x16x32_bf16 v[58:61], v[172:175], v[196:199], v[58:61]
	v_mfma_f32_16x16x32_bf16 v[54:57], v[164:167], v[204:207], v[54:57]
	v_mfma_f32_16x16x32_bf16 v[50:53], v[172:175], v[204:207], v[50:53]
	v_mfma_f32_16x16x32_bf16 v[38:41], v[164:167], v[214:217], v[38:41]
	v_mfma_f32_16x16x32_bf16 v[34:37], v[172:175], v[214:217], v[34:37]
	v_mfma_f32_16x16x32_bf16 v[22:25], v[164:167], v[222:225], v[22:25]
	v_mfma_f32_16x16x32_bf16 v[18:21], v[172:175], v[222:225], v[18:21]
	v_mfma_f32_16x16x32_bf16 v[46:49], v[176:179], v[192:195], v[46:49]
	v_mfma_f32_16x16x32_bf16 v[42:45], v[184:187], v[192:195], v[42:45]
	v_mfma_f32_16x16x32_bf16 v[30:33], v[176:179], v[200:203], v[30:33]
	v_mfma_f32_16x16x32_bf16 v[26:29], v[184:187], v[200:203], v[26:29]
	v_mfma_f32_16x16x32_bf16 v[14:17], v[176:179], v[210:213], v[14:17]
	v_mfma_f32_16x16x32_bf16 v[10:13], v[184:187], v[210:213], v[10:13]
	v_mfma_f32_16x16x32_bf16 v[6:9], v[176:179], v[218:221], v[6:9]
	v_mfma_f32_16x16x32_bf16 v[2:5], v[184:187], v[218:221], v[2:5]
	v_mfma_f32_16x16x32_bf16 v[46:49], v[180:183], v[196:199], v[46:49]
	v_mfma_f32_16x16x32_bf16 v[42:45], v[188:191], v[196:199], v[42:45]
	v_mfma_f32_16x16x32_bf16 v[30:33], v[180:183], v[204:207], v[30:33]
	v_mfma_f32_16x16x32_bf16 v[26:29], v[188:191], v[204:207], v[26:29]
	v_mfma_f32_16x16x32_bf16 v[14:17], v[180:183], v[214:217], v[14:17]
	v_mfma_f32_16x16x32_bf16 v[10:13], v[188:191], v[214:217], v[10:13]
	v_mfma_f32_16x16x32_bf16 v[6:9], v[180:183], v[222:225], v[6:9]
	v_mfma_f32_16x16x32_bf16 v[2:5], v[188:191], v[222:225], v[2:5]
	s_barrier
	s_add_i32 s35, 0, 0x18000
	v_add_u32_e32 v130, s35, v156
	s_add_i32 s20, 0, 0x1c000
	ds_read_b128 v[160:163], v130
	ds_read_b128 v[164:167], v130 offset:1024
	ds_read_b128 v[168:171], v130 offset:2048
	ds_read_b128 v[172:175], v130 offset:3072
	v_add_u32_e32 v130, s20, v156
	ds_read_b128 v[176:179], v130
	ds_read_b128 v[180:183], v130 offset:1024
	ds_read_b128 v[184:187], v130 offset:2048
	ds_read_b128 v[188:191], v130 offset:3072
	s_mov_b32 m0, s15
	v_lshl_add_u64 v[230:231], v[228:229], 0, s[36:37]
	ds_read_b128 v[192:195], v158 offset:32768
	ds_read_b128 v[196:199], v158 offset:33792
	ds_read_b128 v[200:203], v158 offset:34816
	ds_read_b128 v[204:207], v158 offset:35840
	ds_read_b128 v[210:213], v158 offset:36864
	ds_read_b128 v[214:217], v158 offset:37888
	ds_read_b128 v[218:221], v158 offset:38912
	ds_read_b128 v[222:225], v158 offset:39936
	global_load_lds_dwordx4 v[230:231], off
	v_lshl_add_u64 v[230:231], v[228:229], 0, s[38:39]
	s_mov_b32 m0, s16
	s_nop 0
	global_load_lds_dwordx4 v[230:231], off
	s_waitcnt vmcnt(8)
	s_waitcnt lgkmcnt(0)
	s_barrier
	s_waitcnt lgkmcnt(0)
	v_mfma_f32_16x16x32_bf16 v[126:129], v[160:163], v[192:195], v[126:129]
	v_mfma_f32_16x16x32_bf16 v[122:125], v[168:171], v[192:195], v[122:125]
	v_mfma_f32_16x16x32_bf16 v[118:121], v[160:163], v[200:203], v[118:121]
	v_mfma_f32_16x16x32_bf16 v[114:117], v[168:171], v[200:203], v[114:117]
	v_mfma_f32_16x16x32_bf16 v[102:105], v[160:163], v[210:213], v[102:105]
	v_mfma_f32_16x16x32_bf16 v[98:101], v[168:171], v[210:213], v[98:101]
	v_mfma_f32_16x16x32_bf16 v[86:89], v[160:163], v[218:221], v[86:89]
	v_mfma_f32_16x16x32_bf16 v[82:85], v[168:171], v[218:221], v[82:85]
	v_mfma_f32_16x16x32_bf16 v[126:129], v[164:167], v[196:199], v[126:129]
	v_mfma_f32_16x16x32_bf16 v[122:125], v[172:175], v[196:199], v[122:125]
	v_mfma_f32_16x16x32_bf16 v[118:121], v[164:167], v[204:207], v[118:121]
	v_mfma_f32_16x16x32_bf16 v[114:117], v[172:175], v[204:207], v[114:117]
	v_mfma_f32_16x16x32_bf16 v[102:105], v[164:167], v[214:217], v[102:105]
	v_mfma_f32_16x16x32_bf16 v[98:101], v[172:175], v[214:217], v[98:101]
	v_mfma_f32_16x16x32_bf16 v[86:89], v[164:167], v[222:225], v[86:89]
	v_mfma_f32_16x16x32_bf16 v[82:85], v[172:175], v[222:225], v[82:85]
	v_mfma_f32_16x16x32_bf16 v[110:113], v[176:179], v[192:195], v[110:113]
	v_mfma_f32_16x16x32_bf16 v[106:109], v[184:187], v[192:195], v[106:109]
	v_mfma_f32_16x16x32_bf16 v[94:97], v[176:179], v[200:203], v[94:97]
	v_mfma_f32_16x16x32_bf16 v[90:93], v[184:187], v[200:203], v[90:93]
	v_mfma_f32_16x16x32_bf16 v[78:81], v[176:179], v[210:213], v[78:81]
	v_mfma_f32_16x16x32_bf16 v[74:77], v[184:187], v[210:213], v[74:77]
	v_mfma_f32_16x16x32_bf16 v[70:73], v[176:179], v[218:221], v[70:73]
	v_mfma_f32_16x16x32_bf16 v[66:69], v[184:187], v[218:221], v[66:69]
	v_mfma_f32_16x16x32_bf16 v[110:113], v[180:183], v[196:199], v[110:113]
	v_mfma_f32_16x16x32_bf16 v[106:109], v[188:191], v[196:199], v[106:109]
	v_mfma_f32_16x16x32_bf16 v[94:97], v[180:183], v[204:207], v[94:97]
	v_mfma_f32_16x16x32_bf16 v[90:93], v[188:191], v[204:207], v[90:93]
	v_mfma_f32_16x16x32_bf16 v[78:81], v[180:183], v[214:217], v[78:81]
	v_mfma_f32_16x16x32_bf16 v[74:77], v[188:191], v[214:217], v[74:77]
	v_mfma_f32_16x16x32_bf16 v[70:73], v[180:183], v[222:225], v[70:73]
	v_mfma_f32_16x16x32_bf16 v[66:69], v[188:191], v[222:225], v[66:69]
	s_barrier
; #define G8_STA(bufoff, ptr, sg, h) G8_STAGE1(bufoff, (ptr) + (h) * ((sg) ? hA1 : hA0), ((sg) ? voffA1 : voffA0), ((sg) ? r64A1 : r64A0))
; #define G8_STB(bufoff, ptr, sg, h) G8_STAGE1(bufoff, (ptr) + (h) * ((sg) ? hB1 : hB0), ((sg) ? voffB1 : voffB0), ((sg) ? r64B1 : r64B0))
; #define G8_LDA(dst, b, h) do { _Pragma("unroll") for (int m = 0; m < 4; ++m) _Pragma("unroll") for (int k = 0; k < 2; ++k) dst[m][k] = *(const LAS bf16x8*)(lds + G8_SA(b, h) + aoff + m * 2048 + k * 1024); } while (0)
; #define G8_MMA(ai, bj, At, Bt) do { __builtin_amdgcn_s_setprio(1); _Pragma("unroll") for (int m = 0; m < 4; ++m) _Pragma("unroll") for (int n = 0; n < 2; ++n) _Pragma("unroll") for (int k = 0; k < 2; ++k) \
;         acc[ai][bj][m][n] = __builtin_amdgcn_mfma_f32_16x16x32_bf16(Bt[n][k], At[m][k], acc[ai][bj][m][n], 0, 0, 0); __builtin_amdgcn_s_setprio(0); } while (0)
; #define G8_WAIT_V(n) asm volatile("s_waitcnt vmcnt(" #n ")" ::: "memory")
; #define G8_WAIT_L(n) asm volatile("s_waitcnt lgkmcnt(" #n ")" ::: "memory")
; #define G8_BAR __builtin_amdgcn_s_barrier()
; #define G8_SCHED __builtin_amdgcn_sched_barrier(0)
; template <class P>
; __device__ __forceinline__ void gemm_phase(LAS unsigned char* lds, const P& p, const int G, const int c) {
;     ...
;             G8_LDA(At, 1, 1); G8_STB(G8_SB(1, 0), b3, sg2, 0); G8_STB(G8_SB(1, 1), b3, sg2, 1); G8_STA(G8_SA(1, 0), a3, sg2, 0);
;             G8_WAIT_V(8); G8_WAIT_L(0); G8_BAR; G8_MMA(1, 0, At, B0); G8_MMA(1, 1, At, B1); G8_BAR; G8_SCHED;
;         }
;         if (wr == 0) G8_BAR;
	s_add_i32 s6, s35, s10
	v_lshl_add_u64 v[230:231], v[226:227], 0, s[40:41]
	s_mov_b32 m0, s6
	ds_read_b128 v[192:195], v158 offset:49152
	ds_read_b128 v[196:199], v158 offset:50176
	ds_read_b128 v[200:203], v158 offset:51200
	ds_read_b128 v[204:207], v158 offset:52224
	ds_read_b128 v[210:213], v158 offset:53248
	ds_read_b128 v[214:217], v158 offset:54272
	ds_read_b128 v[218:221], v158 offset:55296
	ds_read_b128 v[222:225], v158 offset:56320
	global_load_lds_dwordx4 v[230:231], off
	v_lshl_add_u64 v[230:231], v[226:227], 0, s[42:43]
	s_add_i32 m0, s6, 0x2000
	s_add_i32 s6, s20, s10
	global_load_lds_dwordx4 v[230:231], off
	v_lshl_add_u64 v[230:231], v[226:227], 0, s[48:49]
	s_mov_b32 m0, s6
	v_lshl_add_u64 v[226:227], v[226:227], 0, s[52:53]
	global_load_lds_dwordx4 v[230:231], off
	s_add_i32 m0, s6, 0x2000
	s_nop 0
	global_load_lds_dwordx4 v[226:227], off
	v_lshl_add_u64 v[226:227], v[228:229], 0, s[8:9]
	s_mov_b32 m0, s24
	s_nop 0
	global_load_lds_dwordx4 v[226:227], off
	v_lshl_add_u64 v[226:227], v[228:229], 0, s[44:45]
	s_mov_b32 m0, s25
	s_nop 0
	global_load_lds_dwordx4 v[226:227], off
	s_waitcnt vmcnt(8)
	s_waitcnt lgkmcnt(0)
	s_barrier
	s_waitcnt lgkmcnt(0)
	v_mfma_f32_16x16x32_bf16 v[62:65], v[160:163], v[192:195], v[62:65]
	v_mfma_f32_16x16x32_bf16 v[58:61], v[168:171], v[192:195], v[58:61]
	v_mfma_f32_16x16x32_bf16 v[54:57], v[160:163], v[200:203], v[54:57]
	v_mfma_f32_16x16x32_bf16 v[50:53], v[168:171], v[200:203], v[50:53]
	v_mfma_f32_16x16x32_bf16 v[38:41], v[160:163], v[210:213], v[38:41]
	v_mfma_f32_16x16x32_bf16 v[34:37], v[168:171], v[210:213], v[34:37]
	v_mfma_f32_16x16x32_bf16 v[22:25], v[160:163], v[218:221], v[22:25]
	v_mfma_f32_16x16x32_bf16 v[18:21], v[168:171], v[218:221], v[18:21]
	v_mfma_f32_16x16x32_bf16 v[62:65], v[164:167], v[196:199], v[62:65]
	v_mfma_f32_16x16x32_bf16 v[58:61], v[172:175], v[196:199], v[58:61]
	v_mfma_f32_16x16x32_bf16 v[54:57], v[164:167], v[204:207], v[54:57]
	v_mfma_f32_16x16x32_bf16 v[50:53], v[172:175], v[204:207], v[50:53]
	v_mfma_f32_16x16x32_bf16 v[38:41], v[164:167], v[214:217], v[38:41]
	v_mfma_f32_16x16x32_bf16 v[34:37], v[172:175], v[214:217], v[34:37]
	v_mfma_f32_16x16x32_bf16 v[22:25], v[164:167], v[222:225], v[22:25]
	v_mfma_f32_16x16x32_bf16 v[18:21], v[172:175], v[222:225], v[18:21]
	v_mfma_f32_16x16x32_bf16 v[46:49], v[176:179], v[192:195], v[46:49]
	v_mfma_f32_16x16x32_bf16 v[42:45], v[184:187], v[192:195], v[42:45]
	v_mfma_f32_16x16x32_bf16 v[30:33], v[176:179], v[200:203], v[30:33]
	v_mfma_f32_16x16x32_bf16 v[26:29], v[184:187], v[200:203], v[26:29]
	v_mfma_f32_16x16x32_bf16 v[14:17], v[176:179], v[210:213], v[14:17]
	v_mfma_f32_16x16x32_bf16 v[10:13], v[184:187], v[210:213], v[10:13]
	v_mfma_f32_16x16x32_bf16 v[6:9], v[176:179], v[218:221], v[6:9]
	v_mfma_f32_16x16x32_bf16 v[2:5], v[184:187], v[218:221], v[2:5]
	v_mfma_f32_16x16x32_bf16 v[46:49], v[180:183], v[196:199], v[46:49]
	v_mfma_f32_16x16x32_bf16 v[42:45], v[188:191], v[196:199], v[42:45]
	v_mfma_f32_16x16x32_bf16 v[30:33], v[180:183], v[204:207], v[30:33]
	v_mfma_f32_16x16x32_bf16 v[26:29], v[188:191], v[204:207], v[26:29]
	v_mfma_f32_16x16x32_bf16 v[14:17], v[180:183], v[214:217], v[14:17]
	v_mfma_f32_16x16x32_bf16 v[10:13], v[188:191], v[214:217], v[10:13]
	v_mfma_f32_16x16x32_bf16 v[6:9], v[180:183], v[222:225], v[6:9]
	v_mfma_f32_16x16x32_bf16 v[2:5], v[188:191], v[222:225], v[2:5]
	s_barrier
	s_add_i32 s47, s47, 2
	s_add_u32 s28, s28, 0x40000
	s_addc_u32 s29, s29, 0
	s_add_u32 s94, s94, 0x10000
	s_addc_u32 s95, s95, 0
	s_cmp_gt_u32 s47, 5
	s_cbranch_scc0 .LBB0_539
	s_and_b64 vcc, exec, s[86:87]
	s_cbranch_vccz .LBB0_542
	s_barrier

; #define G8_STA(bufoff, ptr, sg, h) G8_STAGE1(bufoff, (ptr) + (h) * ((sg) ? hA1 : hA0), ((sg) ? voffA1 : voffA0), ((sg) ? r64A1 : r64A0))
; #define G8_STB(bufoff, ptr, sg, h) G8_STAGE1(bufoff, (ptr) + (h) * ((sg) ? hB1 : hB0), ((sg) ? voffB1 : voffB0), ((sg) ? r64B1 : r64B0))
; #define G8_LDA(dst, b, h) do { _Pragma("unroll") for (int m = 0; m < 4; ++m) _Pragma("unroll") for (int k = 0; k < 2; ++k) dst[m][k] = *(const LAS bf16x8*)(lds + G8_SA(b, h) + aoff + m * 2048 + k * 1024); } while (0)
; #define G8_LDB(dst, b, h) do { _Pragma("unroll") for (int n = 0; n < 2; ++n) _Pragma("unroll") for (int k = 0; k < 2; ++k) dst[n][k] = *(const LAS bf16x8*)(lds + G8_SB(b, h) + boff + n * 2048 + k * 1024); } while (0)
; #define G8_MMA(ai, bj, At, Bt) do { __builtin_amdgcn_s_setprio(1); _Pragma("unroll") for (int m = 0; m < 4; ++m) _Pragma("unroll") for (int n = 0; n < 2; ++n) _Pragma("unroll") for (int k = 0; k < 2; ++k) \
;         acc[ai][bj][m][n] = __builtin_amdgcn_mfma_f32_16x16x32_bf16(Bt[n][k], At[m][k], acc[ai][bj][m][n], 0, 0, 0); __builtin_amdgcn_s_setprio(0); } while (0)
; #define G8_BAR __builtin_amdgcn_s_barrier()
; template <class P>
; __device__ __forceinline__ void gemm_phase(LAS unsigned char* lds, const P& p, const int G, const int c) {
;     ...
;         for (int t = 0; t < nt; t += 2) {
;             const bool last = (t == nt - 2);
;             const bool sg1 = (NS > 1) && (t + 1 >= nt0);
;             const bool sg2 = (NS > 1) && !last && (t + 2 >= nt0);
;             const char* a1 = sg1 ? cA1 + (long)(t + 1 - nt0) * ksA1 : cA0 + (long)(t + 1) * ksA0;
;             const char* a2 = last ? nA0 : (sg2 ? cA1 + (long)(t + 2 - nt0) * ksA1 : cA0 + (long)(t + 2) * ksA0);
;             const char* b2 = last ? nB0 : (sg2 ? cB1 + (long)(t + 2 - nt0) * ksB1 : cB0 + (long)(t + 2) * ksB0);
;             const char* a3 = a2 + (sg2 ? ksA1 : ksA0); const char* b3 = b2 + (sg2 ? ksB1 : ksB0);
;             G8_LDB(B0, 0, 0); G8_LDB(B1, 0, 1); G8_SCHED; G8_LDA(At, 0, 0); G8_STA(G8_SA(1, 1), a1, sg1, 1);
;             G8_WAIT_V(8); G8_WAIT_L(0); G8_BAR; G8_MMA(0, 0, At, B0); G8_MMA(0, 1, At, B1); G8_BAR; G8_SCHED;
;             G8_LDA(At, 0, 1); G8_STB(G8_SB(0, 0), b2, sg2, 0); G8_STB(G8_SB(0, 1), b2, sg2, 1); G8_STA(G8_SA(0, 0), a2, sg2, 0);
;             G8_WAIT_V(8); G8_WAIT_L(0); G8_BAR; G8_MMA(1, 0, At, B0); G8_MMA(1, 1, At, B1); G8_BAR; G8_SCHED;
.LBB0_583:
	v_add_u32_e32 v130, s65, v137
	ds_read_b128 v[150:153], v130
	ds_read_b128 v[154:157], v130 offset:1024
	ds_read_b128 v[158:161], v130 offset:2048
	ds_read_b128 v[162:165], v130 offset:3072
	v_add_u32_e32 v130, s34, v137
	ds_read_b128 v[166:169], v130
	ds_read_b128 v[170:173], v130 offset:1024
	ds_read_b128 v[174:177], v130 offset:2048
	ds_read_b128 v[178:181], v130 offset:3072
	s_cmp_gt_u32 s56, 5
	s_cselect_b64 s[18:19], -1, 0
	s_and_b64 vcc, s[6:7], s[18:19]
	s_and_b64 s[6:7], vcc, exec
	s_movk_i32 s6, 0x80
	s_cselect_b32 s6, 0x10000, s6
	v_lshl_add_u64 v[138:139], s[28:29], 0, v[134:135]
	v_lshl_add_u64 v[206:207], v[138:139], 0, s[36:37]
	s_add_i32 m0, s25, 0xc000
	ds_read_b128 v[182:185], v148
	ds_read_b128 v[186:189], v148 offset:1024
	ds_read_b128 v[190:193], v148 offset:2048
	ds_read_b128 v[194:197], v148 offset:3072
	ds_read_b128 v[198:201], v148 offset:4096
	ds_read_b128 v[202:205], v148 offset:5120
	ds_read_b128 v[210:213], v148 offset:6144
	ds_read_b128 v[214:217], v148 offset:7168
	global_load_lds_dwordx4 v[206:207], off
	v_lshl_add_u64 v[138:139], v[138:139], 0, s[38:39]
	s_add_i32 m0, s25, 0xe000
	s_nop 0
	global_load_lds_dwordx4 v[138:139], off
	s_waitcnt vmcnt(8)
	s_waitcnt lgkmcnt(0)
	s_barrier
	s_waitcnt lgkmcnt(0)
	v_mfma_f32_16x16x32_bf16 v[126:129], v[150:153], v[182:185], v[126:129]
	v_mfma_f32_16x16x32_bf16 v[122:125], v[158:161], v[182:185], v[122:125]
	v_mfma_f32_16x16x32_bf16 v[110:113], v[150:153], v[190:193], v[110:113]
	v_mfma_f32_16x16x32_bf16 v[106:109], v[158:161], v[190:193], v[106:109]
	v_mfma_f32_16x16x32_bf16 v[94:97], v[150:153], v[198:201], v[94:97]
	v_mfma_f32_16x16x32_bf16 v[90:93], v[158:161], v[198:201], v[90:93]
	v_mfma_f32_16x16x32_bf16 v[78:81], v[150:153], v[210:213], v[78:81]
	v_mfma_f32_16x16x32_bf16 v[74:77], v[158:161], v[210:213], v[74:77]
	v_mfma_f32_16x16x32_bf16 v[126:129], v[154:157], v[186:189], v[126:129]
	v_mfma_f32_16x16x32_bf16 v[122:125], v[162:165], v[186:189], v[122:125]
	v_mfma_f32_16x16x32_bf16 v[110:113], v[154:157], v[194:197], v[110:113]
	v_mfma_f32_16x16x32_bf16 v[106:109], v[162:165], v[194:197], v[106:109]
	v_mfma_f32_16x16x32_bf16 v[94:97], v[154:157], v[202:205], v[94:97]
	v_mfma_f32_16x16x32_bf16 v[90:93], v[162:165], v[202:205], v[90:93]
	v_mfma_f32_16x16x32_bf16 v[78:81], v[154:157], v[214:217], v[78:81]
	v_mfma_f32_16x16x32_bf16 v[74:77], v[162:165], v[214:217], v[74:77]
	v_mfma_f32_16x16x32_bf16 v[118:121], v[166:169], v[182:185], v[118:121]
	v_mfma_f32_16x16x32_bf16 v[114:117], v[174:177], v[182:185], v[114:117]
	v_mfma_f32_16x16x32_bf16 v[102:105], v[166:169], v[190:193], v[102:105]
	v_mfma_f32_16x16x32_bf16 v[98:101], v[174:177], v[190:193], v[98:101]
	v_mfma_f32_16x16x32_bf16 v[86:89], v[166:169], v[198:201], v[86:89]
	v_mfma_f32_16x16x32_bf16 v[82:85], v[174:177], v[198:201], v[82:85]
	v_mfma_f32_16x16x32_bf16 v[70:73], v[166:169], v[210:213], v[70:73]
	v_mfma_f32_16x16x32_bf16 v[66:69], v[174:177], v[210:213], v[66:69]
	v_mfma_f32_16x16x32_bf16 v[118:121], v[170:173], v[186:189], v[118:121]
	v_mfma_f32_16x16x32_bf16 v[114:117], v[178:181], v[186:189], v[114:117]
	v_mfma_f32_16x16x32_bf16 v[102:105], v[170:173], v[194:197], v[102:105]
	v_mfma_f32_16x16x32_bf16 v[98:101], v[178:181], v[194:197], v[98:101]
	v_mfma_f32_16x16x32_bf16 v[86:89], v[170:173], v[202:205], v[86:89]
	v_mfma_f32_16x16x32_bf16 v[82:85], v[178:181], v[202:205], v[82:85]
	v_mfma_f32_16x16x32_bf16 v[70:73], v[170:173], v[214:217], v[70:73]
	v_mfma_f32_16x16x32_bf16 v[66:69], v[178:181], v[214:217], v[66:69]
	s_barrier
	s_and_b64 s[18:19], vcc, exec
	s_movk_i32 s7, 0xff00
	s_cselect_b32 s16, 0x4000, s7
	s_cselect_b32 s28, 0, -1
	s_add_i32 s7, s65, s24
	v_cndmask_b32_e32 v130, v132, v136, vcc
	s_and_b64 s[18:19], vcc, exec
	v_and_b32_e32 v130, -2, v130
	s_cselect_b32 s29, 0x2000, s64
	v_lshl_add_u64 v[138:139], s[96:97], 0, v[130:131]
	s_mov_b32 m0, s7
	s_add_u32 s18, s96, s29
	ds_read_b128 v[182:185], v148 offset:16384
	ds_read_b128 v[186:189], v148 offset:17408
	ds_read_b128 v[190:193], v148 offset:18432
	ds_read_b128 v[194:197], v148 offset:19456
	ds_read_b128 v[198:201], v148 offset:20480
	ds_read_b128 v[202:205], v148 offset:21504
	ds_read_b128 v[210:213], v148 offset:22528
	ds_read_b128 v[214:217], v148 offset:23552
	global_load_lds_dwordx4 v[138:139], off
	s_addc_u32 s19, s97, s28
	s_add_i32 m0, s7, 0x2000
	v_lshl_add_u64 v[138:139], s[18:19], 0, v[130:131]
	s_add_u32 s18, s96, s16
	s_addc_u32 s19, s97, s28
	s_add_i32 s7, s34, s24
	global_load_lds_dwordx4 v[138:139], off
	v_lshl_add_u64 v[138:139], s[18:19], 0, v[130:131]
	s_add_u32 s18, s18, s29
	s_mov_b32 m0, s7
	s_addc_u32 s19, s19, s28
	global_load_lds_dwordx4 v[138:139], off
	v_lshl_add_u64 v[138:139], s[18:19], 0, v[130:131]
	s_add_i32 m0, s7, 0x2000
	s_nop 0
	global_load_lds_dwordx4 v[138:139], off
	v_lshl_add_u64 v[138:139], s[68:69], 0, v[134:135]
	s_mov_b32 m0, s25
	v_lshl_add_u64 v[206:207], v[138:139], 0, s[22:23]
	global_load_lds_dwordx4 v[138:139], off
	s_mov_b32 m0, s10
	s_nop 0
	global_load_lds_dwordx4 v[206:207], off
	s_waitcnt vmcnt(8)
	s_waitcnt lgkmcnt(0)
	s_barrier
; #define G8_STA(bufoff, ptr, sg, h) G8_STAGE1(bufoff, (ptr) + (h) * ((sg) ? hA1 : hA0), ((sg) ? voffA1 : voffA0), ((sg) ? r64A1 : r64A0))
; #define G8_LDA(dst, b, h) do { _Pragma("unroll") for (int m = 0; m < 4; ++m) _Pragma("unroll") for (int k = 0; k < 2; ++k) dst[m][k] = *(const LAS bf16x8*)(lds + G8_SA(b, h) + aoff + m * 2048 + k * 1024); } while (0)
; #define G8_LDB(dst, b, h) do { _Pragma("unroll") for (int n = 0; n < 2; ++n) _Pragma("unroll") for (int k = 0; k < 2; ++k) dst[n][k] = *(const LAS bf16x8*)(lds + G8_SB(b, h) + boff + n * 2048 + k * 1024); } while (0)
; #define G8_MMA(ai, bj, At, Bt) do { __builtin_amdgcn_s_setprio(1); _Pragma("unroll") for (int m = 0; m < 4; ++m) _Pragma("unroll") for (int n = 0; n < 2; ++n) _Pragma("unroll") for (int k = 0; k < 2; ++k) \
;         acc[ai][bj][m][n] = __builtin_amdgcn_mfma_f32_16x16x32_bf16(Bt[n][k], At[m][k], acc[ai][bj][m][n], 0, 0, 0); __builtin_amdgcn_s_setprio(0); } while (0)
; #define G8_WAIT_V(n) asm volatile("s_waitcnt vmcnt(" #n ")" ::: "memory")
; #define G8_WAIT_L(n) asm volatile("s_waitcnt lgkmcnt(" #n ")" ::: "memory")
; #define G8_BAR __builtin_amdgcn_s_barrier()
; #define G8_SCHED __builtin_amdgcn_sched_barrier(0)
; template <class P>
; __device__ __forceinline__ void gemm_phase(LAS unsigned char* lds, const P& p, const int G, const int c) {
;     ...
;             G8_WAIT_V(8); G8_WAIT_L(0); G8_BAR; G8_MMA(1, 0, At, B0); G8_MMA(1, 1, At, B1); G8_BAR; G8_SCHED;
;             G8_LDB(B0, 1, 0); G8_LDB(B1, 1, 1); G8_SCHED; G8_LDA(At, 1, 0); G8_STA(G8_SA(0, 1), a2, sg2, 1);
;             G8_WAIT_V(8); G8_WAIT_L(0); G8_BAR; G8_MMA(0, 0, At, B0); G8_MMA(0, 1, At, B1); G8_BAR; G8_SCHED;
	s_waitcnt lgkmcnt(0)
	v_mfma_f32_16x16x32_bf16 v[62:65], v[150:153], v[182:185], v[62:65]
	v_mfma_f32_16x16x32_bf16 v[58:61], v[158:161], v[182:185], v[58:61]
	v_mfma_f32_16x16x32_bf16 v[46:49], v[150:153], v[190:193], v[46:49]
	v_mfma_f32_16x16x32_bf16 v[42:45], v[158:161], v[190:193], v[42:45]
	v_mfma_f32_16x16x32_bf16 v[30:33], v[150:153], v[198:201], v[30:33]
	v_mfma_f32_16x16x32_bf16 v[26:29], v[158:161], v[198:201], v[26:29]
	v_mfma_f32_16x16x32_bf16 v[14:17], v[150:153], v[210:213], v[14:17]
	v_mfma_f32_16x16x32_bf16 v[10:13], v[158:161], v[210:213], v[10:13]
	v_mfma_f32_16x16x32_bf16 v[62:65], v[154:157], v[186:189], v[62:65]
	v_mfma_f32_16x16x32_bf16 v[58:61], v[162:165], v[186:189], v[58:61]
	v_mfma_f32_16x16x32_bf16 v[46:49], v[154:157], v[194:197], v[46:49]
	v_mfma_f32_16x16x32_bf16 v[42:45], v[162:165], v[194:197], v[42:45]
	v_mfma_f32_16x16x32_bf16 v[30:33], v[154:157], v[202:205], v[30:33]
	v_mfma_f32_16x16x32_bf16 v[26:29], v[162:165], v[202:205], v[26:29]
	v_mfma_f32_16x16x32_bf16 v[14:17], v[154:157], v[214:217], v[14:17]
	v_mfma_f32_16x16x32_bf16 v[10:13], v[162:165], v[214:217], v[10:13]
	v_mfma_f32_16x16x32_bf16 v[54:57], v[166:169], v[182:185], v[54:57]
	v_mfma_f32_16x16x32_bf16 v[50:53], v[174:177], v[182:185], v[50:53]
	v_mfma_f32_16x16x32_bf16 v[38:41], v[166:169], v[190:193], v[38:41]
	v_mfma_f32_16x16x32_bf16 v[34:37], v[174:177], v[190:193], v[34:37]
	v_mfma_f32_16x16x32_bf16 v[22:25], v[166:169], v[198:201], v[22:25]
	v_mfma_f32_16x16x32_bf16 v[18:21], v[174:177], v[198:201], v[18:21]
	v_mfma_f32_16x16x32_bf16 v[6:9], v[166:169], v[210:213], v[6:9]
	v_mfma_f32_16x16x32_bf16 v[2:5], v[174:177], v[210:213], v[2:5]
	v_mfma_f32_16x16x32_bf16 v[54:57], v[170:173], v[186:189], v[54:57]
	v_mfma_f32_16x16x32_bf16 v[50:53], v[178:181], v[186:189], v[50:53]
	v_mfma_f32_16x16x32_bf16 v[38:41], v[170:173], v[194:197], v[38:41]
	v_mfma_f32_16x16x32_bf16 v[34:37], v[178:181], v[194:197], v[34:37]
	v_mfma_f32_16x16x32_bf16 v[22:25], v[170:173], v[202:205], v[22:25]
	v_mfma_f32_16x16x32_bf16 v[18:21], v[178:181], v[202:205], v[18:21]
	v_mfma_f32_16x16x32_bf16 v[6:9], v[170:173], v[214:217], v[6:9]
	v_mfma_f32_16x16x32_bf16 v[2:5], v[178:181], v[214:217], v[2:5]
	s_barrier
	v_add_u32_e32 v149, s35, v137
	ds_read_b128 v[150:153], v149
	ds_read_b128 v[154:157], v149 offset:1024
	ds_read_b128 v[158:161], v149 offset:2048
	ds_read_b128 v[162:165], v149 offset:3072
	v_add_u32_e32 v149, s20, v137
	ds_read_b128 v[166:169], v149
	ds_read_b128 v[170:173], v149 offset:1024
	ds_read_b128 v[174:177], v149 offset:2048
	ds_read_b128 v[178:181], v149 offset:3072
	s_mov_b32 m0, s11
	v_lshl_add_u64 v[206:207], v[138:139], 0, s[36:37]
	ds_read_b128 v[182:185], v148 offset:32768
	ds_read_b128 v[186:189], v148 offset:33792
	ds_read_b128 v[190:193], v148 offset:34816
	ds_read_b128 v[194:197], v148 offset:35840
	ds_read_b128 v[198:201], v148 offset:36864
	ds_read_b128 v[202:205], v148 offset:37888
	ds_read_b128 v[210:213], v148 offset:38912
	ds_read_b128 v[214:217], v148 offset:39936
	global_load_lds_dwordx4 v[206:207], off
	v_lshl_add_u64 v[206:207], v[138:139], 0, s[38:39]
	s_mov_b32 m0, s33
	s_nop 0
	global_load_lds_dwordx4 v[206:207], off
	s_waitcnt vmcnt(8)
	s_waitcnt lgkmcnt(0)
	s_barrier
	s_waitcnt lgkmcnt(0)
	v_mfma_f32_16x16x32_bf16 v[126:129], v[150:153], v[182:185], v[126:129]
	v_mfma_f32_16x16x32_bf16 v[122:125], v[158:161], v[182:185], v[122:125]
	v_mfma_f32_16x16x32_bf16 v[110:113], v[150:153], v[190:193], v[110:113]
	v_mfma_f32_16x16x32_bf16 v[106:109], v[158:161], v[190:193], v[106:109]
	v_mfma_f32_16x16x32_bf16 v[94:97], v[150:153], v[198:201], v[94:97]
	v_mfma_f32_16x16x32_bf16 v[90:93], v[158:161], v[198:201], v[90:93]
	v_mfma_f32_16x16x32_bf16 v[78:81], v[150:153], v[210:213], v[78:81]
	v_mfma_f32_16x16x32_bf16 v[74:77], v[158:161], v[210:213], v[74:77]
	v_mfma_f32_16x16x32_bf16 v[126:129], v[154:157], v[186:189], v[126:129]
	v_mfma_f32_16x16x32_bf16 v[122:125], v[162:165], v[186:189], v[122:125]
	v_mfma_f32_16x16x32_bf16 v[110:113], v[154:157], v[194:197], v[110:113]
	v_mfma_f32_16x16x32_bf16 v[106:109], v[162:165], v[194:197], v[106:109]
	v_mfma_f32_16x16x32_bf16 v[94:97], v[154:157], v[202:205], v[94:97]
	v_mfma_f32_16x16x32_bf16 v[90:93], v[162:165], v[202:205], v[90:93]
	v_mfma_f32_16x16x32_bf16 v[78:81], v[154:157], v[214:217], v[78:81]
	v_mfma_f32_16x16x32_bf16 v[74:77], v[162:165], v[214:217], v[74:77]
	v_mfma_f32_16x16x32_bf16 v[118:121], v[166:169], v[182:185], v[118:121]
	v_mfma_f32_16x16x32_bf16 v[114:117], v[174:177], v[182:185], v[114:117]
	v_mfma_f32_16x16x32_bf16 v[102:105], v[166:169], v[190:193], v[102:105]
	v_mfma_f32_16x16x32_bf16 v[98:101], v[174:177], v[190:193], v[98:101]
	v_mfma_f32_16x16x32_bf16 v[86:89], v[166:169], v[198:201], v[86:89]
	v_mfma_f32_16x16x32_bf16 v[82:85], v[174:177], v[198:201], v[82:85]
	v_mfma_f32_16x16x32_bf16 v[70:73], v[166:169], v[210:213], v[70:73]
	v_mfma_f32_16x16x32_bf16 v[66:69], v[174:177], v[210:213], v[66:69]
	v_mfma_f32_16x16x32_bf16 v[118:121], v[170:173], v[186:189], v[118:121]
	v_mfma_f32_16x16x32_bf16 v[114:117], v[178:181], v[186:189], v[114:117]
	v_mfma_f32_16x16x32_bf16 v[102:105], v[170:173], v[194:197], v[102:105]
	v_mfma_f32_16x16x32_bf16 v[98:101], v[178:181], v[194:197], v[98:101]
	v_mfma_f32_16x16x32_bf16 v[86:89], v[170:173], v[202:205], v[86:89]
	v_mfma_f32_16x16x32_bf16 v[82:85], v[178:181], v[202:205], v[82:85]
	v_mfma_f32_16x16x32_bf16 v[70:73], v[170:173], v[214:217], v[70:73]
	v_mfma_f32_16x16x32_bf16 v[66:69], v[178:181], v[214:217], v[66:69]
	s_barrier
; #define G8_STA(bufoff, ptr, sg, h) G8_STAGE1(bufoff, (ptr) + (h) * ((sg) ? hA1 : hA0), ((sg) ? voffA1 : voffA0), ((sg) ? r64A1 : r64A0))
; #define G8_STB(bufoff, ptr, sg, h) G8_STAGE1(bufoff, (ptr) + (h) * ((sg) ? hB1 : hB0), ((sg) ? voffB1 : voffB0), ((sg) ? r64B1 : r64B0))
; #define G8_LDA(dst, b, h) do { _Pragma("unroll") for (int m = 0; m < 4; ++m) _Pragma("unroll") for (int k = 0; k < 2; ++k) dst[m][k] = *(const LAS bf16x8*)(lds + G8_SA(b, h) + aoff + m * 2048 + k * 1024); } while (0)
; #define G8_WAIT_V(n) asm volatile("s_waitcnt vmcnt(" #n ")" ::: "memory")
; #define G8_WAIT_L(n) asm volatile("s_waitcnt lgkmcnt(" #n ")" ::: "memory")
; template <class P>
; __device__ __forceinline__ void gemm_phase(LAS unsigned char* lds, const P& p, const int G, const int c) {
;     ...
;         for (int t = 0; t < nt; t += 2) {
;             const bool last = (t == nt - 2);
;             const bool sg1 = (NS > 1) && (t + 1 >= nt0);
;             const bool sg2 = (NS > 1) && !last && (t + 2 >= nt0);
;             const char* a1 = sg1 ? cA1 + (long)(t + 1 - nt0) * ksA1 : cA0 + (long)(t + 1) * ksA0;
;             const char* a2 = last ? nA0 : (sg2 ? cA1 + (long)(t + 2 - nt0) * ksA1 : cA0 + (long)(t + 2) * ksA0);
;             const char* b2 = last ? nB0 : (sg2 ? cB1 + (long)(t + 2 - nt0) * ksB1 : cB0 + (long)(t + 2) * ksB0);
;             const char* a3 = a2 + (sg2 ? ksA1 : ksA0); const char* b3 = b2 + (sg2 ? ksB1 : ksB0);
;             G8_LDB(B0, 0, 0); G8_LDB(B1, 0, 1); G8_SCHED; G8_LDA(At, 0, 0); G8_STA(G8_SA(1, 1), a1, sg1, 1);
;             G8_WAIT_V(8); G8_WAIT_L(0); G8_BAR; G8_MMA(0, 0, At, B0); G8_MMA(0, 1, At, B1); G8_BAR; G8_SCHED;
;             G8_LDA(At, 0, 1); G8_STB(G8_SB(0, 0), b2, sg2, 0); G8_STB(G8_SB(0, 1), b2, sg2, 1); G8_STA(G8_SA(0, 0), a2, sg2, 0);
;             G8_WAIT_V(8); G8_WAIT_L(0); G8_BAR; G8_MMA(1, 0, At, B0); G8_MMA(1, 1, At, B1); G8_BAR; G8_SCHED;
;             G8_LDB(B0, 1, 0); G8_LDB(B1, 1, 1); G8_SCHED; G8_LDA(At, 1, 0); G8_STA(G8_SA(0, 1), a2, sg2, 1);
;             G8_WAIT_V(8); G8_WAIT_L(0); G8_BAR; G8_MMA(0, 0, At, B0); G8_MMA(0, 1, At, B1); G8_BAR; G8_SCHED;
;             G8_LDA(At, 1, 1); G8_STB(G8_SB(1, 0), b3, sg2, 0); G8_STB(G8_SB(1, 1), b3, sg2, 1); G8_STA(G8_SA(1, 0), a3, sg2, 0);
;             G8_WAIT_V(8); G8_WAIT_L(0); G8_BAR; G8_MMA(1, 0, At, B0); G8_MMA(1, 1, At, B1); G8_BAR; G8_SCHED;
	s_add_u32 s6, s96, s6
	s_addc_u32 s7, s97, 0
	s_add_i32 s57, s35, s24
	v_lshl_add_u64 v[206:207], s[6:7], 0, v[130:131]
	s_mov_b32 m0, s57
	s_add_u32 s18, s6, s29
	ds_read_b128 v[182:185], v148 offset:49152
	ds_read_b128 v[186:189], v148 offset:50176
	ds_read_b128 v[190:193], v148 offset:51200
	ds_read_b128 v[194:197], v148 offset:52224
	ds_read_b128 v[198:201], v148 offset:53248
	ds_read_b128 v[202:205], v148 offset:54272
	ds_read_b128 v[210:213], v148 offset:55296
	ds_read_b128 v[214:217], v148 offset:56320
	global_load_lds_dwordx4 v[206:207], off
	s_addc_u32 s19, s7, s28
	s_add_i32 m0, s57, 0x2000
	s_add_u32 s6, s6, s16
	v_lshl_add_u64 v[206:207], s[18:19], 0, v[130:131]
	s_addc_u32 s7, s7, s28
	s_add_i32 s16, s20, s24
	global_load_lds_dwordx4 v[206:207], off
	v_lshl_add_u64 v[206:207], s[6:7], 0, v[130:131]
	s_add_u32 s6, s6, s29
	s_mov_b32 m0, s16
	s_addc_u32 s7, s7, s28
	global_load_lds_dwordx4 v[206:207], off
	v_lshl_add_u64 v[206:207], s[6:7], 0, v[130:131]
	s_add_i32 m0, s16, 0x2000
	s_nop 0
	global_load_lds_dwordx4 v[206:207], off
	v_lshl_add_u64 v[206:207], v[138:139], 0, s[40:41]
	s_mov_b32 m0, s47
	v_lshl_add_u64 v[138:139], v[138:139], 0, s[42:43]
	global_load_lds_dwordx4 v[206:207], off
	s_mov_b32 m0, s50
	s_nop 0
	global_load_lds_dwordx4 v[138:139], off
	s_waitcnt vmcnt(8)
	s_waitcnt lgkmcnt(0)
	s_barrier
	s_waitcnt lgkmcnt(0)
	v_mfma_f32_16x16x32_bf16 v[62:65], v[150:153], v[182:185], v[62:65]
	v_mfma_f32_16x16x32_bf16 v[58:61], v[158:161], v[182:185], v[58:61]
	v_mfma_f32_16x16x32_bf16 v[46:49], v[150:153], v[190:193], v[46:49]
	v_mfma_f32_16x16x32_bf16 v[42:45], v[158:161], v[190:193], v[42:45]
	v_mfma_f32_16x16x32_bf16 v[30:33], v[150:153], v[198:201], v[30:33]
	v_mfma_f32_16x16x32_bf16 v[26:29], v[158:161], v[198:201], v[26:29]
	v_mfma_f32_16x16x32_bf16 v[14:17], v[150:153], v[210:213], v[14:17]
	v_mfma_f32_16x16x32_bf16 v[10:13], v[158:161], v[210:213], v[10:13]
	v_mfma_f32_16x16x32_bf16 v[62:65], v[154:157], v[186:189], v[62:65]
	v_mfma_f32_16x16x32_bf16 v[58:61], v[162:165], v[186:189], v[58:61]
	v_mfma_f32_16x16x32_bf16 v[46:49], v[154:157], v[194:197], v[46:49]
	v_mfma_f32_16x16x32_bf16 v[42:45], v[162:165], v[194:197], v[42:45]
	v_mfma_f32_16x16x32_bf16 v[30:33], v[154:157], v[202:205], v[30:33]
	v_mfma_f32_16x16x32_bf16 v[26:29], v[162:165], v[202:205], v[26:29]
	v_mfma_f32_16x16x32_bf16 v[14:17], v[154:157], v[214:217], v[14:17]
	v_mfma_f32_16x16x32_bf16 v[10:13], v[162:165], v[214:217], v[10:13]
	v_mfma_f32_16x16x32_bf16 v[54:57], v[166:169], v[182:185], v[54:57]
	v_mfma_f32_16x16x32_bf16 v[50:53], v[174:177], v[182:185], v[50:53]
	v_mfma_f32_16x16x32_bf16 v[38:41], v[166:169], v[190:193], v[38:41]
	v_mfma_f32_16x16x32_bf16 v[34:37], v[174:177], v[190:193], v[34:37]
	v_mfma_f32_16x16x32_bf16 v[22:25], v[166:169], v[198:201], v[22:25]
	v_mfma_f32_16x16x32_bf16 v[18:21], v[174:177], v[198:201], v[18:21]
	v_mfma_f32_16x16x32_bf16 v[6:9], v[166:169], v[210:213], v[6:9]
	v_mfma_f32_16x16x32_bf16 v[2:5], v[174:177], v[210:213], v[2:5]
	v_mfma_f32_16x16x32_bf16 v[54:57], v[170:173], v[186:189], v[54:57]
	v_mfma_f32_16x16x32_bf16 v[50:53], v[178:181], v[186:189], v[50:53]
	v_mfma_f32_16x16x32_bf16 v[38:41], v[170:173], v[194:197], v[38:41]
	v_mfma_f32_16x16x32_bf16 v[34:37], v[178:181], v[194:197], v[34:37]
	v_mfma_f32_16x16x32_bf16 v[22:25], v[170:173], v[202:205], v[22:25]
	v_mfma_f32_16x16x32_bf16 v[18:21], v[178:181], v[202:205], v[18:21]
	v_mfma_f32_16x16x32_bf16 v[6:9], v[170:173], v[214:217], v[6:9]
	v_mfma_f32_16x16x32_bf16 v[2:5], v[178:181], v[214:217], v[2:5]
	s_barrier
	s_add_i32 s79, s79, 1
	s_add_u32 s90, s90, 0x20000
	s_addc_u32 s91, s91, 0
	s_add_u32 s92, s92, 0x40000
	s_addc_u32 s93, s93, 0
	s_add_u32 s94, s94, 0x40000
	s_addc_u32 s95, s95, 0
	s_cmp_gt_u32 s56, 9
	s_mov_b32 s18, s56
	s_cbranch_scc1 .LBB0_604

; #define G8_STA(bufoff, ptr, sg, h) G8_STAGE1(bufoff, (ptr) + (h) * ((sg) ? hA1 : hA0), ((sg) ? voffA1 : voffA0), ((sg) ? r64A1 : r64A0))
; #define G8_STB(bufoff, ptr, sg, h) G8_STAGE1(bufoff, (ptr) + (h) * ((sg) ? hB1 : hB0), ((sg) ? voffB1 : voffB0), ((sg) ? r64B1 : r64B0))
; #define G8_LDA(dst, b, h) do { _Pragma("unroll") for (int m = 0; m < 4; ++m) _Pragma("unroll") for (int k = 0; k < 2; ++k) dst[m][k] = *(const LAS bf16x8*)(lds + G8_SA(b, h) + aoff + m * 2048 + k * 1024); } while (0)
; #define G8_LDB(dst, b, h) do { _Pragma("unroll") for (int n = 0; n < 2; ++n) _Pragma("unroll") for (int k = 0; k < 2; ++k) dst[n][k] = *(const LAS bf16x8*)(lds + G8_SB(b, h) + boff + n * 2048 + k * 1024); } while (0)
; #define G8_MMA(ai, bj, At, Bt) do { __builtin_amdgcn_s_setprio(1); _Pragma("unroll") for (int m = 0; m < 4; ++m) _Pragma("unroll") for (int n = 0; n < 2; ++n) _Pragma("unroll") for (int k = 0; k < 2; ++k) \
;         acc[ai][bj][m][n] = __builtin_amdgcn_mfma_f32_16x16x32_bf16(Bt[n][k], At[m][k], acc[ai][bj][m][n], 0, 0, 0); __builtin_amdgcn_s_setprio(0); } while (0)
; #define G8_WAIT_V(n) asm volatile("s_waitcnt vmcnt(" #n ")" ::: "memory")
; #define G8_WAIT_L(n) asm volatile("s_waitcnt lgkmcnt(" #n ")" ::: "memory")
; #define G8_BAR __builtin_amdgcn_s_barrier()
; #define G8_SCHED __builtin_amdgcn_sched_barrier(0)
; template <class P>
; __device__ __forceinline__ void gemm_phase(LAS unsigned char* lds, const P& p, const int G, const int c) {
;     ...
;             G8_LDB(B0, 0, 0); G8_LDB(B1, 0, 1); G8_SCHED; G8_LDA(At, 0, 0); G8_STA(G8_SA(1, 1), a1, sg1, 1);
;             G8_WAIT_V(8); G8_WAIT_L(0); G8_BAR; G8_MMA(0, 0, At, B0); G8_MMA(0, 1, At, B1); G8_BAR; G8_SCHED;
;             G8_LDA(At, 0, 1); G8_STB(G8_SB(0, 0), b2, sg2, 0); G8_STB(G8_SB(0, 1), b2, sg2, 1); G8_STA(G8_SA(0, 0), a2, sg2, 0);
;             G8_WAIT_V(8); G8_WAIT_L(0); G8_BAR; G8_MMA(1, 0, At, B0); G8_MMA(1, 1, At, B1); G8_BAR; G8_SCHED;
.LBB0_679:
	v_add_u32_e32 v153, s50, v1
	ds_read_b128 v[170:173], v153
	ds_read_b128 v[174:177], v153 offset:1024
	ds_read_b128 v[178:181], v153 offset:2048
	ds_read_b128 v[182:185], v153 offset:3072
	v_add_u32_e32 v153, s51, v1
	ds_read_b128 v[186:189], v153
	ds_read_b128 v[190:193], v153 offset:1024
	ds_read_b128 v[194:197], v153 offset:2048
	ds_read_b128 v[198:201], v153 offset:3072
	s_and_b64 s[30:31], exec, s[30:31]
	s_cselect_b32 s31, s18, s59
	s_cselect_b32 s30, s19, s53
	v_lshl_add_u64 v[206:207], v[168:169], 0, s[62:63]
	v_lshl_add_u64 v[238:239], v[206:207], 0, s[40:41]
	s_add_i32 m0, s27, 0xc000
	ds_read_b128 v[202:205], v151
	ds_read_b128 v[210:213], v151 offset:1024
	ds_read_b128 v[214:217], v151 offset:2048
	ds_read_b128 v[218:221], v151 offset:3072
	ds_read_b128 v[222:225], v151 offset:4096
	ds_read_b128 v[226:229], v151 offset:5120
	ds_read_b128 v[230:233], v151 offset:6144
	ds_read_b128 v[234:237], v151 offset:7168
	global_load_lds_dwordx4 v[238:239], off
	v_lshl_add_u64 v[206:207], v[206:207], 0, s[42:43]
	s_add_i32 m0, s27, 0xe000
	s_nop 0
	global_load_lds_dwordx4 v[206:207], off
	s_waitcnt vmcnt(8)
	s_waitcnt lgkmcnt(0)
	s_barrier
	s_waitcnt lgkmcnt(0)
	v_mfma_f32_16x16x32_bf16 v[126:129], v[170:173], v[202:205], v[126:129]
	v_mfma_f32_16x16x32_bf16 v[122:125], v[178:181], v[202:205], v[122:125]
	v_mfma_f32_16x16x32_bf16 v[110:113], v[170:173], v[214:217], v[110:113]
	v_mfma_f32_16x16x32_bf16 v[106:109], v[178:181], v[214:217], v[106:109]
	v_mfma_f32_16x16x32_bf16 v[94:97], v[170:173], v[222:225], v[94:97]
	v_mfma_f32_16x16x32_bf16 v[90:93], v[178:181], v[222:225], v[90:93]
	v_mfma_f32_16x16x32_bf16 v[78:81], v[170:173], v[230:233], v[78:81]
	v_mfma_f32_16x16x32_bf16 v[74:77], v[178:181], v[230:233], v[74:77]
	v_mfma_f32_16x16x32_bf16 v[126:129], v[174:177], v[210:213], v[126:129]
	v_mfma_f32_16x16x32_bf16 v[122:125], v[182:185], v[210:213], v[122:125]
	v_mfma_f32_16x16x32_bf16 v[110:113], v[174:177], v[218:221], v[110:113]
	v_mfma_f32_16x16x32_bf16 v[106:109], v[182:185], v[218:221], v[106:109]
	v_mfma_f32_16x16x32_bf16 v[94:97], v[174:177], v[226:229], v[94:97]
	v_mfma_f32_16x16x32_bf16 v[90:93], v[182:185], v[226:229], v[90:93]
	v_mfma_f32_16x16x32_bf16 v[78:81], v[174:177], v[234:237], v[78:81]
	v_mfma_f32_16x16x32_bf16 v[74:77], v[182:185], v[234:237], v[74:77]
	v_mfma_f32_16x16x32_bf16 v[118:121], v[186:189], v[202:205], v[118:121]
	v_mfma_f32_16x16x32_bf16 v[114:117], v[194:197], v[202:205], v[114:117]
	v_mfma_f32_16x16x32_bf16 v[102:105], v[186:189], v[214:217], v[102:105]
	v_mfma_f32_16x16x32_bf16 v[98:101], v[194:197], v[214:217], v[98:101]
	v_mfma_f32_16x16x32_bf16 v[86:89], v[186:189], v[222:225], v[86:89]
	v_mfma_f32_16x16x32_bf16 v[82:85], v[194:197], v[222:225], v[82:85]
	v_mfma_f32_16x16x32_bf16 v[70:73], v[186:189], v[230:233], v[70:73]
	v_mfma_f32_16x16x32_bf16 v[66:69], v[194:197], v[230:233], v[66:69]
	v_mfma_f32_16x16x32_bf16 v[118:121], v[190:193], v[210:213], v[118:121]
	v_mfma_f32_16x16x32_bf16 v[114:117], v[198:201], v[210:213], v[114:117]
	v_mfma_f32_16x16x32_bf16 v[102:105], v[190:193], v[218:221], v[102:105]
	v_mfma_f32_16x16x32_bf16 v[98:101], v[198:201], v[218:221], v[98:101]
	v_mfma_f32_16x16x32_bf16 v[86:89], v[190:193], v[226:229], v[86:89]
	v_mfma_f32_16x16x32_bf16 v[82:85], v[198:201], v[226:229], v[82:85]
	v_mfma_f32_16x16x32_bf16 v[70:73], v[190:193], v[234:237], v[70:73]
	v_mfma_f32_16x16x32_bf16 v[66:69], v[198:201], v[234:237], v[66:69]
	s_barrier
	v_lshl_add_u64 v[206:207], s[30:31], 0, v[130:131]
	s_add_i32 s30, s50, s26
	s_mov_b32 m0, s30
	ds_read_b128 v[202:205], v151 offset:16384
	ds_read_b128 v[210:213], v151 offset:17408
	ds_read_b128 v[214:217], v151 offset:18432
	ds_read_b128 v[218:221], v151 offset:19456
	ds_read_b128 v[222:225], v151 offset:20480
	ds_read_b128 v[226:229], v151 offset:21504
	ds_read_b128 v[230:233], v151 offset:22528
	ds_read_b128 v[234:237], v151 offset:23552
	global_load_lds_dwordx4 v[206:207], off
	v_lshl_add_u64 v[238:239], v[206:207], 0, s[0:1]
	s_add_i32 m0, s30, 0x2000
	s_add_i32 s30, s51, s26
	global_load_lds_dwordx4 v[238:239], off
	v_lshl_add_u64 v[238:239], v[206:207], 0, s[4:5]
	s_mov_b32 m0, s30
	s_nop 0
	global_load_lds_dwordx4 v[238:239], off
	v_lshl_add_u64 v[238:239], v[206:207], 0, s[6:7]
	s_add_i32 m0, s30, 0x2000
	s_nop 0
	global_load_lds_dwordx4 v[238:239], off
	v_lshl_add_u64 v[238:239], s[28:29], 0, v[132:133]
	s_mov_b32 m0, s27
	v_lshl_add_u64 v[240:241], v[238:239], 0, s[0:1]
	global_load_lds_dwordx4 v[238:239], off
	s_mov_b32 m0, s33
	s_nop 0
	global_load_lds_dwordx4 v[240:241], off
	s_waitcnt vmcnt(8)
	s_waitcnt lgkmcnt(0)
	s_barrier
; #define G8_STA(bufoff, ptr, sg, h) G8_STAGE1(bufoff, (ptr) + (h) * ((sg) ? hA1 : hA0), ((sg) ? voffA1 : voffA0), ((sg) ? r64A1 : r64A0))
; #define G8_LDA(dst, b, h) do { _Pragma("unroll") for (int m = 0; m < 4; ++m) _Pragma("unroll") for (int k = 0; k < 2; ++k) dst[m][k] = *(const LAS bf16x8*)(lds + G8_SA(b, h) + aoff + m * 2048 + k * 1024); } while (0)
; #define G8_LDB(dst, b, h) do { _Pragma("unroll") for (int n = 0; n < 2; ++n) _Pragma("unroll") for (int k = 0; k < 2; ++k) dst[n][k] = *(const LAS bf16x8*)(lds + G8_SB(b, h) + boff + n * 2048 + k * 1024); } while (0)
; #define G8_MMA(ai, bj, At, Bt) do { __builtin_amdgcn_s_setprio(1); _Pragma("unroll") for (int m = 0; m < 4; ++m) _Pragma("unroll") for (int n = 0; n < 2; ++n) _Pragma("unroll") for (int k = 0; k < 2; ++k) \
;         acc[ai][bj][m][n] = __builtin_amdgcn_mfma_f32_16x16x32_bf16(Bt[n][k], At[m][k], acc[ai][bj][m][n], 0, 0, 0); __builtin_amdgcn_s_setprio(0); } while (0)
; #define G8_WAIT_V(n) asm volatile("s_waitcnt vmcnt(" #n ")" ::: "memory")
; #define G8_WAIT_L(n) asm volatile("s_waitcnt lgkmcnt(" #n ")" ::: "memory")
; #define G8_BAR __builtin_amdgcn_s_barrier()
; #define G8_SCHED __builtin_amdgcn_sched_barrier(0)
; template <class P>
; __device__ __forceinline__ void gemm_phase(LAS unsigned char* lds, const P& p, const int G, const int c) {
;     ...
;             G8_WAIT_V(8); G8_WAIT_L(0); G8_BAR; G8_MMA(1, 0, At, B0); G8_MMA(1, 1, At, B1); G8_BAR; G8_SCHED;
;             G8_LDB(B0, 1, 0); G8_LDB(B1, 1, 1); G8_SCHED; G8_LDA(At, 1, 0); G8_STA(G8_SA(0, 1), a2, sg2, 1);
;             G8_WAIT_V(8); G8_WAIT_L(0); G8_BAR; G8_MMA(0, 0, At, B0); G8_MMA(0, 1, At, B1); G8_BAR; G8_SCHED;
	s_waitcnt lgkmcnt(0)
	v_mfma_f32_16x16x32_bf16 v[62:65], v[170:173], v[202:205], v[62:65]
	v_mfma_f32_16x16x32_bf16 v[58:61], v[178:181], v[202:205], v[58:61]
	v_mfma_f32_16x16x32_bf16 v[46:49], v[170:173], v[214:217], v[46:49]
	v_mfma_f32_16x16x32_bf16 v[42:45], v[178:181], v[214:217], v[42:45]
	v_mfma_f32_16x16x32_bf16 v[30:33], v[170:173], v[222:225], v[30:33]
	v_mfma_f32_16x16x32_bf16 v[26:29], v[178:181], v[222:225], v[26:29]
	v_mfma_f32_16x16x32_bf16 v[14:17], v[170:173], v[230:233], v[14:17]
	v_mfma_f32_16x16x32_bf16 v[10:13], v[178:181], v[230:233], v[10:13]
	v_mfma_f32_16x16x32_bf16 v[62:65], v[174:177], v[210:213], v[62:65]
	v_mfma_f32_16x16x32_bf16 v[58:61], v[182:185], v[210:213], v[58:61]
	v_mfma_f32_16x16x32_bf16 v[46:49], v[174:177], v[218:221], v[46:49]
	v_mfma_f32_16x16x32_bf16 v[42:45], v[182:185], v[218:221], v[42:45]
	v_mfma_f32_16x16x32_bf16 v[30:33], v[174:177], v[226:229], v[30:33]
	v_mfma_f32_16x16x32_bf16 v[26:29], v[182:185], v[226:229], v[26:29]
	v_mfma_f32_16x16x32_bf16 v[14:17], v[174:177], v[234:237], v[14:17]
	v_mfma_f32_16x16x32_bf16 v[10:13], v[182:185], v[234:237], v[10:13]
	v_mfma_f32_16x16x32_bf16 v[54:57], v[186:189], v[202:205], v[54:57]
	v_mfma_f32_16x16x32_bf16 v[50:53], v[194:197], v[202:205], v[50:53]
	v_mfma_f32_16x16x32_bf16 v[38:41], v[186:189], v[214:217], v[38:41]
	v_mfma_f32_16x16x32_bf16 v[34:37], v[194:197], v[214:217], v[34:37]
	v_mfma_f32_16x16x32_bf16 v[22:25], v[186:189], v[222:225], v[22:25]
	v_mfma_f32_16x16x32_bf16 v[18:21], v[194:197], v[222:225], v[18:21]
	v_mfma_f32_16x16x32_bf16 v[6:9], v[186:189], v[230:233], v[6:9]
	v_mfma_f32_16x16x32_bf16 v[2:5], v[194:197], v[230:233], v[2:5]
	v_mfma_f32_16x16x32_bf16 v[54:57], v[190:193], v[210:213], v[54:57]
	v_mfma_f32_16x16x32_bf16 v[50:53], v[198:201], v[210:213], v[50:53]
	v_mfma_f32_16x16x32_bf16 v[38:41], v[190:193], v[218:221], v[38:41]
	v_mfma_f32_16x16x32_bf16 v[34:37], v[198:201], v[218:221], v[34:37]
	v_mfma_f32_16x16x32_bf16 v[22:25], v[190:193], v[226:229], v[22:25]
	v_mfma_f32_16x16x32_bf16 v[18:21], v[198:201], v[226:229], v[18:21]
	v_mfma_f32_16x16x32_bf16 v[6:9], v[190:193], v[234:237], v[6:9]
	v_mfma_f32_16x16x32_bf16 v[2:5], v[198:201], v[234:237], v[2:5]
	s_barrier
	s_add_i32 s28, 0, 0x18000
	v_add_u32_e32 v153, s28, v1
	s_add_i32 s29, 0, 0x1c000
	ds_read_b128 v[170:173], v153
	ds_read_b128 v[174:177], v153 offset:1024
	ds_read_b128 v[178:181], v153 offset:2048
	ds_read_b128 v[182:185], v153 offset:3072
	v_add_u32_e32 v153, s29, v1
	ds_read_b128 v[186:189], v153
	ds_read_b128 v[190:193], v153 offset:1024
	ds_read_b128 v[194:197], v153 offset:2048
	ds_read_b128 v[198:201], v153 offset:3072
	s_mov_b32 m0, s34
	v_lshl_add_u64 v[240:241], v[238:239], 0, s[4:5]
	ds_read_b128 v[202:205], v151 offset:32768
	ds_read_b128 v[210:213], v151 offset:33792
	ds_read_b128 v[214:217], v151 offset:34816
	ds_read_b128 v[218:221], v151 offset:35840
	ds_read_b128 v[222:225], v151 offset:36864
	ds_read_b128 v[226:229], v151 offset:37888
	ds_read_b128 v[230:233], v151 offset:38912
	ds_read_b128 v[234:237], v151 offset:39936
	global_load_lds_dwordx4 v[240:241], off
	v_lshl_add_u64 v[240:241], v[238:239], 0, s[6:7]
	s_mov_b32 m0, s35
	s_nop 0
	global_load_lds_dwordx4 v[240:241], off
	s_waitcnt vmcnt(8)
	s_waitcnt lgkmcnt(0)
	s_barrier
	s_waitcnt lgkmcnt(0)
	v_mfma_f32_16x16x32_bf16 v[126:129], v[170:173], v[202:205], v[126:129]
	v_mfma_f32_16x16x32_bf16 v[122:125], v[178:181], v[202:205], v[122:125]
	v_mfma_f32_16x16x32_bf16 v[110:113], v[170:173], v[214:217], v[110:113]
	v_mfma_f32_16x16x32_bf16 v[106:109], v[178:181], v[214:217], v[106:109]
	v_mfma_f32_16x16x32_bf16 v[94:97], v[170:173], v[222:225], v[94:97]
	v_mfma_f32_16x16x32_bf16 v[90:93], v[178:181], v[222:225], v[90:93]
	v_mfma_f32_16x16x32_bf16 v[78:81], v[170:173], v[230:233], v[78:81]
	v_mfma_f32_16x16x32_bf16 v[74:77], v[178:181], v[230:233], v[74:77]
	v_mfma_f32_16x16x32_bf16 v[126:129], v[174:177], v[210:213], v[126:129]
	v_mfma_f32_16x16x32_bf16 v[122:125], v[182:185], v[210:213], v[122:125]
	v_mfma_f32_16x16x32_bf16 v[110:113], v[174:177], v[218:221], v[110:113]
	v_mfma_f32_16x16x32_bf16 v[106:109], v[182:185], v[218:221], v[106:109]
	v_mfma_f32_16x16x32_bf16 v[94:97], v[174:177], v[226:229], v[94:97]
	v_mfma_f32_16x16x32_bf16 v[90:93], v[182:185], v[226:229], v[90:93]
	v_mfma_f32_16x16x32_bf16 v[78:81], v[174:177], v[234:237], v[78:81]
	v_mfma_f32_16x16x32_bf16 v[74:77], v[182:185], v[234:237], v[74:77]
	v_mfma_f32_16x16x32_bf16 v[118:121], v[186:189], v[202:205], v[118:121]
	v_mfma_f32_16x16x32_bf16 v[114:117], v[194:197], v[202:205], v[114:117]
	v_mfma_f32_16x16x32_bf16 v[102:105], v[186:189], v[214:217], v[102:105]
	v_mfma_f32_16x16x32_bf16 v[98:101], v[194:197], v[214:217], v[98:101]
	v_mfma_f32_16x16x32_bf16 v[86:89], v[186:189], v[222:225], v[86:89]
	v_mfma_f32_16x16x32_bf16 v[82:85], v[194:197], v[222:225], v[82:85]
	v_mfma_f32_16x16x32_bf16 v[70:73], v[186:189], v[230:233], v[70:73]
	v_mfma_f32_16x16x32_bf16 v[66:69], v[194:197], v[230:233], v[66:69]
	v_mfma_f32_16x16x32_bf16 v[118:121], v[190:193], v[210:213], v[118:121]
	v_mfma_f32_16x16x32_bf16 v[114:117], v[198:201], v[210:213], v[114:117]
	v_mfma_f32_16x16x32_bf16 v[102:105], v[190:193], v[218:221], v[102:105]
	v_mfma_f32_16x16x32_bf16 v[98:101], v[198:201], v[218:221], v[98:101]
	v_mfma_f32_16x16x32_bf16 v[86:89], v[190:193], v[226:229], v[86:89]
	v_mfma_f32_16x16x32_bf16 v[82:85], v[198:201], v[226:229], v[82:85]
	v_mfma_f32_16x16x32_bf16 v[70:73], v[190:193], v[234:237], v[70:73]
	v_mfma_f32_16x16x32_bf16 v[66:69], v[198:201], v[234:237], v[66:69]
	s_barrier
; #define G8_STA(bufoff, ptr, sg, h) G8_STAGE1(bufoff, (ptr) + (h) * ((sg) ? hA1 : hA0), ((sg) ? voffA1 : voffA0), ((sg) ? r64A1 : r64A0))
; #define G8_STB(bufoff, ptr, sg, h) G8_STAGE1(bufoff, (ptr) + (h) * ((sg) ? hB1 : hB0), ((sg) ? voffB1 : voffB0), ((sg) ? r64B1 : r64B0))
; #define G8_LDA(dst, b, h) do { _Pragma("unroll") for (int m = 0; m < 4; ++m) _Pragma("unroll") for (int k = 0; k < 2; ++k) dst[m][k] = *(const LAS bf16x8*)(lds + G8_SA(b, h) + aoff + m * 2048 + k * 1024); } while (0)
; #define G8_WAIT_V(n) asm volatile("s_waitcnt vmcnt(" #n ")" ::: "memory")
; #define G8_WAIT_L(n) asm volatile("s_waitcnt lgkmcnt(" #n ")" ::: "memory")
; template <class P>
; __device__ __forceinline__ void gemm_phase(LAS unsigned char* lds, const P& p, const int G, const int c) {
;     ...
;         for (int t = 0; t < nt; t += 2) {
;             const bool last = (t == nt - 2);
;             const bool sg1 = (NS > 1) && (t + 1 >= nt0);
;             const bool sg2 = (NS > 1) && !last && (t + 2 >= nt0);
;             const char* a1 = sg1 ? cA1 + (long)(t + 1 - nt0) * ksA1 : cA0 + (long)(t + 1) * ksA0;
;             const char* a2 = last ? nA0 : (sg2 ? cA1 + (long)(t + 2 - nt0) * ksA1 : cA0 + (long)(t + 2) * ksA0);
;             const char* b2 = last ? nB0 : (sg2 ? cB1 + (long)(t + 2 - nt0) * ksB1 : cB0 + (long)(t + 2) * ksB0);
;             const char* a3 = a2 + (sg2 ? ksA1 : ksA0); const char* b3 = b2 + (sg2 ? ksB1 : ksB0);
;             G8_LDB(B0, 0, 0); G8_LDB(B1, 0, 1); G8_SCHED; G8_LDA(At, 0, 0); G8_STA(G8_SA(1, 1), a1, sg1, 1);
;             G8_WAIT_V(8); G8_WAIT_L(0); G8_BAR; G8_MMA(0, 0, At, B0); G8_MMA(0, 1, At, B1); G8_BAR; G8_SCHED;
;             G8_LDA(At, 0, 1); G8_STB(G8_SB(0, 0), b2, sg2, 0); G8_STB(G8_SB(0, 1), b2, sg2, 1); G8_STA(G8_SA(0, 0), a2, sg2, 0);
;             G8_WAIT_V(8); G8_WAIT_L(0); G8_BAR; G8_MMA(1, 0, At, B0); G8_MMA(1, 1, At, B1); G8_BAR; G8_SCHED;
;             G8_LDB(B0, 1, 0); G8_LDB(B1, 1, 1); G8_SCHED; G8_LDA(At, 1, 0); G8_STA(G8_SA(0, 1), a2, sg2, 1);
;             G8_WAIT_V(8); G8_WAIT_L(0); G8_BAR; G8_MMA(0, 0, At, B0); G8_MMA(0, 1, At, B1); G8_BAR; G8_SCHED;
;             G8_LDA(At, 1, 1); G8_STB(G8_SB(1, 0), b3, sg2, 0); G8_STB(G8_SB(1, 1), b3, sg2, 1); G8_STA(G8_SA(1, 0), a3, sg2, 0);
;             G8_WAIT_V(8); G8_WAIT_L(0); G8_BAR; G8_MMA(1, 0, At, B0); G8_MMA(1, 1, At, B1); G8_BAR; G8_SCHED;
;         }
	s_add_i32 s28, s28, s26
	v_lshl_add_u64 v[240:241], v[206:207], 0, s[12:13]
	s_mov_b32 m0, s28
	ds_read_b128 v[202:205], v151 offset:49152
	ds_read_b128 v[210:213], v151 offset:50176
	ds_read_b128 v[214:217], v151 offset:51200
	ds_read_b128 v[218:221], v151 offset:52224
	ds_read_b128 v[222:225], v151 offset:53248
	ds_read_b128 v[226:229], v151 offset:54272
	ds_read_b128 v[230:233], v151 offset:55296
	ds_read_b128 v[234:237], v151 offset:56320
	global_load_lds_dwordx4 v[240:241], off
	v_lshl_add_u64 v[240:241], v[206:207], 0, s[14:15]
	s_add_i32 m0, s28, 0x2000
	s_add_i32 s28, s29, s26
	global_load_lds_dwordx4 v[240:241], off
	v_lshl_add_u64 v[240:241], v[206:207], 0, s[22:23]
	s_mov_b32 m0, s28
	v_lshl_add_u64 v[206:207], v[206:207], 0, s[36:37]
	global_load_lds_dwordx4 v[240:241], off
	s_add_i32 m0, s28, 0x2000
	s_nop 0
	global_load_lds_dwordx4 v[206:207], off
	v_lshl_add_u64 v[206:207], v[238:239], 0, s[16:17]
	s_mov_b32 m0, s46
	s_nop 0
	global_load_lds_dwordx4 v[206:207], off
	v_lshl_add_u64 v[206:207], v[238:239], 0, s[20:21]
	s_mov_b32 m0, s47
	s_nop 0
	global_load_lds_dwordx4 v[206:207], off
	s_waitcnt vmcnt(8)
	s_waitcnt lgkmcnt(0)
	s_barrier
	s_waitcnt lgkmcnt(0)
	v_mfma_f32_16x16x32_bf16 v[62:65], v[170:173], v[202:205], v[62:65]
	v_mfma_f32_16x16x32_bf16 v[58:61], v[178:181], v[202:205], v[58:61]
	v_mfma_f32_16x16x32_bf16 v[46:49], v[170:173], v[214:217], v[46:49]
	v_mfma_f32_16x16x32_bf16 v[42:45], v[178:181], v[214:217], v[42:45]
	v_mfma_f32_16x16x32_bf16 v[30:33], v[170:173], v[222:225], v[30:33]
	v_mfma_f32_16x16x32_bf16 v[26:29], v[178:181], v[222:225], v[26:29]
	v_mfma_f32_16x16x32_bf16 v[14:17], v[170:173], v[230:233], v[14:17]
	v_mfma_f32_16x16x32_bf16 v[10:13], v[178:181], v[230:233], v[10:13]
	v_mfma_f32_16x16x32_bf16 v[62:65], v[174:177], v[210:213], v[62:65]
	v_mfma_f32_16x16x32_bf16 v[58:61], v[182:185], v[210:213], v[58:61]
	v_mfma_f32_16x16x32_bf16 v[46:49], v[174:177], v[218:221], v[46:49]
	v_mfma_f32_16x16x32_bf16 v[42:45], v[182:185], v[218:221], v[42:45]
	v_mfma_f32_16x16x32_bf16 v[30:33], v[174:177], v[226:229], v[30:33]
	v_mfma_f32_16x16x32_bf16 v[26:29], v[182:185], v[226:229], v[26:29]
	v_mfma_f32_16x16x32_bf16 v[14:17], v[174:177], v[234:237], v[14:17]
	v_mfma_f32_16x16x32_bf16 v[10:13], v[182:185], v[234:237], v[10:13]
	v_mfma_f32_16x16x32_bf16 v[54:57], v[186:189], v[202:205], v[54:57]
	v_mfma_f32_16x16x32_bf16 v[50:53], v[194:197], v[202:205], v[50:53]
	v_mfma_f32_16x16x32_bf16 v[38:41], v[186:189], v[214:217], v[38:41]
	v_mfma_f32_16x16x32_bf16 v[34:37], v[194:197], v[214:217], v[34:37]
	v_mfma_f32_16x16x32_bf16 v[22:25], v[186:189], v[222:225], v[22:25]
	v_mfma_f32_16x16x32_bf16 v[18:21], v[194:197], v[222:225], v[18:21]
	v_mfma_f32_16x16x32_bf16 v[6:9], v[186:189], v[230:233], v[6:9]
	v_mfma_f32_16x16x32_bf16 v[2:5], v[194:197], v[230:233], v[2:5]
	v_mfma_f32_16x16x32_bf16 v[54:57], v[190:193], v[210:213], v[54:57]
	v_mfma_f32_16x16x32_bf16 v[50:53], v[198:201], v[210:213], v[50:53]
	v_mfma_f32_16x16x32_bf16 v[38:41], v[190:193], v[218:221], v[38:41]
	v_mfma_f32_16x16x32_bf16 v[34:37], v[198:201], v[218:221], v[34:37]
	v_mfma_f32_16x16x32_bf16 v[22:25], v[190:193], v[226:229], v[22:25]
	v_mfma_f32_16x16x32_bf16 v[18:21], v[198:201], v[226:229], v[18:21]
	v_mfma_f32_16x16x32_bf16 v[6:9], v[190:193], v[234:237], v[6:9]
	v_mfma_f32_16x16x32_bf16 v[2:5], v[198:201], v[234:237], v[2:5]
	s_barrier
	s_add_i32 s66, s66, 2
	s_add_u32 s53, s53, 0x100000
	s_addc_u32 s59, s59, 0
	s_add_u32 s62, s62, 0x820000
	s_addc_u32 s63, s63, 0
	s_cmp_gt_u32 s66, 13
	s_cbranch_scc1 .LBB0_682

; #define G8_STA(bufoff, ptr, sg, h) G8_STAGE1(bufoff, (ptr) + (h) * ((sg) ? hA1 : hA0), ((sg) ? voffA1 : voffA0), ((sg) ? r64A1 : r64A0))
; #define G8_STB(bufoff, ptr, sg, h) G8_STAGE1(bufoff, (ptr) + (h) * ((sg) ? hB1 : hB0), ((sg) ? voffB1 : voffB0), ((sg) ? r64B1 : r64B0))
; #define G8_LDA(dst, b, h) do { _Pragma("unroll") for (int m = 0; m < 4; ++m) _Pragma("unroll") for (int k = 0; k < 2; ++k) dst[m][k] = *(const LAS bf16x8*)(lds + G8_SA(b, h) + aoff + m * 2048 + k * 1024); } while (0)
; #define G8_LDB(dst, b, h) do { _Pragma("unroll") for (int n = 0; n < 2; ++n) _Pragma("unroll") for (int k = 0; k < 2; ++k) dst[n][k] = *(const LAS bf16x8*)(lds + G8_SB(b, h) + boff + n * 2048 + k * 1024); } while (0)
; #define G8_MMA(ai, bj, At, Bt) do { __builtin_amdgcn_s_setprio(1); _Pragma("unroll") for (int m = 0; m < 4; ++m) _Pragma("unroll") for (int n = 0; n < 2; ++n) _Pragma("unroll") for (int k = 0; k < 2; ++k) \
;         acc[ai][bj][m][n] = __builtin_amdgcn_mfma_f32_16x16x32_bf16(Bt[n][k], At[m][k], acc[ai][bj][m][n], 0, 0, 0); __builtin_amdgcn_s_setprio(0); } while (0)
; #define G8_WAIT_V(n) asm volatile("s_waitcnt vmcnt(" #n ")" ::: "memory")
; #define G8_WAIT_L(n) asm volatile("s_waitcnt lgkmcnt(" #n ")" ::: "memory")
; #define G8_BAR __builtin_amdgcn_s_barrier()
; #define G8_SCHED __builtin_amdgcn_sched_barrier(0)
; template <class P>
; __device__ __forceinline__ void gemm_phase(LAS unsigned char* lds, const P& p, const int G, const int c) {
;     ...
;             G8_LDB(B0, 0, 0); G8_LDB(B1, 0, 1); G8_SCHED; G8_LDA(At, 0, 0); G8_STA(G8_SA(1, 1), a1, sg1, 1);
;             G8_WAIT_V(8); G8_WAIT_L(0); G8_BAR; G8_MMA(0, 0, At, B0); G8_MMA(0, 1, At, B1); G8_BAR; G8_SCHED;
;             G8_LDA(At, 0, 1); G8_STB(G8_SB(0, 0), b2, sg2, 0); G8_STB(G8_SB(0, 1), b2, sg2, 1); G8_STA(G8_SA(0, 0), a2, sg2, 0);
;             G8_WAIT_V(8); G8_WAIT_L(0); G8_BAR; G8_MMA(1, 0, At, B0); G8_MMA(1, 1, At, B1); G8_BAR; G8_SCHED;
.LBB0_707:
	ds_read_b128 v[68:71], v230
	ds_read_b128 v[72:75], v230 offset:1024
	ds_read_b128 v[76:79], v230 offset:2048
	ds_read_b128 v[138:141], v230 offset:3072
	ds_read_b128 v[142:145], v231
	ds_read_b128 v[154:157], v231 offset:1024
	ds_read_b128 v[158:161], v231 offset:2048
	ds_read_b128 v[162:165], v231 offset:3072
	s_add_u32 s65, s74, s76
	s_addc_u32 s66, s75, s77
	s_add_u32 s65, s65, 0x800000
	s_addc_u32 s66, s66, 0
	s_cmp_eq_u32 s76, 0x7800000
	s_cselect_b32 s67, s18, s66
	s_cselect_b32 s66, s19, s65
	s_cselect_b32 s79, s61, s29
	s_cselect_b32 s78, s63, s28
	v_lshl_add_u64 v[80:81], v[66:67], 0, s[76:77]
	s_mov_b64 s[80:81], 0x401000
	v_lshl_add_u64 v[198:199], v[80:81], 0, s[80:81]
	s_add_i32 m0, s25, 0xc000
	ds_read_b128 v[166:169], v232
	ds_read_b128 v[170:173], v232 offset:1024
	ds_read_b128 v[174:177], v232 offset:2048
	ds_read_b128 v[178:181], v232 offset:3072
	ds_read_b128 v[182:185], v232 offset:4096
	ds_read_b128 v[186:189], v232 offset:5120
	ds_read_b128 v[190:193], v232 offset:6144
	ds_read_b128 v[194:197], v232 offset:7168
	global_load_lds_dwordx4 v[198:199], off
	v_lshl_add_u64 v[80:81], v[80:81], 0, s[54:55]
	s_add_i32 m0, s25, 0xe000
	s_nop 0
	global_load_lds_dwordx4 v[80:81], off
	s_waitcnt vmcnt(8)
	s_waitcnt lgkmcnt(0)
	s_barrier
	s_waitcnt lgkmcnt(0)
	v_mfma_f32_16x16x32_bf16 v[150:153], v[68:71], v[166:169], v[150:153]
	v_mfma_f32_16x16x32_bf16 v[146:149], v[76:79], v[166:169], v[146:149]
	v_mfma_f32_16x16x32_bf16 v[126:129], v[68:71], v[174:177], v[126:129]
	v_mfma_f32_16x16x32_bf16 v[122:125], v[76:79], v[174:177], v[122:125]
	v_mfma_f32_16x16x32_bf16 v[110:113], v[68:71], v[182:185], v[110:113]
	v_mfma_f32_16x16x32_bf16 v[106:109], v[76:79], v[182:185], v[106:109]
	v_mfma_f32_16x16x32_bf16 v[94:97], v[68:71], v[190:193], v[94:97]
	v_mfma_f32_16x16x32_bf16 v[90:93], v[76:79], v[190:193], v[90:93]
	v_mfma_f32_16x16x32_bf16 v[150:153], v[72:75], v[170:173], v[150:153]
	v_mfma_f32_16x16x32_bf16 v[146:149], v[138:141], v[170:173], v[146:149]
	v_mfma_f32_16x16x32_bf16 v[126:129], v[72:75], v[178:181], v[126:129]
	v_mfma_f32_16x16x32_bf16 v[122:125], v[138:141], v[178:181], v[122:125]
	v_mfma_f32_16x16x32_bf16 v[110:113], v[72:75], v[186:189], v[110:113]
	v_mfma_f32_16x16x32_bf16 v[106:109], v[138:141], v[186:189], v[106:109]
	v_mfma_f32_16x16x32_bf16 v[94:97], v[72:75], v[194:197], v[94:97]
	v_mfma_f32_16x16x32_bf16 v[90:93], v[138:141], v[194:197], v[90:93]
	v_mfma_f32_16x16x32_bf16 v[134:137], v[142:145], v[166:169], v[134:137]
	v_mfma_f32_16x16x32_bf16 v[130:133], v[158:161], v[166:169], v[130:133]
	v_mfma_f32_16x16x32_bf16 v[118:121], v[142:145], v[174:177], v[118:121]
	v_mfma_f32_16x16x32_bf16 v[114:117], v[158:161], v[174:177], v[114:117]
	v_mfma_f32_16x16x32_bf16 v[102:105], v[142:145], v[182:185], v[102:105]
	v_mfma_f32_16x16x32_bf16 v[98:101], v[158:161], v[182:185], v[98:101]
	v_mfma_f32_16x16x32_bf16 v[86:89], v[142:145], v[190:193], v[86:89]
	v_mfma_f32_16x16x32_bf16 v[80:83], v[158:161], v[190:193], v[82:85]
	v_mfma_f32_16x16x32_bf16 v[134:137], v[154:157], v[170:173], v[134:137]
	v_mfma_f32_16x16x32_bf16 v[130:133], v[162:165], v[170:173], v[130:133]
	v_mfma_f32_16x16x32_bf16 v[118:121], v[154:157], v[178:181], v[118:121]
	v_mfma_f32_16x16x32_bf16 v[114:117], v[162:165], v[178:181], v[114:117]
	v_mfma_f32_16x16x32_bf16 v[102:105], v[154:157], v[186:189], v[102:105]
	v_mfma_f32_16x16x32_bf16 v[98:101], v[162:165], v[186:189], v[98:101]
	v_mfma_f32_16x16x32_bf16 v[86:89], v[154:157], v[194:197], v[86:89]
	v_mfma_f32_16x16x32_bf16 v[80:83], v[162:165], v[194:197], v[80:83]
	s_barrier
	s_add_i32 s65, s50, s24
	v_lshl_add_u64 v[198:199], s[78:79], 0, v[202:203]
	s_mov_b32 m0, s65
	ds_read_b128 v[166:169], v232 offset:16384
	ds_read_b128 v[170:173], v232 offset:17408
	ds_read_b128 v[174:177], v232 offset:18432
	ds_read_b128 v[178:181], v232 offset:19456
	ds_read_b128 v[182:185], v232 offset:20480
	ds_read_b128 v[186:189], v232 offset:21504
	ds_read_b128 v[190:193], v232 offset:22528
	ds_read_b128 v[194:197], v232 offset:23552
	global_load_lds_dwordx4 v[198:199], off
	v_lshl_add_u64 v[84:85], v[198:199], 0, s[6:7]
	s_add_i32 m0, s65, 0x2000
	s_add_i32 s65, s51, s24
	global_load_lds_dwordx4 v[84:85], off
	v_lshl_add_u64 v[84:85], v[198:199], 0, s[8:9]
	s_mov_b32 m0, s65
	v_lshl_add_u64 v[200:201], s[66:67], 0, v[204:205]
	global_load_lds_dwordx4 v[84:85], off
	v_lshl_add_u64 v[84:85], v[198:199], 0, s[10:11]
	s_add_i32 m0, s65, 0x2000
	s_nop 0
	global_load_lds_dwordx4 v[84:85], off
	s_mov_b32 m0, s25
	v_lshl_add_u64 v[84:85], v[200:201], 0, s[12:13]
	global_load_lds_dwordx4 v[200:201], off
	s_mov_b32 m0, s26
	s_nop 0
	global_load_lds_dwordx4 v[84:85], off
	s_waitcnt vmcnt(8)
	s_waitcnt lgkmcnt(0)
	s_barrier
; #define G8_STA(bufoff, ptr, sg, h) G8_STAGE1(bufoff, (ptr) + (h) * ((sg) ? hA1 : hA0), ((sg) ? voffA1 : voffA0), ((sg) ? r64A1 : r64A0))
; #define G8_LDA(dst, b, h) do { _Pragma("unroll") for (int m = 0; m < 4; ++m) _Pragma("unroll") for (int k = 0; k < 2; ++k) dst[m][k] = *(const LAS bf16x8*)(lds + G8_SA(b, h) + aoff + m * 2048 + k * 1024); } while (0)
; #define G8_LDB(dst, b, h) do { _Pragma("unroll") for (int n = 0; n < 2; ++n) _Pragma("unroll") for (int k = 0; k < 2; ++k) dst[n][k] = *(const LAS bf16x8*)(lds + G8_SB(b, h) + boff + n * 2048 + k * 1024); } while (0)
; #define G8_MMA(ai, bj, At, Bt) do { __builtin_amdgcn_s_setprio(1); _Pragma("unroll") for (int m = 0; m < 4; ++m) _Pragma("unroll") for (int n = 0; n < 2; ++n) _Pragma("unroll") for (int k = 0; k < 2; ++k) \
;         acc[ai][bj][m][n] = __builtin_amdgcn_mfma_f32_16x16x32_bf16(Bt[n][k], At[m][k], acc[ai][bj][m][n], 0, 0, 0); __builtin_amdgcn_s_setprio(0); } while (0)
; #define G8_WAIT_V(n) asm volatile("s_waitcnt vmcnt(" #n ")" ::: "memory")
; #define G8_WAIT_L(n) asm volatile("s_waitcnt lgkmcnt(" #n ")" ::: "memory")
; #define G8_BAR __builtin_amdgcn_s_barrier()
; #define G8_SCHED __builtin_amdgcn_sched_barrier(0)
; template <class P>
; __device__ __forceinline__ void gemm_phase(LAS unsigned char* lds, const P& p, const int G, const int c) {
;     ...
;             G8_WAIT_V(8); G8_WAIT_L(0); G8_BAR; G8_MMA(1, 0, At, B0); G8_MMA(1, 1, At, B1); G8_BAR; G8_SCHED;
;             G8_LDB(B0, 1, 0); G8_LDB(B1, 1, 1); G8_SCHED; G8_LDA(At, 1, 0); G8_STA(G8_SA(0, 1), a2, sg2, 1);
;             G8_WAIT_V(8); G8_WAIT_L(0); G8_BAR; G8_MMA(0, 0, At, B0); G8_MMA(0, 1, At, B1); G8_BAR; G8_SCHED;
	s_waitcnt lgkmcnt(0)
	v_mfma_f32_16x16x32_bf16 v[62:65], v[68:71], v[166:169], v[62:65]
	v_mfma_f32_16x16x32_bf16 v[58:61], v[76:79], v[166:169], v[58:61]
	v_mfma_f32_16x16x32_bf16 v[46:49], v[68:71], v[174:177], v[46:49]
	v_mfma_f32_16x16x32_bf16 v[42:45], v[76:79], v[174:177], v[42:45]
	v_mfma_f32_16x16x32_bf16 v[30:33], v[68:71], v[182:185], v[30:33]
	v_mfma_f32_16x16x32_bf16 v[26:29], v[76:79], v[182:185], v[26:29]
	v_mfma_f32_16x16x32_bf16 v[14:17], v[68:71], v[190:193], v[14:17]
	v_mfma_f32_16x16x32_bf16 v[10:13], v[76:79], v[190:193], v[10:13]
	v_mfma_f32_16x16x32_bf16 v[62:65], v[72:75], v[170:173], v[62:65]
	v_mfma_f32_16x16x32_bf16 v[58:61], v[138:141], v[170:173], v[58:61]
	v_mfma_f32_16x16x32_bf16 v[46:49], v[72:75], v[178:181], v[46:49]
	v_mfma_f32_16x16x32_bf16 v[42:45], v[138:141], v[178:181], v[42:45]
	v_mfma_f32_16x16x32_bf16 v[30:33], v[72:75], v[186:189], v[30:33]
	v_mfma_f32_16x16x32_bf16 v[26:29], v[138:141], v[186:189], v[26:29]
	v_mfma_f32_16x16x32_bf16 v[14:17], v[72:75], v[194:197], v[14:17]
	v_mfma_f32_16x16x32_bf16 v[10:13], v[138:141], v[194:197], v[10:13]
	v_mfma_f32_16x16x32_bf16 v[54:57], v[142:145], v[166:169], v[54:57]
	v_mfma_f32_16x16x32_bf16 v[50:53], v[158:161], v[166:169], v[50:53]
	v_mfma_f32_16x16x32_bf16 v[38:41], v[142:145], v[174:177], v[38:41]
	v_mfma_f32_16x16x32_bf16 v[34:37], v[158:161], v[174:177], v[34:37]
	v_mfma_f32_16x16x32_bf16 v[22:25], v[142:145], v[182:185], v[22:25]
	v_mfma_f32_16x16x32_bf16 v[18:21], v[158:161], v[182:185], v[18:21]
	v_mfma_f32_16x16x32_bf16 v[6:9], v[142:145], v[190:193], v[6:9]
	v_mfma_f32_16x16x32_bf16 v[2:5], v[158:161], v[190:193], v[2:5]
	v_mfma_f32_16x16x32_bf16 v[54:57], v[154:157], v[170:173], v[54:57]
	v_mfma_f32_16x16x32_bf16 v[50:53], v[162:165], v[170:173], v[50:53]
	v_mfma_f32_16x16x32_bf16 v[38:41], v[154:157], v[178:181], v[38:41]
	v_mfma_f32_16x16x32_bf16 v[34:37], v[162:165], v[178:181], v[34:37]
	v_mfma_f32_16x16x32_bf16 v[22:25], v[154:157], v[186:189], v[22:25]
	v_mfma_f32_16x16x32_bf16 v[18:21], v[162:165], v[186:189], v[18:21]
	v_mfma_f32_16x16x32_bf16 v[6:9], v[154:157], v[194:197], v[6:9]
	v_mfma_f32_16x16x32_bf16 v[2:5], v[162:165], v[194:197], v[2:5]
	s_barrier
	s_add_i32 s65, 0, 0x18000
	v_add_u32_e32 v84, s65, v229
	s_add_i32 s66, 0, 0x1c000
	ds_read_b128 v[68:71], v84
	ds_read_b128 v[72:75], v84 offset:1024
	ds_read_b128 v[76:79], v84 offset:2048
	ds_read_b128 v[138:141], v84 offset:3072
	v_add_u32_e32 v84, s66, v229
	ds_read_b128 v[142:145], v84
	ds_read_b128 v[154:157], v84 offset:1024
	ds_read_b128 v[158:161], v84 offset:2048
	ds_read_b128 v[162:165], v84 offset:3072
	s_mov_b32 m0, s27
	v_lshl_add_u64 v[84:85], v[200:201], 0, s[14:15]
	ds_read_b128 v[166:169], v232 offset:32768
	ds_read_b128 v[170:173], v232 offset:33792
	ds_read_b128 v[174:177], v232 offset:34816
	ds_read_b128 v[178:181], v232 offset:35840
	ds_read_b128 v[182:185], v232 offset:36864
	ds_read_b128 v[186:189], v232 offset:37888
	ds_read_b128 v[190:193], v232 offset:38912
	ds_read_b128 v[194:197], v232 offset:39936
	global_load_lds_dwordx4 v[84:85], off
	v_lshl_add_u64 v[84:85], v[200:201], 0, s[16:17]
	s_mov_b32 m0, s31
	s_nop 0
	global_load_lds_dwordx4 v[84:85], off
	s_waitcnt vmcnt(8)
	s_waitcnt lgkmcnt(0)
	s_barrier
	s_waitcnt lgkmcnt(0)
	v_mfma_f32_16x16x32_bf16 v[150:153], v[68:71], v[166:169], v[150:153]
	v_mfma_f32_16x16x32_bf16 v[146:149], v[76:79], v[166:169], v[146:149]
	v_mfma_f32_16x16x32_bf16 v[126:129], v[68:71], v[174:177], v[126:129]
	v_mfma_f32_16x16x32_bf16 v[122:125], v[76:79], v[174:177], v[122:125]
	v_mfma_f32_16x16x32_bf16 v[110:113], v[68:71], v[182:185], v[110:113]
	v_mfma_f32_16x16x32_bf16 v[106:109], v[76:79], v[182:185], v[106:109]
	v_mfma_f32_16x16x32_bf16 v[94:97], v[68:71], v[190:193], v[94:97]
	v_mfma_f32_16x16x32_bf16 v[90:93], v[76:79], v[190:193], v[90:93]
	v_mfma_f32_16x16x32_bf16 v[150:153], v[72:75], v[170:173], v[150:153]
	v_mfma_f32_16x16x32_bf16 v[146:149], v[138:141], v[170:173], v[146:149]
	v_mfma_f32_16x16x32_bf16 v[126:129], v[72:75], v[178:181], v[126:129]
	v_mfma_f32_16x16x32_bf16 v[122:125], v[138:141], v[178:181], v[122:125]
	v_mfma_f32_16x16x32_bf16 v[110:113], v[72:75], v[186:189], v[110:113]
	v_mfma_f32_16x16x32_bf16 v[106:109], v[138:141], v[186:189], v[106:109]
	v_mfma_f32_16x16x32_bf16 v[94:97], v[72:75], v[194:197], v[94:97]
	v_mfma_f32_16x16x32_bf16 v[90:93], v[138:141], v[194:197], v[90:93]
	v_mfma_f32_16x16x32_bf16 v[134:137], v[142:145], v[166:169], v[134:137]
	v_mfma_f32_16x16x32_bf16 v[130:133], v[158:161], v[166:169], v[130:133]
	v_mfma_f32_16x16x32_bf16 v[118:121], v[142:145], v[174:177], v[118:121]
	v_mfma_f32_16x16x32_bf16 v[114:117], v[158:161], v[174:177], v[114:117]
	v_mfma_f32_16x16x32_bf16 v[102:105], v[142:145], v[182:185], v[102:105]
	v_mfma_f32_16x16x32_bf16 v[98:101], v[158:161], v[182:185], v[98:101]
	v_mfma_f32_16x16x32_bf16 v[84:87], v[142:145], v[190:193], v[86:89]
	v_mfma_f32_16x16x32_bf16 v[80:83], v[158:161], v[190:193], v[80:83]
	v_mfma_f32_16x16x32_bf16 v[134:137], v[154:157], v[170:173], v[134:137]
	v_mfma_f32_16x16x32_bf16 v[130:133], v[162:165], v[170:173], v[130:133]
	v_mfma_f32_16x16x32_bf16 v[118:121], v[154:157], v[178:181], v[118:121]
	v_mfma_f32_16x16x32_bf16 v[114:117], v[162:165], v[178:181], v[114:117]
	v_mfma_f32_16x16x32_bf16 v[102:105], v[154:157], v[186:189], v[102:105]
	v_mfma_f32_16x16x32_bf16 v[98:101], v[162:165], v[186:189], v[98:101]
	v_mfma_f32_16x16x32_bf16 v[86:89], v[154:157], v[194:197], v[84:87]
	v_mfma_f32_16x16x32_bf16 v[82:85], v[162:165], v[194:197], v[80:83]
	s_barrier
; #define G8_STA(bufoff, ptr, sg, h) G8_STAGE1(bufoff, (ptr) + (h) * ((sg) ? hA1 : hA0), ((sg) ? voffA1 : voffA0), ((sg) ? r64A1 : r64A0))
; #define G8_STB(bufoff, ptr, sg, h) G8_STAGE1(bufoff, (ptr) + (h) * ((sg) ? hB1 : hB0), ((sg) ? voffB1 : voffB0), ((sg) ? r64B1 : r64B0))
; #define G8_LDA(dst, b, h) do { _Pragma("unroll") for (int m = 0; m < 4; ++m) _Pragma("unroll") for (int k = 0; k < 2; ++k) dst[m][k] = *(const LAS bf16x8*)(lds + G8_SA(b, h) + aoff + m * 2048 + k * 1024); } while (0)
; #define G8_MMA(ai, bj, At, Bt) do { __builtin_amdgcn_s_setprio(1); _Pragma("unroll") for (int m = 0; m < 4; ++m) _Pragma("unroll") for (int n = 0; n < 2; ++n) _Pragma("unroll") for (int k = 0; k < 2; ++k) \
;         acc[ai][bj][m][n] = __builtin_amdgcn_mfma_f32_16x16x32_bf16(Bt[n][k], At[m][k], acc[ai][bj][m][n], 0, 0, 0); __builtin_amdgcn_s_setprio(0); } while (0)
; #define G8_WAIT_V(n) asm volatile("s_waitcnt vmcnt(" #n ")" ::: "memory")
; #define G8_WAIT_L(n) asm volatile("s_waitcnt lgkmcnt(" #n ")" ::: "memory")
; #define G8_BAR __builtin_amdgcn_s_barrier()
; #define G8_SCHED __builtin_amdgcn_sched_barrier(0)
; template <class P>
; __device__ __forceinline__ void gemm_phase(LAS unsigned char* lds, const P& p, const int G, const int c) {
;     ...
;             G8_LDA(At, 1, 1); G8_STB(G8_SB(1, 0), b3, sg2, 0); G8_STB(G8_SB(1, 1), b3, sg2, 1); G8_STA(G8_SA(1, 0), a3, sg2, 0);
;             G8_WAIT_V(8); G8_WAIT_L(0); G8_BAR; G8_MMA(1, 0, At, B0); G8_MMA(1, 1, At, B1); G8_BAR; G8_SCHED;
;         }
;         if (wr == 0) G8_BAR;
	s_add_i32 s65, s65, s24
	v_lshl_add_u64 v[80:81], v[198:199], 0, s[36:37]
	s_mov_b32 m0, s65
	ds_read_b128 v[166:169], v232 offset:49152
	ds_read_b128 v[170:173], v232 offset:50176
	ds_read_b128 v[174:177], v232 offset:51200
	ds_read_b128 v[178:181], v232 offset:52224
	ds_read_b128 v[182:185], v232 offset:53248
	ds_read_b128 v[186:189], v232 offset:54272
	ds_read_b128 v[190:193], v232 offset:55296
	ds_read_b128 v[194:197], v232 offset:56320
	global_load_lds_dwordx4 v[80:81], off
	v_lshl_add_u64 v[80:81], v[198:199], 0, s[38:39]
	s_add_i32 m0, s65, 0x2000
	s_add_i32 s65, s66, s24
	global_load_lds_dwordx4 v[80:81], off
	v_lshl_add_u64 v[80:81], v[198:199], 0, s[44:45]
	s_mov_b32 m0, s65
	s_nop 0
	global_load_lds_dwordx4 v[80:81], off
	v_lshl_add_u64 v[80:81], v[198:199], 0, s[48:49]
	s_add_i32 m0, s65, 0x2000
	s_nop 0
	global_load_lds_dwordx4 v[80:81], off
	v_lshl_add_u64 v[80:81], v[200:201], 0, s[40:41]
	s_mov_b32 m0, s46
	s_nop 0
	global_load_lds_dwordx4 v[80:81], off
	v_lshl_add_u64 v[80:81], v[200:201], 0, s[42:43]
	s_mov_b32 m0, s47
	s_nop 0
	global_load_lds_dwordx4 v[80:81], off
	s_waitcnt vmcnt(8)
	s_waitcnt lgkmcnt(0)
	s_barrier
	s_waitcnt lgkmcnt(0)
	v_mfma_f32_16x16x32_bf16 v[62:65], v[68:71], v[166:169], v[62:65]
	v_mfma_f32_16x16x32_bf16 v[58:61], v[76:79], v[166:169], v[58:61]
	v_mfma_f32_16x16x32_bf16 v[46:49], v[68:71], v[174:177], v[46:49]
	v_mfma_f32_16x16x32_bf16 v[42:45], v[76:79], v[174:177], v[42:45]
	v_mfma_f32_16x16x32_bf16 v[30:33], v[68:71], v[182:185], v[30:33]
	v_mfma_f32_16x16x32_bf16 v[26:29], v[76:79], v[182:185], v[26:29]
	v_mfma_f32_16x16x32_bf16 v[14:17], v[68:71], v[190:193], v[14:17]
	v_mfma_f32_16x16x32_bf16 v[10:13], v[76:79], v[190:193], v[10:13]
	v_mfma_f32_16x16x32_bf16 v[62:65], v[72:75], v[170:173], v[62:65]
	v_mfma_f32_16x16x32_bf16 v[58:61], v[138:141], v[170:173], v[58:61]
	v_mfma_f32_16x16x32_bf16 v[46:49], v[72:75], v[178:181], v[46:49]
	v_mfma_f32_16x16x32_bf16 v[42:45], v[138:141], v[178:181], v[42:45]
	v_mfma_f32_16x16x32_bf16 v[30:33], v[72:75], v[186:189], v[30:33]
	v_mfma_f32_16x16x32_bf16 v[26:29], v[138:141], v[186:189], v[26:29]
	v_mfma_f32_16x16x32_bf16 v[14:17], v[72:75], v[194:197], v[14:17]
	v_mfma_f32_16x16x32_bf16 v[10:13], v[138:141], v[194:197], v[10:13]
	v_mfma_f32_16x16x32_bf16 v[54:57], v[142:145], v[166:169], v[54:57]
	v_mfma_f32_16x16x32_bf16 v[50:53], v[158:161], v[166:169], v[50:53]
	v_mfma_f32_16x16x32_bf16 v[38:41], v[142:145], v[174:177], v[38:41]
	v_mfma_f32_16x16x32_bf16 v[34:37], v[158:161], v[174:177], v[34:37]
	v_mfma_f32_16x16x32_bf16 v[22:25], v[142:145], v[182:185], v[22:25]
	v_mfma_f32_16x16x32_bf16 v[18:21], v[158:161], v[182:185], v[18:21]
	v_mfma_f32_16x16x32_bf16 v[6:9], v[142:145], v[190:193], v[6:9]
	v_mfma_f32_16x16x32_bf16 v[2:5], v[158:161], v[190:193], v[2:5]
	v_mfma_f32_16x16x32_bf16 v[54:57], v[154:157], v[170:173], v[54:57]
	v_mfma_f32_16x16x32_bf16 v[50:53], v[162:165], v[170:173], v[50:53]
	v_mfma_f32_16x16x32_bf16 v[38:41], v[154:157], v[178:181], v[38:41]
	v_mfma_f32_16x16x32_bf16 v[34:37], v[162:165], v[178:181], v[34:37]
	v_mfma_f32_16x16x32_bf16 v[22:25], v[154:157], v[186:189], v[22:25]
	v_mfma_f32_16x16x32_bf16 v[18:21], v[162:165], v[186:189], v[18:21]
	v_mfma_f32_16x16x32_bf16 v[6:9], v[154:157], v[194:197], v[6:9]
	v_mfma_f32_16x16x32_bf16 v[2:5], v[162:165], v[194:197], v[2:5]
	s_barrier
	s_add_i32 s64, s64, 2
	s_add_u32 s28, s28, 0x80000
	s_addc_u32 s29, s29, 0
	s_add_u32 s76, s76, 0x800000
	s_addc_u32 s77, s77, 0
	s_cmp_gt_u32 s64, 29
	s_cbranch_scc0 .LBB0_707
	s_and_b64 vcc, exec, s[52:53]
	s_cbranch_vccz .LBB0_710
	s_barrier

; #define G8_STA(bufoff, ptr, sg, h) G8_STAGE1(bufoff, (ptr) + (h) * ((sg) ? hA1 : hA0), ((sg) ? voffA1 : voffA0), ((sg) ? r64A1 : r64A0))
; #define G8_STB(bufoff, ptr, sg, h) G8_STAGE1(bufoff, (ptr) + (h) * ((sg) ? hB1 : hB0), ((sg) ? voffB1 : voffB0), ((sg) ? r64B1 : r64B0))
; #define G8_LDA(dst, b, h) do { _Pragma("unroll") for (int m = 0; m < 4; ++m) _Pragma("unroll") for (int k = 0; k < 2; ++k) dst[m][k] = *(const LAS bf16x8*)(lds + G8_SA(b, h) + aoff + m * 2048 + k * 1024); } while (0)
; #define G8_LDB(dst, b, h) do { _Pragma("unroll") for (int n = 0; n < 2; ++n) _Pragma("unroll") for (int k = 0; k < 2; ++k) dst[n][k] = *(const LAS bf16x8*)(lds + G8_SB(b, h) + boff + n * 2048 + k * 1024); } while (0)
; #define G8_MMA(ai, bj, At, Bt) do { __builtin_amdgcn_s_setprio(1); _Pragma("unroll") for (int m = 0; m < 4; ++m) _Pragma("unroll") for (int n = 0; n < 2; ++n) _Pragma("unroll") for (int k = 0; k < 2; ++k) \
;         acc[ai][bj][m][n] = __builtin_amdgcn_mfma_f32_16x16x32_bf16(Bt[n][k], At[m][k], acc[ai][bj][m][n], 0, 0, 0); __builtin_amdgcn_s_setprio(0); } while (0)
; #define G8_WAIT_V(n) asm volatile("s_waitcnt vmcnt(" #n ")" ::: "memory")
; #define G8_WAIT_L(n) asm volatile("s_waitcnt lgkmcnt(" #n ")" ::: "memory")
; #define G8_BAR __builtin_amdgcn_s_barrier()
; #define G8_SCHED __builtin_amdgcn_sched_barrier(0)
; template <class P>
; __device__ __forceinline__ void gemm_phase(LAS unsigned char* lds, const P& p, const int G, const int c) {
;     ...
;             G8_LDB(B0, 0, 0); G8_LDB(B1, 0, 1); G8_SCHED; G8_LDA(At, 0, 0); G8_STA(G8_SA(1, 1), a1, sg1, 1);
;             G8_WAIT_V(8); G8_WAIT_L(0); G8_BAR; G8_MMA(0, 0, At, B0); G8_MMA(0, 1, At, B1); G8_BAR; G8_SCHED;
;             G8_LDA(At, 0, 1); G8_STB(G8_SB(0, 0), b2, sg2, 0); G8_STB(G8_SB(0, 1), b2, sg2, 1); G8_STA(G8_SA(0, 0), a2, sg2, 0);
;             G8_WAIT_V(8); G8_WAIT_L(0); G8_BAR; G8_MMA(1, 0, At, B0); G8_MMA(1, 1, At, B1); G8_BAR; G8_SCHED;
.LBB0_770:
	ds_read_b128 v[130:133], v158
	ds_read_b128 v[134:137], v158 offset:1024
	ds_read_b128 v[138:141], v158 offset:2048
	ds_read_b128 v[162:165], v158 offset:3072
	ds_read_b128 v[166:169], v159
	ds_read_b128 v[170:173], v159 offset:1024
	ds_read_b128 v[174:177], v159 offset:2048
	ds_read_b128 v[178:181], v159 offset:3072
	s_add_u32 s77, s70, s72
	s_addc_u32 s78, s71, s73
	s_add_u32 s77, s77, 0x800000
	s_addc_u32 s78, s78, 0
	s_cmp_eq_u32 s72, 0x7800000
	s_cselect_b32 s79, s18, s78
	s_cselect_b32 s78, s19, s77
	s_cselect_b32 s81, s57, s29
	s_cselect_b32 s80, s59, s28
	v_lshl_add_u64 v[142:143], v[128:129], 0, s[72:73]
	v_lshl_add_u64 v[154:155], v[142:143], 0, s[40:41]
	s_add_i32 m0, s27, 0xc000
	ds_read_b128 v[182:185], v160
	ds_read_b128 v[186:189], v160 offset:1024
	ds_read_b128 v[190:193], v160 offset:2048
	ds_read_b128 v[194:197], v160 offset:3072
	ds_read_b128 v[198:201], v160 offset:4096
	ds_read_b128 v[202:205], v160 offset:5120
	ds_read_b128 v[210:213], v160 offset:6144
	ds_read_b128 v[214:217], v160 offset:7168
	global_load_lds_dwordx4 v[154:155], off
	v_lshl_add_u64 v[142:143], v[142:143], 0, s[42:43]
	s_add_i32 m0, s27, 0xe000
	s_nop 0
	global_load_lds_dwordx4 v[142:143], off
	s_waitcnt vmcnt(8)
	s_waitcnt lgkmcnt(0)
	s_barrier
	s_waitcnt lgkmcnt(0)
	v_mfma_f32_16x16x32_bf16 v[120:123], v[130:133], v[182:185], v[120:123]
	v_mfma_f32_16x16x32_bf16 v[124:127], v[138:141], v[182:185], v[124:127]
	v_mfma_f32_16x16x32_bf16 v[112:115], v[130:133], v[190:193], v[112:115]
	v_mfma_f32_16x16x32_bf16 v[116:119], v[138:141], v[190:193], v[116:119]
	v_mfma_f32_16x16x32_bf16 v[100:103], v[130:133], v[198:201], v[100:103]
	v_mfma_f32_16x16x32_bf16 v[108:111], v[138:141], v[198:201], v[108:111]
	v_mfma_f32_16x16x32_bf16 v[84:87], v[130:133], v[210:213], v[84:87]
	v_mfma_f32_16x16x32_bf16 v[72:75], v[138:141], v[210:213], v[72:75]
	v_mfma_f32_16x16x32_bf16 v[120:123], v[134:137], v[186:189], v[120:123]
	v_mfma_f32_16x16x32_bf16 v[124:127], v[162:165], v[186:189], v[124:127]
	v_mfma_f32_16x16x32_bf16 v[112:115], v[134:137], v[194:197], v[112:115]
	v_mfma_f32_16x16x32_bf16 v[116:119], v[162:165], v[194:197], v[116:119]
	v_mfma_f32_16x16x32_bf16 v[100:103], v[134:137], v[202:205], v[100:103]
	v_mfma_f32_16x16x32_bf16 v[108:111], v[162:165], v[202:205], v[108:111]
	v_mfma_f32_16x16x32_bf16 v[84:87], v[134:137], v[214:217], v[84:87]
	v_mfma_f32_16x16x32_bf16 v[72:75], v[162:165], v[214:217], v[72:75]
	v_mfma_f32_16x16x32_bf16 v[104:107], v[166:169], v[182:185], v[104:107]
	v_mfma_f32_16x16x32_bf16 v[92:95], v[174:177], v[182:185], v[92:95]
	v_mfma_f32_16x16x32_bf16 v[96:99], v[166:169], v[190:193], v[96:99]
	v_mfma_f32_16x16x32_bf16 v[80:83], v[174:177], v[190:193], v[80:83]
	v_mfma_f32_16x16x32_bf16 v[88:91], v[166:169], v[198:201], v[88:91]
	v_mfma_f32_16x16x32_bf16 v[76:79], v[174:177], v[198:201], v[76:79]
	v_mfma_f32_16x16x32_bf16 v[68:71], v[166:169], v[210:213], v[68:71]
	v_mfma_f32_16x16x32_bf16 v[64:67], v[174:177], v[210:213], v[64:67]
	v_mfma_f32_16x16x32_bf16 v[104:107], v[170:173], v[186:189], v[104:107]
	v_mfma_f32_16x16x32_bf16 v[92:95], v[178:181], v[186:189], v[92:95]
	v_mfma_f32_16x16x32_bf16 v[96:99], v[170:173], v[194:197], v[96:99]
	v_mfma_f32_16x16x32_bf16 v[80:83], v[178:181], v[194:197], v[80:83]
	v_mfma_f32_16x16x32_bf16 v[88:91], v[170:173], v[202:205], v[88:91]
	v_mfma_f32_16x16x32_bf16 v[76:79], v[178:181], v[202:205], v[76:79]
	v_mfma_f32_16x16x32_bf16 v[68:71], v[170:173], v[214:217], v[68:71]
	v_mfma_f32_16x16x32_bf16 v[64:67], v[178:181], v[214:217], v[64:67]
	s_barrier
	s_add_i32 s77, s30, s26
	v_lshl_add_u64 v[142:143], s[80:81], 0, v[144:145]
	s_mov_b32 m0, s77
	ds_read_b128 v[182:185], v160 offset:16384
	ds_read_b128 v[186:189], v160 offset:17408
	ds_read_b128 v[190:193], v160 offset:18432
	ds_read_b128 v[194:197], v160 offset:19456
	ds_read_b128 v[198:201], v160 offset:20480
	ds_read_b128 v[202:205], v160 offset:21504
	ds_read_b128 v[210:213], v160 offset:22528
	ds_read_b128 v[214:217], v160 offset:23552
	global_load_lds_dwordx4 v[142:143], off
	v_lshl_add_u64 v[154:155], v[142:143], 0, s[4:5]
	s_add_i32 m0, s77, 0x2000
	s_add_i32 s77, s74, s26
	global_load_lds_dwordx4 v[154:155], off
	v_lshl_add_u64 v[154:155], v[142:143], 0, s[6:7]
	s_mov_b32 m0, s77
	s_nop 0
	global_load_lds_dwordx4 v[154:155], off
	v_lshl_add_u64 v[154:155], v[142:143], 0, s[8:9]
	s_add_i32 m0, s77, 0x2000
	s_nop 0
	global_load_lds_dwordx4 v[154:155], off
	v_lshl_add_u64 v[154:155], s[78:79], 0, v[146:147]
	s_mov_b32 m0, s27
	v_lshl_add_u64 v[206:207], v[154:155], 0, s[4:5]
	global_load_lds_dwordx4 v[154:155], off
	s_mov_b32 m0, s31
	s_nop 0
	global_load_lds_dwordx4 v[206:207], off
	s_waitcnt vmcnt(8)
	s_waitcnt lgkmcnt(0)
	s_barrier
; #define G8_STA(bufoff, ptr, sg, h) G8_STAGE1(bufoff, (ptr) + (h) * ((sg) ? hA1 : hA0), ((sg) ? voffA1 : voffA0), ((sg) ? r64A1 : r64A0))
; #define G8_LDA(dst, b, h) do { _Pragma("unroll") for (int m = 0; m < 4; ++m) _Pragma("unroll") for (int k = 0; k < 2; ++k) dst[m][k] = *(const LAS bf16x8*)(lds + G8_SA(b, h) + aoff + m * 2048 + k * 1024); } while (0)
; #define G8_LDB(dst, b, h) do { _Pragma("unroll") for (int n = 0; n < 2; ++n) _Pragma("unroll") for (int k = 0; k < 2; ++k) dst[n][k] = *(const LAS bf16x8*)(lds + G8_SB(b, h) + boff + n * 2048 + k * 1024); } while (0)
; #define G8_MMA(ai, bj, At, Bt) do { __builtin_amdgcn_s_setprio(1); _Pragma("unroll") for (int m = 0; m < 4; ++m) _Pragma("unroll") for (int n = 0; n < 2; ++n) _Pragma("unroll") for (int k = 0; k < 2; ++k) \
;         acc[ai][bj][m][n] = __builtin_amdgcn_mfma_f32_16x16x32_bf16(Bt[n][k], At[m][k], acc[ai][bj][m][n], 0, 0, 0); __builtin_amdgcn_s_setprio(0); } while (0)
; #define G8_WAIT_V(n) asm volatile("s_waitcnt vmcnt(" #n ")" ::: "memory")
; #define G8_WAIT_L(n) asm volatile("s_waitcnt lgkmcnt(" #n ")" ::: "memory")
; #define G8_BAR __builtin_amdgcn_s_barrier()
; #define G8_SCHED __builtin_amdgcn_sched_barrier(0)
; template <class P>
; __device__ __forceinline__ void gemm_phase(LAS unsigned char* lds, const P& p, const int G, const int c) {
;     ...
;             G8_WAIT_V(8); G8_WAIT_L(0); G8_BAR; G8_MMA(1, 0, At, B0); G8_MMA(1, 1, At, B1); G8_BAR; G8_SCHED;
;             G8_LDB(B0, 1, 0); G8_LDB(B1, 1, 1); G8_SCHED; G8_LDA(At, 1, 0); G8_STA(G8_SA(0, 1), a2, sg2, 1);
;             G8_WAIT_V(8); G8_WAIT_L(0); G8_BAR; G8_MMA(0, 0, At, B0); G8_MMA(0, 1, At, B1); G8_BAR; G8_SCHED;
	s_waitcnt lgkmcnt(0)
	v_mfma_f32_16x16x32_bf16 v[60:63], v[130:133], v[182:185], v[60:63]
	v_mfma_f32_16x16x32_bf16 v[56:59], v[138:141], v[182:185], v[56:59]
	v_mfma_f32_16x16x32_bf16 v[52:55], v[130:133], v[190:193], v[52:55]
	v_mfma_f32_16x16x32_bf16 v[44:47], v[138:141], v[190:193], v[44:47]
	v_mfma_f32_16x16x32_bf16 v[36:39], v[130:133], v[198:201], v[36:39]
	v_mfma_f32_16x16x32_bf16 v[28:31], v[138:141], v[198:201], v[28:31]
	v_mfma_f32_16x16x32_bf16 v[20:23], v[130:133], v[210:213], v[20:23]
	v_mfma_f32_16x16x32_bf16 v[12:15], v[138:141], v[210:213], v[12:15]
	v_mfma_f32_16x16x32_bf16 v[60:63], v[134:137], v[186:189], v[60:63]
	v_mfma_f32_16x16x32_bf16 v[56:59], v[162:165], v[186:189], v[56:59]
	v_mfma_f32_16x16x32_bf16 v[52:55], v[134:137], v[194:197], v[52:55]
	v_mfma_f32_16x16x32_bf16 v[44:47], v[162:165], v[194:197], v[44:47]
	v_mfma_f32_16x16x32_bf16 v[36:39], v[134:137], v[202:205], v[36:39]
	v_mfma_f32_16x16x32_bf16 v[28:31], v[162:165], v[202:205], v[28:31]
	v_mfma_f32_16x16x32_bf16 v[20:23], v[134:137], v[214:217], v[20:23]
	v_mfma_f32_16x16x32_bf16 v[12:15], v[162:165], v[214:217], v[12:15]
	v_mfma_f32_16x16x32_bf16 v[48:51], v[166:169], v[182:185], v[48:51]
	v_mfma_f32_16x16x32_bf16 v[40:43], v[174:177], v[182:185], v[40:43]
	v_mfma_f32_16x16x32_bf16 v[32:35], v[166:169], v[190:193], v[32:35]
	v_mfma_f32_16x16x32_bf16 v[24:27], v[174:177], v[190:193], v[24:27]
	v_mfma_f32_16x16x32_bf16 v[16:19], v[166:169], v[198:201], v[16:19]
	v_mfma_f32_16x16x32_bf16 v[8:11], v[174:177], v[198:201], v[8:11]
	v_mfma_f32_16x16x32_bf16 v[4:7], v[166:169], v[210:213], v[4:7]
	v_mfma_f32_16x16x32_bf16 v[0:3], v[174:177], v[210:213], v[0:3]
	v_mfma_f32_16x16x32_bf16 v[48:51], v[170:173], v[186:189], v[48:51]
	v_mfma_f32_16x16x32_bf16 v[40:43], v[178:181], v[186:189], v[40:43]
	v_mfma_f32_16x16x32_bf16 v[32:35], v[170:173], v[194:197], v[32:35]
	v_mfma_f32_16x16x32_bf16 v[24:27], v[178:181], v[194:197], v[24:27]
	v_mfma_f32_16x16x32_bf16 v[16:19], v[170:173], v[202:205], v[16:19]
	v_mfma_f32_16x16x32_bf16 v[8:11], v[178:181], v[202:205], v[8:11]
	v_mfma_f32_16x16x32_bf16 v[4:7], v[170:173], v[214:217], v[4:7]
	v_mfma_f32_16x16x32_bf16 v[0:3], v[178:181], v[214:217], v[0:3]
	s_barrier
	s_add_i32 s77, 0, 0x18000
	v_add_u32_e32 v161, s77, v156
	s_add_i32 s78, 0, 0x1c000
	ds_read_b128 v[130:133], v161
	ds_read_b128 v[134:137], v161 offset:1024
	ds_read_b128 v[138:141], v161 offset:2048
	ds_read_b128 v[162:165], v161 offset:3072
	v_add_u32_e32 v161, s78, v156
	ds_read_b128 v[166:169], v161
	ds_read_b128 v[170:173], v161 offset:1024
	ds_read_b128 v[174:177], v161 offset:2048
	ds_read_b128 v[178:181], v161 offset:3072
	s_mov_b32 m0, s33
	v_lshl_add_u64 v[206:207], v[154:155], 0, s[6:7]
	ds_read_b128 v[182:185], v160 offset:32768
	ds_read_b128 v[186:189], v160 offset:33792
	ds_read_b128 v[190:193], v160 offset:34816
	ds_read_b128 v[194:197], v160 offset:35840
	ds_read_b128 v[198:201], v160 offset:36864
	ds_read_b128 v[202:205], v160 offset:37888
	ds_read_b128 v[210:213], v160 offset:38912
	ds_read_b128 v[214:217], v160 offset:39936
	global_load_lds_dwordx4 v[206:207], off
	v_lshl_add_u64 v[206:207], v[154:155], 0, s[8:9]
	s_mov_b32 m0, s34
	s_nop 0
	global_load_lds_dwordx4 v[206:207], off
	s_waitcnt vmcnt(8)
	s_waitcnt lgkmcnt(0)
	s_barrier
	s_waitcnt lgkmcnt(0)
	v_mfma_f32_16x16x32_bf16 v[120:123], v[130:133], v[182:185], v[120:123]
	v_mfma_f32_16x16x32_bf16 v[124:127], v[138:141], v[182:185], v[124:127]
	v_mfma_f32_16x16x32_bf16 v[112:115], v[130:133], v[190:193], v[112:115]
	v_mfma_f32_16x16x32_bf16 v[116:119], v[138:141], v[190:193], v[116:119]
	v_mfma_f32_16x16x32_bf16 v[100:103], v[130:133], v[198:201], v[100:103]
	v_mfma_f32_16x16x32_bf16 v[108:111], v[138:141], v[198:201], v[108:111]
	v_mfma_f32_16x16x32_bf16 v[84:87], v[130:133], v[210:213], v[84:87]
	v_mfma_f32_16x16x32_bf16 v[72:75], v[138:141], v[210:213], v[72:75]
	v_mfma_f32_16x16x32_bf16 v[120:123], v[134:137], v[186:189], v[120:123]
	v_mfma_f32_16x16x32_bf16 v[124:127], v[162:165], v[186:189], v[124:127]
	v_mfma_f32_16x16x32_bf16 v[112:115], v[134:137], v[194:197], v[112:115]
	v_mfma_f32_16x16x32_bf16 v[116:119], v[162:165], v[194:197], v[116:119]
	v_mfma_f32_16x16x32_bf16 v[100:103], v[134:137], v[202:205], v[100:103]
	v_mfma_f32_16x16x32_bf16 v[108:111], v[162:165], v[202:205], v[108:111]
	v_mfma_f32_16x16x32_bf16 v[84:87], v[134:137], v[214:217], v[84:87]
	v_mfma_f32_16x16x32_bf16 v[72:75], v[162:165], v[214:217], v[72:75]
	v_mfma_f32_16x16x32_bf16 v[104:107], v[166:169], v[182:185], v[104:107]
	v_mfma_f32_16x16x32_bf16 v[92:95], v[174:177], v[182:185], v[92:95]
	v_mfma_f32_16x16x32_bf16 v[96:99], v[166:169], v[190:193], v[96:99]
	v_mfma_f32_16x16x32_bf16 v[80:83], v[174:177], v[190:193], v[80:83]
	v_mfma_f32_16x16x32_bf16 v[88:91], v[166:169], v[198:201], v[88:91]
	v_mfma_f32_16x16x32_bf16 v[76:79], v[174:177], v[198:201], v[76:79]
	v_mfma_f32_16x16x32_bf16 v[68:71], v[166:169], v[210:213], v[68:71]
	v_mfma_f32_16x16x32_bf16 v[64:67], v[174:177], v[210:213], v[64:67]
	v_mfma_f32_16x16x32_bf16 v[104:107], v[170:173], v[186:189], v[104:107]
	v_mfma_f32_16x16x32_bf16 v[92:95], v[178:181], v[186:189], v[92:95]
	v_mfma_f32_16x16x32_bf16 v[96:99], v[170:173], v[194:197], v[96:99]
	v_mfma_f32_16x16x32_bf16 v[80:83], v[178:181], v[194:197], v[80:83]
	v_mfma_f32_16x16x32_bf16 v[88:91], v[170:173], v[202:205], v[88:91]
	v_mfma_f32_16x16x32_bf16 v[76:79], v[178:181], v[202:205], v[76:79]
	v_mfma_f32_16x16x32_bf16 v[68:71], v[170:173], v[214:217], v[68:71]
	v_mfma_f32_16x16x32_bf16 v[64:67], v[178:181], v[214:217], v[64:67]
	s_barrier
; #define G8_STA(bufoff, ptr, sg, h) G8_STAGE1(bufoff, (ptr) + (h) * ((sg) ? hA1 : hA0), ((sg) ? voffA1 : voffA0), ((sg) ? r64A1 : r64A0))
; #define G8_STB(bufoff, ptr, sg, h) G8_STAGE1(bufoff, (ptr) + (h) * ((sg) ? hB1 : hB0), ((sg) ? voffB1 : voffB0), ((sg) ? r64B1 : r64B0))
; #define G8_LDA(dst, b, h) do { _Pragma("unroll") for (int m = 0; m < 4; ++m) _Pragma("unroll") for (int k = 0; k < 2; ++k) dst[m][k] = *(const LAS bf16x8*)(lds + G8_SA(b, h) + aoff + m * 2048 + k * 1024); } while (0)
; #define G8_MMA(ai, bj, At, Bt) do { __builtin_amdgcn_s_setprio(1); _Pragma("unroll") for (int m = 0; m < 4; ++m) _Pragma("unroll") for (int n = 0; n < 2; ++n) _Pragma("unroll") for (int k = 0; k < 2; ++k) \
;         acc[ai][bj][m][n] = __builtin_amdgcn_mfma_f32_16x16x32_bf16(Bt[n][k], At[m][k], acc[ai][bj][m][n], 0, 0, 0); __builtin_amdgcn_s_setprio(0); } while (0)
; #define G8_WAIT_V(n) asm volatile("s_waitcnt vmcnt(" #n ")" ::: "memory")
; #define G8_WAIT_L(n) asm volatile("s_waitcnt lgkmcnt(" #n ")" ::: "memory")
; #define G8_BAR __builtin_amdgcn_s_barrier()
; #define G8_SCHED __builtin_amdgcn_sched_barrier(0)
; template <class P>
; __device__ __forceinline__ void gemm_phase(LAS unsigned char* lds, const P& p, const int G, const int c) {
;     ...
;             G8_LDA(At, 1, 1); G8_STB(G8_SB(1, 0), b3, sg2, 0); G8_STB(G8_SB(1, 1), b3, sg2, 1); G8_STA(G8_SA(1, 0), a3, sg2, 0);
;             G8_WAIT_V(8); G8_WAIT_L(0); G8_BAR; G8_MMA(1, 0, At, B0); G8_MMA(1, 1, At, B1); G8_BAR; G8_SCHED;
;         }
;         if (wr == 0) G8_BAR;
	s_add_i32 s77, s77, s26
	v_lshl_add_u64 v[206:207], v[142:143], 0, s[12:13]
	s_mov_b32 m0, s77
	ds_read_b128 v[182:185], v160 offset:49152
	ds_read_b128 v[186:189], v160 offset:50176
	ds_read_b128 v[190:193], v160 offset:51200
	ds_read_b128 v[194:197], v160 offset:52224
	ds_read_b128 v[198:201], v160 offset:53248
	ds_read_b128 v[202:205], v160 offset:54272
	ds_read_b128 v[210:213], v160 offset:55296
	ds_read_b128 v[214:217], v160 offset:56320
	global_load_lds_dwordx4 v[206:207], off
	v_lshl_add_u64 v[206:207], v[142:143], 0, s[14:15]
	s_add_i32 m0, s77, 0x2000
	s_add_i32 s77, s78, s26
	global_load_lds_dwordx4 v[206:207], off
	v_lshl_add_u64 v[206:207], v[142:143], 0, s[22:23]
	s_mov_b32 m0, s77
	v_lshl_add_u64 v[142:143], v[142:143], 0, s[36:37]
	global_load_lds_dwordx4 v[206:207], off
	s_add_i32 m0, s77, 0x2000
	s_nop 0
	global_load_lds_dwordx4 v[142:143], off
	v_lshl_add_u64 v[142:143], v[154:155], 0, s[16:17]
	s_mov_b32 m0, s67
	s_nop 0
	global_load_lds_dwordx4 v[142:143], off
	v_lshl_add_u64 v[142:143], v[154:155], 0, s[20:21]
	s_mov_b32 m0, s69
	s_nop 0
	global_load_lds_dwordx4 v[142:143], off
	s_waitcnt vmcnt(8)
	s_waitcnt lgkmcnt(0)
	s_barrier
	s_waitcnt lgkmcnt(0)
	v_mfma_f32_16x16x32_bf16 v[60:63], v[130:133], v[182:185], v[60:63]
	v_mfma_f32_16x16x32_bf16 v[56:59], v[138:141], v[182:185], v[56:59]
	v_mfma_f32_16x16x32_bf16 v[52:55], v[130:133], v[190:193], v[52:55]
	v_mfma_f32_16x16x32_bf16 v[44:47], v[138:141], v[190:193], v[44:47]
	v_mfma_f32_16x16x32_bf16 v[36:39], v[130:133], v[198:201], v[36:39]
	v_mfma_f32_16x16x32_bf16 v[28:31], v[138:141], v[198:201], v[28:31]
	v_mfma_f32_16x16x32_bf16 v[20:23], v[130:133], v[210:213], v[20:23]
	v_mfma_f32_16x16x32_bf16 v[12:15], v[138:141], v[210:213], v[12:15]
	v_mfma_f32_16x16x32_bf16 v[60:63], v[134:137], v[186:189], v[60:63]
	v_mfma_f32_16x16x32_bf16 v[56:59], v[162:165], v[186:189], v[56:59]
	v_mfma_f32_16x16x32_bf16 v[52:55], v[134:137], v[194:197], v[52:55]
	v_mfma_f32_16x16x32_bf16 v[44:47], v[162:165], v[194:197], v[44:47]
	v_mfma_f32_16x16x32_bf16 v[36:39], v[134:137], v[202:205], v[36:39]
	v_mfma_f32_16x16x32_bf16 v[28:31], v[162:165], v[202:205], v[28:31]
	v_mfma_f32_16x16x32_bf16 v[20:23], v[134:137], v[214:217], v[20:23]
	v_mfma_f32_16x16x32_bf16 v[12:15], v[162:165], v[214:217], v[12:15]
	v_mfma_f32_16x16x32_bf16 v[48:51], v[166:169], v[182:185], v[48:51]
	v_mfma_f32_16x16x32_bf16 v[40:43], v[174:177], v[182:185], v[40:43]
	v_mfma_f32_16x16x32_bf16 v[32:35], v[166:169], v[190:193], v[32:35]
	v_mfma_f32_16x16x32_bf16 v[24:27], v[174:177], v[190:193], v[24:27]
	v_mfma_f32_16x16x32_bf16 v[16:19], v[166:169], v[198:201], v[16:19]
	v_mfma_f32_16x16x32_bf16 v[8:11], v[174:177], v[198:201], v[8:11]
	v_mfma_f32_16x16x32_bf16 v[4:7], v[166:169], v[210:213], v[4:7]
	v_mfma_f32_16x16x32_bf16 v[0:3], v[174:177], v[210:213], v[0:3]
	v_mfma_f32_16x16x32_bf16 v[48:51], v[170:173], v[186:189], v[48:51]
	v_mfma_f32_16x16x32_bf16 v[40:43], v[178:181], v[186:189], v[40:43]
	v_mfma_f32_16x16x32_bf16 v[32:35], v[170:173], v[194:197], v[32:35]
	v_mfma_f32_16x16x32_bf16 v[24:27], v[178:181], v[194:197], v[24:27]
	v_mfma_f32_16x16x32_bf16 v[16:19], v[170:173], v[202:205], v[16:19]
	v_mfma_f32_16x16x32_bf16 v[8:11], v[178:181], v[202:205], v[8:11]
	v_mfma_f32_16x16x32_bf16 v[4:7], v[170:173], v[214:217], v[4:7]
	v_mfma_f32_16x16x32_bf16 v[0:3], v[178:181], v[214:217], v[0:3]
	s_barrier
	s_add_i32 s76, s76, 2
	s_add_u32 s28, s28, 0x40000
	s_addc_u32 s29, s29, 0
	s_add_u32 s72, s72, 0x800000
	s_addc_u32 s73, s73, 0
	s_cmp_gt_u32 s76, 29
	s_cbranch_scc0 .LBB0_770
	s_and_b64 vcc, exec, s[38:39]
	s_cbranch_vccz .LBB0_773
	s_barrier
